# back-edge rotation (guide 7.11, minimal): loop-carried SALU of the 11 GEMM K-loops moved in front of the loop-back s_barrier
# baseline (speedup 1.0000x reference)
.LBB0_221:
	v_add_u32_e32 v132, 0x10000, v151
	ds_read_b128 v[136:139], v132
	ds_read_b128 v[154:157], v132 offset:1024
	ds_read_b128 v[160:163], v132 offset:2048
	ds_read_b128 v[164:167], v132 offset:3072
	v_add_u32_e32 v132, 0x14000, v151
	ds_read_b128 v[168:171], v132
	ds_read_b128 v[172:175], v132 offset:1024
	ds_read_b128 v[176:179], v132 offset:2048
	ds_read_b128 v[180:183], v132 offset:3072
	s_add_i32 s4, vcc_hi, 0xfff80080
	s_cmp_eq_u32 s75, s7
	s_cselect_b32 s36, s95, s4
	s_cselect_b32 s5, vcc_lo, s6
	s_or_b32 s4, s36, 0x80
	s_mov_b32 m0, s78
	ds_read_b128 v[184:187], v153
	ds_read_b128 v[188:191], v153 offset:1024
	ds_read_b128 v[192:195], v153 offset:2048
	ds_read_b128 v[196:199], v153 offset:3072
	ds_read_b128 v[200:203], v153 offset:4096
	ds_read_b128 v[204:207], v153 offset:5120
	ds_read_b128 v[208:211], v153 offset:6144
	ds_read_b128 v[212:215], v153 offset:7168
	buffer_load_dwordx4 v143, s[84:87], vcc_hi offen lds
	s_mov_b32 m0, s79
	s_nop 0
	buffer_load_dwordx4 v147, s[84:87], vcc_hi offen lds
	s_waitcnt vmcnt(8)
	s_waitcnt lgkmcnt(0)
	s_barrier
	s_setprio 1
	s_waitcnt lgkmcnt(7)
	v_mfma_i32_16x16x64_i8 v[120:123], v[136:139], v[184:187], v[120:123]
	v_mfma_i32_16x16x64_i8 v[112:115], v[160:163], v[184:187], v[112:115]
	s_waitcnt lgkmcnt(5)
	v_mfma_i32_16x16x64_i8 v[104:107], v[136:139], v[192:195], v[104:107]
	v_mfma_i32_16x16x64_i8 v[96:99], v[160:163], v[192:195], v[96:99]
	s_waitcnt lgkmcnt(3)
	v_mfma_i32_16x16x64_i8 v[88:91], v[136:139], v[200:203], v[88:91]
	v_mfma_i32_16x16x64_i8 v[80:83], v[160:163], v[200:203], v[80:83]
	s_waitcnt lgkmcnt(1)
	v_mfma_i32_16x16x64_i8 v[72:75], v[136:139], v[208:211], v[72:75]
	v_mfma_i32_16x16x64_i8 v[64:67], v[160:163], v[208:211], v[64:67]
	v_mfma_i32_16x16x64_i8 v[120:123], v[154:157], v[188:191], v[120:123]
	v_mfma_i32_16x16x64_i8 v[112:115], v[164:167], v[188:191], v[112:115]
	v_mfma_i32_16x16x64_i8 v[104:107], v[154:157], v[196:199], v[104:107]
	v_mfma_i32_16x16x64_i8 v[96:99], v[164:167], v[196:199], v[96:99]
	v_mfma_i32_16x16x64_i8 v[88:91], v[154:157], v[204:207], v[88:91]
	v_mfma_i32_16x16x64_i8 v[80:83], v[164:167], v[204:207], v[80:83]
	s_waitcnt lgkmcnt(0)
	v_mfma_i32_16x16x64_i8 v[72:75], v[154:157], v[212:215], v[72:75]
	v_mfma_i32_16x16x64_i8 v[64:67], v[164:167], v[212:215], v[64:67]
	s_setprio 0
	s_setprio 1
	v_mfma_i32_16x16x64_i8 v[124:127], v[168:171], v[184:187], v[124:127]
	v_mfma_i32_16x16x64_i8 v[116:119], v[176:179], v[184:187], v[116:119]
	v_mfma_i32_16x16x64_i8 v[108:111], v[168:171], v[192:195], v[108:111]
	v_mfma_i32_16x16x64_i8 v[100:103], v[176:179], v[192:195], v[100:103]
	v_mfma_i32_16x16x64_i8 v[92:95], v[168:171], v[200:203], v[92:95]
	v_mfma_i32_16x16x64_i8 v[84:87], v[176:179], v[200:203], v[84:87]
	v_mfma_i32_16x16x64_i8 v[76:79], v[168:171], v[208:211], v[76:79]
	v_mfma_i32_16x16x64_i8 v[68:71], v[176:179], v[208:211], v[68:71]
	v_mfma_i32_16x16x64_i8 v[124:127], v[172:175], v[188:191], v[124:127]
	v_mfma_i32_16x16x64_i8 v[116:119], v[180:183], v[188:191], v[116:119]
	v_mfma_i32_16x16x64_i8 v[108:111], v[172:175], v[196:199], v[108:111]
	v_mfma_i32_16x16x64_i8 v[100:103], v[180:183], v[196:199], v[100:103]
	v_mfma_i32_16x16x64_i8 v[92:95], v[172:175], v[204:207], v[92:95]
	v_mfma_i32_16x16x64_i8 v[84:87], v[180:183], v[204:207], v[84:87]
	v_mfma_i32_16x16x64_i8 v[76:79], v[172:175], v[212:215], v[76:79]
	v_mfma_i32_16x16x64_i8 v[68:71], v[180:183], v[212:215], v[68:71]
	s_setprio 0
	s_barrier
	s_mov_b32 m0, s14
	s_mov_b32 s30, s86
	s_mov_b32 s31, s87
	ds_read_b128 v[184:187], v153 offset:16384
	ds_read_b128 v[188:191], v153 offset:17408
	ds_read_b128 v[192:195], v153 offset:18432
	ds_read_b128 v[196:199], v153 offset:19456
	ds_read_b128 v[200:203], v153 offset:20480
	ds_read_b128 v[204:207], v153 offset:21504
	ds_read_b128 v[208:211], v153 offset:22528
	ds_read_b128 v[212:215], v153 offset:23552
	buffer_load_dwordx4 v145, s[28:31], s5 offen lds
	s_mov_b32 m0, s15
	s_add_i32 s37, s5, 0x80000
	buffer_load_dwordx4 v149, s[28:31], s5 offen lds
	s_mov_b32 m0, s18
	s_nop 0
	buffer_load_dwordx4 v145, s[28:31], s37 offen lds
	s_mov_b32 m0, s19
	s_nop 0
	buffer_load_dwordx4 v149, s[28:31], s37 offen lds
	s_mov_b32 m0, s2
	s_nop 0
	buffer_load_dwordx4 v143, s[84:87], s36 offen lds
	s_mov_b32 m0, s20
	s_nop 0
	buffer_load_dwordx4 v147, s[84:87], s36 offen lds
	s_waitcnt vmcnt(8)
	s_waitcnt lgkmcnt(0)
	s_barrier
	s_setprio 1
	s_waitcnt lgkmcnt(7)
	v_mfma_i32_16x16x64_i8 v[56:59], v[136:139], v[184:187], v[56:59]
	v_mfma_i32_16x16x64_i8 v[48:51], v[160:163], v[184:187], v[48:51]
	s_waitcnt lgkmcnt(5)
	v_mfma_i32_16x16x64_i8 v[40:43], v[136:139], v[192:195], v[40:43]
	v_mfma_i32_16x16x64_i8 v[32:35], v[160:163], v[192:195], v[32:35]
	s_waitcnt lgkmcnt(3)
	v_mfma_i32_16x16x64_i8 v[24:27], v[136:139], v[200:203], v[24:27]
	v_mfma_i32_16x16x64_i8 v[16:19], v[160:163], v[200:203], v[16:19]
	s_waitcnt lgkmcnt(1)
	v_mfma_i32_16x16x64_i8 v[8:11], v[136:139], v[208:211], v[8:11]
	v_mfma_i32_16x16x64_i8 v[0:3], v[160:163], v[208:211], v[0:3]
	v_mfma_i32_16x16x64_i8 v[56:59], v[154:157], v[188:191], v[56:59]
	v_mfma_i32_16x16x64_i8 v[48:51], v[164:167], v[188:191], v[48:51]
	v_mfma_i32_16x16x64_i8 v[40:43], v[154:157], v[196:199], v[40:43]
	v_mfma_i32_16x16x64_i8 v[32:35], v[164:167], v[196:199], v[32:35]
	v_mfma_i32_16x16x64_i8 v[24:27], v[154:157], v[204:207], v[24:27]
	v_mfma_i32_16x16x64_i8 v[16:19], v[164:167], v[204:207], v[16:19]
	s_waitcnt lgkmcnt(0)
	v_mfma_i32_16x16x64_i8 v[8:11], v[154:157], v[212:215], v[8:11]
	v_mfma_i32_16x16x64_i8 v[0:3], v[164:167], v[212:215], v[0:3]
	s_setprio 0
	s_setprio 1
	v_mfma_i32_16x16x64_i8 v[60:63], v[168:171], v[184:187], v[60:63]
	v_mfma_i32_16x16x64_i8 v[52:55], v[176:179], v[184:187], v[52:55]
	v_mfma_i32_16x16x64_i8 v[44:47], v[168:171], v[192:195], v[44:47]
	v_mfma_i32_16x16x64_i8 v[36:39], v[176:179], v[192:195], v[36:39]
	v_mfma_i32_16x16x64_i8 v[28:31], v[168:171], v[200:203], v[28:31]
	v_mfma_i32_16x16x64_i8 v[20:23], v[176:179], v[200:203], v[20:23]
	v_mfma_i32_16x16x64_i8 v[12:15], v[168:171], v[208:211], v[12:15]
	v_mfma_i32_16x16x64_i8 v[4:7], v[176:179], v[208:211], v[4:7]
	v_mfma_i32_16x16x64_i8 v[60:63], v[172:175], v[188:191], v[60:63]
	v_mfma_i32_16x16x64_i8 v[52:55], v[180:183], v[188:191], v[52:55]
	v_mfma_i32_16x16x64_i8 v[44:47], v[172:175], v[196:199], v[44:47]
	v_mfma_i32_16x16x64_i8 v[36:39], v[180:183], v[196:199], v[36:39]
	v_mfma_i32_16x16x64_i8 v[28:31], v[172:175], v[204:207], v[28:31]
	v_mfma_i32_16x16x64_i8 v[20:23], v[180:183], v[204:207], v[20:23]
	v_mfma_i32_16x16x64_i8 v[12:15], v[172:175], v[212:215], v[12:15]
	v_mfma_i32_16x16x64_i8 v[4:7], v[180:183], v[212:215], v[4:7]
	s_setprio 0
	s_barrier
	v_add_u32_e32 v132, 0x18000, v151
	ds_read_b128 v[136:139], v132
	ds_read_b128 v[154:157], v132 offset:1024
	ds_read_b128 v[160:163], v132 offset:2048
	ds_read_b128 v[164:167], v132 offset:3072
	v_add_u32_e32 v132, 0x1c000, v151
	ds_read_b128 v[168:171], v132
	ds_read_b128 v[172:175], v132 offset:1024
	ds_read_b128 v[176:179], v132 offset:2048
	ds_read_b128 v[180:183], v132 offset:3072
	s_add_i32 s36, s36, 0x80000
	s_mov_b32 m0, s21
	ds_read_b128 v[184:187], v153 offset:32768
	ds_read_b128 v[188:191], v153 offset:33792
	ds_read_b128 v[192:195], v153 offset:34816
	ds_read_b128 v[196:199], v153 offset:35840
	ds_read_b128 v[200:203], v153 offset:36864
	ds_read_b128 v[204:207], v153 offset:37888
	ds_read_b128 v[208:211], v153 offset:38912
	ds_read_b128 v[212:215], v153 offset:39936
	buffer_load_dwordx4 v143, s[84:87], s36 offen lds
	s_mov_b32 m0, s26
	s_nop 0
	buffer_load_dwordx4 v147, s[84:87], s36 offen lds
	s_waitcnt vmcnt(8)
	s_waitcnt lgkmcnt(0)
	s_barrier
	s_setprio 1
	s_waitcnt lgkmcnt(7)
	v_mfma_i32_16x16x64_i8 v[120:123], v[136:139], v[184:187], v[120:123]
	v_mfma_i32_16x16x64_i8 v[112:115], v[160:163], v[184:187], v[112:115]
	s_waitcnt lgkmcnt(5)
	v_mfma_i32_16x16x64_i8 v[104:107], v[136:139], v[192:195], v[104:107]
	v_mfma_i32_16x16x64_i8 v[96:99], v[160:163], v[192:195], v[96:99]
	s_waitcnt lgkmcnt(3)
	v_mfma_i32_16x16x64_i8 v[88:91], v[136:139], v[200:203], v[88:91]
	v_mfma_i32_16x16x64_i8 v[80:83], v[160:163], v[200:203], v[80:83]
	s_waitcnt lgkmcnt(1)
	v_mfma_i32_16x16x64_i8 v[72:75], v[136:139], v[208:211], v[72:75]
	v_mfma_i32_16x16x64_i8 v[64:67], v[160:163], v[208:211], v[64:67]
	v_mfma_i32_16x16x64_i8 v[120:123], v[154:157], v[188:191], v[120:123]
	v_mfma_i32_16x16x64_i8 v[112:115], v[164:167], v[188:191], v[112:115]
	v_mfma_i32_16x16x64_i8 v[104:107], v[154:157], v[196:199], v[104:107]
	v_mfma_i32_16x16x64_i8 v[96:99], v[164:167], v[196:199], v[96:99]
	v_mfma_i32_16x16x64_i8 v[88:91], v[154:157], v[204:207], v[88:91]
	v_mfma_i32_16x16x64_i8 v[80:83], v[164:167], v[204:207], v[80:83]
	s_waitcnt lgkmcnt(0)
	v_mfma_i32_16x16x64_i8 v[72:75], v[154:157], v[212:215], v[72:75]
	v_mfma_i32_16x16x64_i8 v[64:67], v[164:167], v[212:215], v[64:67]
	s_setprio 0
	s_setprio 1
	v_mfma_i32_16x16x64_i8 v[124:127], v[168:171], v[184:187], v[124:127]
	v_mfma_i32_16x16x64_i8 v[116:119], v[176:179], v[184:187], v[116:119]
	v_mfma_i32_16x16x64_i8 v[108:111], v[168:171], v[192:195], v[108:111]
	v_mfma_i32_16x16x64_i8 v[100:103], v[176:179], v[192:195], v[100:103]
	v_mfma_i32_16x16x64_i8 v[92:95], v[168:171], v[200:203], v[92:95]
	v_mfma_i32_16x16x64_i8 v[84:87], v[176:179], v[200:203], v[84:87]
	v_mfma_i32_16x16x64_i8 v[76:79], v[168:171], v[208:211], v[76:79]
	v_mfma_i32_16x16x64_i8 v[68:71], v[176:179], v[208:211], v[68:71]
	v_mfma_i32_16x16x64_i8 v[124:127], v[172:175], v[188:191], v[124:127]
	v_mfma_i32_16x16x64_i8 v[116:119], v[180:183], v[188:191], v[116:119]
	v_mfma_i32_16x16x64_i8 v[108:111], v[172:175], v[196:199], v[108:111]
	v_mfma_i32_16x16x64_i8 v[100:103], v[180:183], v[196:199], v[100:103]
	v_mfma_i32_16x16x64_i8 v[92:95], v[172:175], v[204:207], v[92:95]
	v_mfma_i32_16x16x64_i8 v[84:87], v[180:183], v[204:207], v[84:87]
	v_mfma_i32_16x16x64_i8 v[76:79], v[172:175], v[212:215], v[76:79]
	v_mfma_i32_16x16x64_i8 v[68:71], v[180:183], v[212:215], v[68:71]
	s_setprio 0
	s_barrier
	s_mov_b32 m0, s60
	s_or_b32 s36, s5, 0x80
	ds_read_b128 v[184:187], v153 offset:49152
	ds_read_b128 v[188:191], v153 offset:50176
	ds_read_b128 v[192:195], v153 offset:51200
	ds_read_b128 v[196:199], v153 offset:52224
	ds_read_b128 v[200:203], v153 offset:53248
	ds_read_b128 v[204:207], v153 offset:54272
	ds_read_b128 v[208:211], v153 offset:55296
	ds_read_b128 v[212:215], v153 offset:56320
	buffer_load_dwordx4 v145, s[28:31], s36 offen lds
	s_mov_b32 m0, s61
	s_add_i32 s5, s5, 0x80080
	buffer_load_dwordx4 v149, s[28:31], s36 offen lds
	s_mov_b32 m0, s73
	s_nop 0
	buffer_load_dwordx4 v145, s[28:31], s5 offen lds
	s_mov_b32 m0, s74
	s_nop 0
	buffer_load_dwordx4 v149, s[28:31], s5 offen lds
	s_mov_b32 m0, s70
	s_nop 0
	buffer_load_dwordx4 v143, s[84:87], s4 offen lds
	s_mov_b32 m0, s71
	s_nop 0
	buffer_load_dwordx4 v147, s[84:87], s4 offen lds
	s_waitcnt vmcnt(8)
	s_waitcnt lgkmcnt(0)
	s_barrier
	s_setprio 1
	s_waitcnt lgkmcnt(7)
	v_mfma_i32_16x16x64_i8 v[56:59], v[136:139], v[184:187], v[56:59]
	v_mfma_i32_16x16x64_i8 v[48:51], v[160:163], v[184:187], v[48:51]
	s_waitcnt lgkmcnt(5)
	v_mfma_i32_16x16x64_i8 v[40:43], v[136:139], v[192:195], v[40:43]
	v_mfma_i32_16x16x64_i8 v[32:35], v[160:163], v[192:195], v[32:35]
	s_waitcnt lgkmcnt(3)
	v_mfma_i32_16x16x64_i8 v[24:27], v[136:139], v[200:203], v[24:27]
	v_mfma_i32_16x16x64_i8 v[16:19], v[160:163], v[200:203], v[16:19]
	s_waitcnt lgkmcnt(1)
	v_mfma_i32_16x16x64_i8 v[8:11], v[136:139], v[208:211], v[8:11]
	v_mfma_i32_16x16x64_i8 v[0:3], v[160:163], v[208:211], v[0:3]
	v_mfma_i32_16x16x64_i8 v[56:59], v[154:157], v[188:191], v[56:59]
	v_mfma_i32_16x16x64_i8 v[48:51], v[164:167], v[188:191], v[48:51]
	v_mfma_i32_16x16x64_i8 v[40:43], v[154:157], v[196:199], v[40:43]
	v_mfma_i32_16x16x64_i8 v[32:35], v[164:167], v[196:199], v[32:35]
	v_mfma_i32_16x16x64_i8 v[24:27], v[154:157], v[204:207], v[24:27]
	v_mfma_i32_16x16x64_i8 v[16:19], v[164:167], v[204:207], v[16:19]
	s_waitcnt lgkmcnt(0)
	v_mfma_i32_16x16x64_i8 v[8:11], v[154:157], v[212:215], v[8:11]
	v_mfma_i32_16x16x64_i8 v[0:3], v[164:167], v[212:215], v[0:3]
	s_setprio 0
	s_setprio 1
	v_mfma_i32_16x16x64_i8 v[60:63], v[168:171], v[184:187], v[60:63]
	v_mfma_i32_16x16x64_i8 v[52:55], v[176:179], v[184:187], v[52:55]
	v_mfma_i32_16x16x64_i8 v[44:47], v[168:171], v[192:195], v[44:47]
	v_mfma_i32_16x16x64_i8 v[36:39], v[176:179], v[192:195], v[36:39]
	v_mfma_i32_16x16x64_i8 v[28:31], v[168:171], v[200:203], v[28:31]
	v_mfma_i32_16x16x64_i8 v[20:23], v[176:179], v[200:203], v[20:23]
	v_mfma_i32_16x16x64_i8 v[12:15], v[168:171], v[208:211], v[12:15]
	v_mfma_i32_16x16x64_i8 v[4:7], v[176:179], v[208:211], v[4:7]
	v_mfma_i32_16x16x64_i8 v[60:63], v[172:175], v[188:191], v[60:63]
	v_mfma_i32_16x16x64_i8 v[52:55], v[180:183], v[188:191], v[52:55]
	v_mfma_i32_16x16x64_i8 v[44:47], v[172:175], v[196:199], v[44:47]
	v_mfma_i32_16x16x64_i8 v[36:39], v[180:183], v[196:199], v[36:39]
	v_mfma_i32_16x16x64_i8 v[28:31], v[172:175], v[204:207], v[28:31]
	v_mfma_i32_16x16x64_i8 v[20:23], v[180:183], v[204:207], v[20:23]
	v_mfma_i32_16x16x64_i8 v[12:15], v[172:175], v[212:215], v[12:15]
	v_mfma_i32_16x16x64_i8 v[4:7], v[180:183], v[212:215], v[4:7]
	s_setprio 0
	s_add_i32 s7, s7, 2
	s_addk_i32 vcc_hi, 0x100
	s_addk_i32 s6, 0x100
	s_cmp_ge_i32 s7, s49
	s_barrier
	s_cbranch_scc0 .LBB0_221
	v_readlane_b32 s95, v254, 22

.LBB0_317:
	ds_read_b128 v[128:131], v202
	ds_read_b128 v[132:135], v202 offset:1024
	ds_read_b128 v[136:139], v202 offset:2048
	ds_read_b128 v[140:143], v202 offset:3072
	ds_read_b128 v[144:147], v203
	ds_read_b128 v[148:151], v203 offset:1024
	ds_read_b128 v[152:155], v203 offset:2048
	ds_read_b128 v[156:159], v203 offset:3072
	s_add_i32 s2, s5, 0xffea8080
	s_cmp_eq_u32 s4, vcc_hi
	s_cselect_b32 s29, s0, s2
	s_cselect_b32 s23, s1, vcc_lo
	s_add_i32 s2, s29, 0x80
	s_mov_b32 m0, s86
	ds_read_b128 v[160:163], v204
	ds_read_b128 v[164:167], v204 offset:1024
	ds_read_b128 v[168:171], v204 offset:2048
	ds_read_b128 v[172:175], v204 offset:3072
	ds_read_b128 v[180:183], v204 offset:4096
	ds_read_b128 v[184:187], v204 offset:5120
	ds_read_b128 v[188:191], v204 offset:6144
	ds_read_b128 v[192:195], v204 offset:7168
	buffer_load_dwordx4 v198, s[52:55], s5 offen lds
	s_mov_b32 m0, s87
	s_nop 0
	buffer_load_dwordx4 v200, s[52:55], s5 offen lds
	s_waitcnt vmcnt(8)
	s_waitcnt lgkmcnt(0)
	s_barrier
	s_setprio 1
	s_waitcnt lgkmcnt(6)
	v_mfma_scale_f32_16x16x128_f8f6f4 v[124:127], v[128:135], v[160:167], v[124:127], v205, v205 op_sel_hi:[0,0,0]
	v_mfma_scale_f32_16x16x128_f8f6f4 v[120:123], v[136:143], v[160:167], v[120:123], v205, v205 op_sel_hi:[0,0,0]
	s_waitcnt lgkmcnt(4)
	v_mfma_scale_f32_16x16x128_f8f6f4 v[108:111], v[128:135], v[168:175], v[108:111], v205, v205 op_sel_hi:[0,0,0]
	v_mfma_scale_f32_16x16x128_f8f6f4 v[104:107], v[136:143], v[168:175], v[104:107], v205, v205 op_sel_hi:[0,0,0]
	s_waitcnt lgkmcnt(2)
	v_mfma_scale_f32_16x16x128_f8f6f4 v[210:213], v[128:135], v[180:187], v[92:95], v205, v205 op_sel_hi:[0,0,0]
	v_mfma_scale_f32_16x16x128_f8f6f4 v[214:217], v[136:143], v[180:187], v[88:91], v205, v205 op_sel_hi:[0,0,0]
	s_waitcnt lgkmcnt(0)
	v_mfma_scale_f32_16x16x128_f8f6f4 v[218:221], v[128:135], v[188:195], v[76:79], v205, v205 op_sel_hi:[0,0,0]
	v_mfma_scale_f32_16x16x128_f8f6f4 v[222:225], v[136:143], v[188:195], v[72:75], v205, v205 op_sel_hi:[0,0,0]
	s_setprio 0
	s_setprio 1
	v_mfma_scale_f32_16x16x128_f8f6f4 v[116:119], v[144:151], v[160:167], v[116:119], v205, v205 op_sel_hi:[0,0,0]
	v_mfma_scale_f32_16x16x128_f8f6f4 v[112:115], v[152:159], v[160:167], v[112:115], v205, v205 op_sel_hi:[0,0,0]
	v_mfma_scale_f32_16x16x128_f8f6f4 v[100:103], v[144:151], v[168:175], v[100:103], v205, v205 op_sel_hi:[0,0,0]
	v_mfma_scale_f32_16x16x128_f8f6f4 v[96:99], v[152:159], v[168:175], v[96:99], v205, v205 op_sel_hi:[0,0,0]
	v_mfma_scale_f32_16x16x128_f8f6f4 v[160:163], v[144:151], v[180:187], v[84:87], v205, v205 op_sel_hi:[0,0,0]
	v_mfma_scale_f32_16x16x128_f8f6f4 v[164:167], v[152:159], v[180:187], v[80:83], v205, v205 op_sel_hi:[0,0,0]
	v_mfma_scale_f32_16x16x128_f8f6f4 v[168:171], v[144:151], v[188:195], v[68:71], v205, v205 op_sel_hi:[0,0,0]
	v_mfma_scale_f32_16x16x128_f8f6f4 v[172:175], v[152:159], v[188:195], v[64:67], v205, v205 op_sel_hi:[0,0,0]
	s_setprio 0
	s_barrier
	s_mov_b32 m0, s14
	s_mov_b32 s50, s54
	s_mov_b32 s51, s55
	s_nop 1
	ds_read_b128 v[64:67], v204 offset:16384
	ds_read_b128 v[68:71], v204 offset:17408
	ds_read_b128 v[72:75], v204 offset:18432
	ds_read_b128 v[76:79], v204 offset:19456
	ds_read_b128 v[80:83], v204 offset:20480
	ds_read_b128 v[84:87], v204 offset:21504
	ds_read_b128 v[88:91], v204 offset:22528
	ds_read_b128 v[92:95], v204 offset:23552
	buffer_load_dwordx4 v199, s[48:51], s23 offen lds
	s_mov_b32 m0, s15
	s_add_i32 s36, s23, 0x158000
	buffer_load_dwordx4 v201, s[48:51], s23 offen lds
	s_mov_b32 m0, s18
	s_nop 0
	buffer_load_dwordx4 v199, s[48:51], s36 offen lds
	s_mov_b32 m0, s19
	s_nop 0
	buffer_load_dwordx4 v201, s[48:51], s36 offen lds
	s_mov_b32 m0, s3
	s_nop 0
	buffer_load_dwordx4 v198, s[52:55], s29 offen lds
	s_mov_b32 m0, s21
	s_nop 0
	buffer_load_dwordx4 v200, s[52:55], s29 offen lds
	s_waitcnt vmcnt(8)
	s_waitcnt lgkmcnt(0)
	s_barrier
	s_setprio 1
	s_waitcnt lgkmcnt(6)
	v_mfma_scale_f32_16x16x128_f8f6f4 v[60:63], v[128:135], v[64:71], v[60:63], v205, v205 op_sel_hi:[0,0,0]
	v_mfma_scale_f32_16x16x128_f8f6f4 v[56:59], v[136:143], v[64:71], v[56:59], v205, v205 op_sel_hi:[0,0,0]
	s_waitcnt lgkmcnt(4)
	v_mfma_scale_f32_16x16x128_f8f6f4 v[180:183], v[128:135], v[72:79], v[44:47], v205, v205 op_sel_hi:[0,0,0]
	v_mfma_scale_f32_16x16x128_f8f6f4 v[184:187], v[136:143], v[72:79], v[40:43], v205, v205 op_sel_hi:[0,0,0]
	s_waitcnt lgkmcnt(2)
	v_mfma_scale_f32_16x16x128_f8f6f4 v[188:191], v[128:135], v[80:87], v[28:31], v205, v205 op_sel_hi:[0,0,0]
	v_mfma_scale_f32_16x16x128_f8f6f4 v[192:195], v[136:143], v[80:87], v[24:27], v205, v205 op_sel_hi:[0,0,0]
	s_waitcnt lgkmcnt(0)
	v_mfma_scale_f32_16x16x128_f8f6f4 v[226:229], v[128:135], v[88:95], v[12:15], v205, v205 op_sel_hi:[0,0,0]
	v_mfma_scale_f32_16x16x128_f8f6f4 v[230:233], v[136:143], v[88:95], v[8:11], v205, v205 op_sel_hi:[0,0,0]
	s_setprio 0
	s_setprio 1
	v_mfma_scale_f32_16x16x128_f8f6f4 v[52:55], v[144:151], v[64:71], v[52:55], v205, v205 op_sel_hi:[0,0,0]
	v_mfma_scale_f32_16x16x128_f8f6f4 v[48:51], v[152:159], v[64:71], v[48:51], v205, v205 op_sel_hi:[0,0,0]
	v_mfma_scale_f32_16x16x128_f8f6f4 v[234:237], v[144:151], v[72:79], v[36:39], v205, v205 op_sel_hi:[0,0,0]
	v_mfma_scale_f32_16x16x128_f8f6f4 v[238:241], v[152:159], v[72:79], v[32:35], v205, v205 op_sel_hi:[0,0,0]
	v_mfma_scale_f32_16x16x128_f8f6f4 v[242:245], v[144:151], v[80:87], v[20:23], v205, v205 op_sel_hi:[0,0,0]
	v_mfma_scale_f32_16x16x128_f8f6f4 v[246:249], v[152:159], v[80:87], v[16:19], v205, v205 op_sel_hi:[0,0,0]
	v_mfma_scale_f32_16x16x128_f8f6f4 v[250:253], v[144:151], v[88:95], v[4:7], v205, v205 op_sel_hi:[0,0,0]
	v_mfma_scale_f32_16x16x128_f8f6f4 v[176:179], v[152:159], v[88:95], v[0:3], v205, v205 op_sel_hi:[0,0,0]
	s_setprio 0
	s_barrier
	s_nop 4
	ds_read_b128 v[0:3], v206
	ds_read_b128 v[4:7], v206 offset:1024
	ds_read_b128 v[16:19], v206 offset:2048
	ds_read_b128 v[20:23], v206 offset:3072
	ds_read_b128 v[128:131], v207
	ds_read_b128 v[132:135], v207 offset:1024
	ds_read_b128 v[136:139], v207 offset:2048
	ds_read_b128 v[140:143], v207 offset:3072
	s_add_i32 s29, s29, 0x158000
	s_mov_b32 m0, s26
	ds_read_b128 v[8:11], v204 offset:32768
	ds_read_b128 v[12:15], v204 offset:33792
	ds_read_b128 v[24:27], v204 offset:34816
	ds_read_b128 v[28:31], v204 offset:35840
	ds_read_b128 v[32:35], v204 offset:36864
	ds_read_b128 v[36:39], v204 offset:37888
	ds_read_b128 v[40:43], v204 offset:38912
	ds_read_b128 v[44:47], v204 offset:39936
	buffer_load_dwordx4 v198, s[52:55], s29 offen lds
	s_mov_b32 m0, s27
	s_nop 0
	buffer_load_dwordx4 v200, s[52:55], s29 offen lds
	s_waitcnt vmcnt(8)
	s_waitcnt lgkmcnt(0)
	s_barrier
	s_setprio 1
	s_waitcnt lgkmcnt(6)
	v_mfma_scale_f32_16x16x128_f8f6f4 v[124:127], v[0:7], v[8:15], v[124:127], v205, v205 op_sel_hi:[0,0,0]
	v_mfma_scale_f32_16x16x128_f8f6f4 v[120:123], v[16:23], v[8:15], v[120:123], v205, v205 op_sel_hi:[0,0,0]
	s_waitcnt lgkmcnt(4)
	v_mfma_scale_f32_16x16x128_f8f6f4 v[108:111], v[0:7], v[24:31], v[108:111], v205, v205 op_sel_hi:[0,0,0]
	v_mfma_scale_f32_16x16x128_f8f6f4 v[104:107], v[16:23], v[24:31], v[104:107], v205, v205 op_sel_hi:[0,0,0]
	s_waitcnt lgkmcnt(2)
	v_mfma_scale_f32_16x16x128_f8f6f4 v[92:95], v[0:7], v[32:39], v[210:213], v205, v205 op_sel_hi:[0,0,0]
	v_mfma_scale_f32_16x16x128_f8f6f4 v[88:91], v[16:23], v[32:39], v[214:217], v205, v205 op_sel_hi:[0,0,0]
	s_waitcnt lgkmcnt(0)
	v_mfma_scale_f32_16x16x128_f8f6f4 v[76:79], v[0:7], v[40:47], v[218:221], v205, v205 op_sel_hi:[0,0,0]
	v_mfma_scale_f32_16x16x128_f8f6f4 v[72:75], v[16:23], v[40:47], v[222:225], v205, v205 op_sel_hi:[0,0,0]
	s_setprio 0
	s_setprio 1
	v_mfma_scale_f32_16x16x128_f8f6f4 v[116:119], v[128:135], v[8:15], v[116:119], v205, v205 op_sel_hi:[0,0,0]
	v_mfma_scale_f32_16x16x128_f8f6f4 v[112:115], v[136:143], v[8:15], v[112:115], v205, v205 op_sel_hi:[0,0,0]
	v_mfma_scale_f32_16x16x128_f8f6f4 v[100:103], v[128:135], v[24:31], v[100:103], v205, v205 op_sel_hi:[0,0,0]
	v_mfma_scale_f32_16x16x128_f8f6f4 v[96:99], v[136:143], v[24:31], v[96:99], v205, v205 op_sel_hi:[0,0,0]
	v_mfma_scale_f32_16x16x128_f8f6f4 v[84:87], v[128:135], v[32:39], v[160:163], v205, v205 op_sel_hi:[0,0,0]
	v_mfma_scale_f32_16x16x128_f8f6f4 v[80:83], v[136:143], v[32:39], v[164:167], v205, v205 op_sel_hi:[0,0,0]
	v_mfma_scale_f32_16x16x128_f8f6f4 v[68:71], v[128:135], v[40:47], v[168:171], v205, v205 op_sel_hi:[0,0,0]
	v_mfma_scale_f32_16x16x128_f8f6f4 v[64:67], v[136:143], v[40:47], v[172:175], v205, v205 op_sel_hi:[0,0,0]
	s_setprio 0
	s_barrier
	s_mov_b32 m0, s31
	s_add_i32 s29, s23, 0x80
	ds_read_b128 v[32:35], v204 offset:49152
	ds_read_b128 v[36:39], v204 offset:50176
	ds_read_b128 v[144:147], v204 offset:51200
	ds_read_b128 v[148:151], v204 offset:52224
	ds_read_b128 v[152:155], v204 offset:53248
	ds_read_b128 v[156:159], v204 offset:54272
	ds_read_b128 v[160:163], v204 offset:55296
	ds_read_b128 v[164:167], v204 offset:56320
	buffer_load_dwordx4 v199, s[48:51], s29 offen lds
	s_mov_b32 m0, s78
	s_add_i32 s23, s23, 0x158080
	buffer_load_dwordx4 v201, s[48:51], s29 offen lds
	s_mov_b32 m0, s81
	s_nop 0
	buffer_load_dwordx4 v199, s[48:51], s23 offen lds
	s_mov_b32 m0, s82
	s_nop 0
	buffer_load_dwordx4 v201, s[48:51], s23 offen lds
	s_mov_b32 m0, s79
	s_nop 0
	buffer_load_dwordx4 v198, s[52:55], s2 offen lds
	s_mov_b32 m0, s80
	s_nop 0
	buffer_load_dwordx4 v200, s[52:55], s2 offen lds
	s_waitcnt vmcnt(8)
	s_waitcnt lgkmcnt(0)
	s_barrier
	s_setprio 1
	s_waitcnt lgkmcnt(6)
	v_mfma_scale_f32_16x16x128_f8f6f4 v[60:63], v[0:7], v[32:39], v[60:63], v205, v205 op_sel_hi:[0,0,0]
	v_mfma_scale_f32_16x16x128_f8f6f4 v[56:59], v[16:23], v[32:39], v[56:59], v205, v205 op_sel_hi:[0,0,0]
	s_waitcnt lgkmcnt(4)
	v_mfma_scale_f32_16x16x128_f8f6f4 v[44:47], v[0:7], v[144:151], v[180:183], v205, v205 op_sel_hi:[0,0,0]
	v_mfma_scale_f32_16x16x128_f8f6f4 v[40:43], v[16:23], v[144:151], v[184:187], v205, v205 op_sel_hi:[0,0,0]
	s_waitcnt lgkmcnt(2)
	v_mfma_scale_f32_16x16x128_f8f6f4 v[28:31], v[0:7], v[152:159], v[188:191], v205, v205 op_sel_hi:[0,0,0]
	v_mfma_scale_f32_16x16x128_f8f6f4 v[24:27], v[16:23], v[152:159], v[192:195], v205, v205 op_sel_hi:[0,0,0]
	s_waitcnt lgkmcnt(0)
	v_mfma_scale_f32_16x16x128_f8f6f4 v[12:15], v[0:7], v[160:167], v[226:229], v205, v205 op_sel_hi:[0,0,0]
	v_mfma_scale_f32_16x16x128_f8f6f4 v[8:11], v[16:23], v[160:167], v[230:233], v205, v205 op_sel_hi:[0,0,0]
	s_setprio 0
	s_setprio 1
	v_mfma_scale_f32_16x16x128_f8f6f4 v[52:55], v[128:135], v[32:39], v[52:55], v205, v205 op_sel_hi:[0,0,0]
	v_mfma_scale_f32_16x16x128_f8f6f4 v[48:51], v[136:143], v[32:39], v[48:51], v205, v205 op_sel_hi:[0,0,0]
	v_mfma_scale_f32_16x16x128_f8f6f4 v[36:39], v[128:135], v[144:151], v[234:237], v205, v205 op_sel_hi:[0,0,0]
	v_mfma_scale_f32_16x16x128_f8f6f4 v[32:35], v[136:143], v[144:151], v[238:241], v205, v205 op_sel_hi:[0,0,0]
	v_mfma_scale_f32_16x16x128_f8f6f4 v[20:23], v[128:135], v[152:159], v[242:245], v205, v205 op_sel_hi:[0,0,0]
	v_mfma_scale_f32_16x16x128_f8f6f4 v[16:19], v[136:143], v[152:159], v[246:249], v205, v205 op_sel_hi:[0,0,0]
	v_mfma_scale_f32_16x16x128_f8f6f4 v[4:7], v[128:135], v[160:167], v[250:253], v205, v205 op_sel_hi:[0,0,0]
	v_mfma_scale_f32_16x16x128_f8f6f4 v[0:3], v[136:143], v[160:167], v[176:179], v205, v205 op_sel_hi:[0,0,0]
	s_setprio 0
	s_add_i32 vcc_hi, vcc_hi, 2
	s_addk_i32 s5, 0x100
	s_addk_i32 vcc_lo, 0x100
	s_cmp_ge_i32 vcc_hi, s61
	s_barrier
	s_cbranch_scc0 .LBB0_317
	s_and_b64 vcc, exec, s[16:17]
	s_cbranch_vccz .LBB0_320

.LBB0_652:
	ds_read_b128 v[134:137], v142
	ds_read_b128 v[148:151], v142 offset:1024
	ds_read_b128 v[152:155], v142 offset:2048
	ds_read_b128 v[156:159], v142 offset:3072
	ds_read_b128 v[160:163], v143
	ds_read_b128 v[164:167], v143 offset:1024
	ds_read_b128 v[168:171], v143 offset:2048
	ds_read_b128 v[172:175], v143 offset:3072
	s_add_i32 s22, s46, 0xfff00080
	s_cmp_eq_u32 s83, vcc_lo
	s_cselect_b32 s40, s4, s22
	s_cselect_b32 s23, s5, s47
	s_or_b32 s22, s40, 0x80
	s_mov_b32 m0, s85
	ds_read_b128 v[176:179], v144
	ds_read_b128 v[180:183], v144 offset:1024
	ds_read_b128 v[184:187], v144 offset:2048
	ds_read_b128 v[188:191], v144 offset:3072
	ds_read_b128 v[192:195], v144 offset:4096
	ds_read_b128 v[196:199], v144 offset:5120
	ds_read_b128 v[200:203], v144 offset:6144
	ds_read_b128 v[204:207], v144 offset:7168
	buffer_load_dwordx4 v138, s[16:19], s46 offen lds
	s_mov_b32 m0, s86
	s_nop 0
	buffer_load_dwordx4 v140, s[16:19], s46 offen lds
	s_waitcnt vmcnt(8)
	s_waitcnt lgkmcnt(0)
	s_barrier
	s_setprio 1
	s_waitcnt lgkmcnt(7)
	v_mfma_f32_16x16x32_bf16 v[126:129], v[134:137], v[176:179], v[126:129]
	v_mfma_f32_16x16x32_bf16 v[122:125], v[152:155], v[176:179], v[122:125]
	s_waitcnt lgkmcnt(5)
	v_mfma_f32_16x16x32_bf16 v[110:113], v[134:137], v[184:187], v[110:113]
	v_mfma_f32_16x16x32_bf16 v[106:109], v[152:155], v[184:187], v[106:109]
	s_waitcnt lgkmcnt(3)
	v_mfma_f32_16x16x32_bf16 v[94:97], v[134:137], v[192:195], v[94:97]
	v_mfma_f32_16x16x32_bf16 v[90:93], v[152:155], v[192:195], v[90:93]
	s_waitcnt lgkmcnt(1)
	v_mfma_f32_16x16x32_bf16 v[78:81], v[134:137], v[200:203], v[78:81]
	v_mfma_f32_16x16x32_bf16 v[74:77], v[152:155], v[200:203], v[74:77]
	v_mfma_f32_16x16x32_bf16 v[126:129], v[148:151], v[180:183], v[126:129]
	v_mfma_f32_16x16x32_bf16 v[122:125], v[156:159], v[180:183], v[122:125]
	v_mfma_f32_16x16x32_bf16 v[110:113], v[148:151], v[188:191], v[110:113]
	v_mfma_f32_16x16x32_bf16 v[106:109], v[156:159], v[188:191], v[106:109]
	v_mfma_f32_16x16x32_bf16 v[94:97], v[148:151], v[196:199], v[94:97]
	v_mfma_f32_16x16x32_bf16 v[90:93], v[156:159], v[196:199], v[90:93]
	s_waitcnt lgkmcnt(0)
	v_mfma_f32_16x16x32_bf16 v[78:81], v[148:151], v[204:207], v[78:81]
	v_mfma_f32_16x16x32_bf16 v[74:77], v[156:159], v[204:207], v[74:77]
	s_setprio 0
	s_setprio 1
	v_mfma_f32_16x16x32_bf16 v[118:121], v[160:163], v[176:179], v[118:121]
	v_mfma_f32_16x16x32_bf16 v[114:117], v[168:171], v[176:179], v[114:117]
	v_mfma_f32_16x16x32_bf16 v[102:105], v[160:163], v[184:187], v[102:105]
	v_mfma_f32_16x16x32_bf16 v[98:101], v[168:171], v[184:187], v[98:101]
	v_mfma_f32_16x16x32_bf16 v[86:89], v[160:163], v[192:195], v[86:89]
	v_mfma_f32_16x16x32_bf16 v[82:85], v[168:171], v[192:195], v[82:85]
	v_mfma_f32_16x16x32_bf16 v[70:73], v[160:163], v[200:203], v[70:73]
	v_mfma_f32_16x16x32_bf16 v[66:69], v[168:171], v[200:203], v[66:69]
	v_mfma_f32_16x16x32_bf16 v[118:121], v[164:167], v[180:183], v[118:121]
	v_mfma_f32_16x16x32_bf16 v[114:117], v[172:175], v[180:183], v[114:117]
	v_mfma_f32_16x16x32_bf16 v[102:105], v[164:167], v[188:191], v[102:105]
	v_mfma_f32_16x16x32_bf16 v[98:101], v[172:175], v[188:191], v[98:101]
	v_mfma_f32_16x16x32_bf16 v[86:89], v[164:167], v[196:199], v[86:89]
	v_mfma_f32_16x16x32_bf16 v[82:85], v[172:175], v[196:199], v[82:85]
	v_mfma_f32_16x16x32_bf16 v[70:73], v[164:167], v[204:207], v[70:73]
	v_mfma_f32_16x16x32_bf16 v[66:69], v[172:175], v[204:207], v[66:69]
	s_setprio 0
	s_barrier
	s_mov_b32 m0, s20
	s_mov_b32 s78, s18
	s_mov_b32 s79, s19
	ds_read_b128 v[176:179], v144 offset:16384
	ds_read_b128 v[180:183], v144 offset:17408
	ds_read_b128 v[184:187], v144 offset:18432
	ds_read_b128 v[188:191], v144 offset:19456
	ds_read_b128 v[192:195], v144 offset:20480
	ds_read_b128 v[196:199], v144 offset:21504
	ds_read_b128 v[200:203], v144 offset:22528
	ds_read_b128 v[204:207], v144 offset:23552
	buffer_load_dwordx4 v139, s[76:79], s23 offen lds
	s_mov_b32 m0, s21
	s_add_i32 s41, s23, 0x100000
	buffer_load_dwordx4 v141, s[76:79], s23 offen lds
	s_mov_b32 m0, s26
	s_nop 0
	buffer_load_dwordx4 v139, s[76:79], s41 offen lds
	s_mov_b32 m0, s27
	s_nop 0
	buffer_load_dwordx4 v141, s[76:79], s41 offen lds
	s_mov_b32 m0, s15
	s_nop 0
	buffer_load_dwordx4 v138, s[16:19], s40 offen lds
	s_mov_b32 m0, s30
	s_nop 0
	buffer_load_dwordx4 v140, s[16:19], s40 offen lds
	s_waitcnt vmcnt(8)
	s_waitcnt lgkmcnt(0)
	s_barrier
	s_setprio 1
	s_waitcnt lgkmcnt(7)
	v_mfma_f32_16x16x32_bf16 v[62:65], v[134:137], v[176:179], v[62:65]
	v_mfma_f32_16x16x32_bf16 v[58:61], v[152:155], v[176:179], v[58:61]
	s_waitcnt lgkmcnt(5)
	v_mfma_f32_16x16x32_bf16 v[46:49], v[134:137], v[184:187], v[46:49]
	v_mfma_f32_16x16x32_bf16 v[42:45], v[152:155], v[184:187], v[42:45]
	s_waitcnt lgkmcnt(3)
	v_mfma_f32_16x16x32_bf16 v[30:33], v[134:137], v[192:195], v[30:33]
	v_mfma_f32_16x16x32_bf16 v[26:29], v[152:155], v[192:195], v[26:29]
	s_waitcnt lgkmcnt(1)
	v_mfma_f32_16x16x32_bf16 v[14:17], v[134:137], v[200:203], v[14:17]
	v_mfma_f32_16x16x32_bf16 v[10:13], v[152:155], v[200:203], v[10:13]
	v_mfma_f32_16x16x32_bf16 v[62:65], v[148:151], v[180:183], v[62:65]
	v_mfma_f32_16x16x32_bf16 v[58:61], v[156:159], v[180:183], v[58:61]
	v_mfma_f32_16x16x32_bf16 v[46:49], v[148:151], v[188:191], v[46:49]
	v_mfma_f32_16x16x32_bf16 v[42:45], v[156:159], v[188:191], v[42:45]
	v_mfma_f32_16x16x32_bf16 v[30:33], v[148:151], v[196:199], v[30:33]
	v_mfma_f32_16x16x32_bf16 v[26:29], v[156:159], v[196:199], v[26:29]
	s_waitcnt lgkmcnt(0)
	v_mfma_f32_16x16x32_bf16 v[14:17], v[148:151], v[204:207], v[14:17]
	v_mfma_f32_16x16x32_bf16 v[10:13], v[156:159], v[204:207], v[10:13]
	s_setprio 0
	s_setprio 1
	v_mfma_f32_16x16x32_bf16 v[54:57], v[160:163], v[176:179], v[54:57]
	v_mfma_f32_16x16x32_bf16 v[50:53], v[168:171], v[176:179], v[50:53]
	v_mfma_f32_16x16x32_bf16 v[38:41], v[160:163], v[184:187], v[38:41]
	v_mfma_f32_16x16x32_bf16 v[34:37], v[168:171], v[184:187], v[34:37]
	v_mfma_f32_16x16x32_bf16 v[22:25], v[160:163], v[192:195], v[22:25]
	v_mfma_f32_16x16x32_bf16 v[18:21], v[168:171], v[192:195], v[18:21]
	v_mfma_f32_16x16x32_bf16 v[6:9], v[160:163], v[200:203], v[6:9]
	v_mfma_f32_16x16x32_bf16 v[2:5], v[168:171], v[200:203], v[2:5]
	v_mfma_f32_16x16x32_bf16 v[54:57], v[164:167], v[180:183], v[54:57]
	v_mfma_f32_16x16x32_bf16 v[50:53], v[172:175], v[180:183], v[50:53]
	v_mfma_f32_16x16x32_bf16 v[38:41], v[164:167], v[188:191], v[38:41]
	v_mfma_f32_16x16x32_bf16 v[34:37], v[172:175], v[188:191], v[34:37]
	v_mfma_f32_16x16x32_bf16 v[22:25], v[164:167], v[196:199], v[22:25]
	v_mfma_f32_16x16x32_bf16 v[18:21], v[172:175], v[196:199], v[18:21]
	v_mfma_f32_16x16x32_bf16 v[6:9], v[164:167], v[204:207], v[6:9]
	v_mfma_f32_16x16x32_bf16 v[2:5], v[172:175], v[204:207], v[2:5]
	s_setprio 0
	s_barrier
	ds_read_b128 v[134:137], v145
	ds_read_b128 v[148:151], v145 offset:1024
	ds_read_b128 v[152:155], v145 offset:2048
	ds_read_b128 v[156:159], v145 offset:3072
	ds_read_b128 v[160:163], v146
	ds_read_b128 v[164:167], v146 offset:1024
	ds_read_b128 v[168:171], v146 offset:2048
	ds_read_b128 v[172:175], v146 offset:3072
	s_add_i32 s40, s40, 0x100000
	s_mov_b32 m0, s31
	ds_read_b128 v[176:179], v144 offset:32768
	ds_read_b128 v[180:183], v144 offset:33792
	ds_read_b128 v[184:187], v144 offset:34816
	ds_read_b128 v[188:191], v144 offset:35840
	ds_read_b128 v[192:195], v144 offset:36864
	ds_read_b128 v[196:199], v144 offset:37888
	ds_read_b128 v[200:203], v144 offset:38912
	ds_read_b128 v[204:207], v144 offset:39936
	buffer_load_dwordx4 v138, s[16:19], s40 offen lds
	s_mov_b32 m0, s50
	s_nop 0
	buffer_load_dwordx4 v140, s[16:19], s40 offen lds
	s_waitcnt vmcnt(8)
	s_waitcnt lgkmcnt(0)
	s_barrier
	s_setprio 1
	s_waitcnt lgkmcnt(7)
	v_mfma_f32_16x16x32_bf16 v[126:129], v[134:137], v[176:179], v[126:129]
	v_mfma_f32_16x16x32_bf16 v[122:125], v[152:155], v[176:179], v[122:125]
	s_waitcnt lgkmcnt(5)
	v_mfma_f32_16x16x32_bf16 v[110:113], v[134:137], v[184:187], v[110:113]
	v_mfma_f32_16x16x32_bf16 v[106:109], v[152:155], v[184:187], v[106:109]
	s_waitcnt lgkmcnt(3)
	v_mfma_f32_16x16x32_bf16 v[94:97], v[134:137], v[192:195], v[94:97]
	v_mfma_f32_16x16x32_bf16 v[90:93], v[152:155], v[192:195], v[90:93]
	s_waitcnt lgkmcnt(1)
	v_mfma_f32_16x16x32_bf16 v[78:81], v[134:137], v[200:203], v[78:81]
	v_mfma_f32_16x16x32_bf16 v[74:77], v[152:155], v[200:203], v[74:77]
	v_mfma_f32_16x16x32_bf16 v[126:129], v[148:151], v[180:183], v[126:129]
	v_mfma_f32_16x16x32_bf16 v[122:125], v[156:159], v[180:183], v[122:125]
	v_mfma_f32_16x16x32_bf16 v[110:113], v[148:151], v[188:191], v[110:113]
	v_mfma_f32_16x16x32_bf16 v[106:109], v[156:159], v[188:191], v[106:109]
	v_mfma_f32_16x16x32_bf16 v[94:97], v[148:151], v[196:199], v[94:97]
	v_mfma_f32_16x16x32_bf16 v[90:93], v[156:159], v[196:199], v[90:93]
	s_waitcnt lgkmcnt(0)
	v_mfma_f32_16x16x32_bf16 v[78:81], v[148:151], v[204:207], v[78:81]
	v_mfma_f32_16x16x32_bf16 v[74:77], v[156:159], v[204:207], v[74:77]
	s_setprio 0
	s_setprio 1
	v_mfma_f32_16x16x32_bf16 v[118:121], v[160:163], v[176:179], v[118:121]
	v_mfma_f32_16x16x32_bf16 v[114:117], v[168:171], v[176:179], v[114:117]
	v_mfma_f32_16x16x32_bf16 v[102:105], v[160:163], v[184:187], v[102:105]
	v_mfma_f32_16x16x32_bf16 v[98:101], v[168:171], v[184:187], v[98:101]
	v_mfma_f32_16x16x32_bf16 v[86:89], v[160:163], v[192:195], v[86:89]
	v_mfma_f32_16x16x32_bf16 v[82:85], v[168:171], v[192:195], v[82:85]
	v_mfma_f32_16x16x32_bf16 v[70:73], v[160:163], v[200:203], v[70:73]
	v_mfma_f32_16x16x32_bf16 v[66:69], v[168:171], v[200:203], v[66:69]
	v_mfma_f32_16x16x32_bf16 v[118:121], v[164:167], v[180:183], v[118:121]
	v_mfma_f32_16x16x32_bf16 v[114:117], v[172:175], v[180:183], v[114:117]
	v_mfma_f32_16x16x32_bf16 v[102:105], v[164:167], v[188:191], v[102:105]
	v_mfma_f32_16x16x32_bf16 v[98:101], v[172:175], v[188:191], v[98:101]
	v_mfma_f32_16x16x32_bf16 v[86:89], v[164:167], v[196:199], v[86:89]
	v_mfma_f32_16x16x32_bf16 v[82:85], v[172:175], v[196:199], v[82:85]
	v_mfma_f32_16x16x32_bf16 v[70:73], v[164:167], v[204:207], v[70:73]
	v_mfma_f32_16x16x32_bf16 v[66:69], v[172:175], v[204:207], v[66:69]
	s_setprio 0
	s_barrier
	s_mov_b32 m0, s58
	s_or_b32 s40, s23, 0x80
	ds_read_b128 v[176:179], v144 offset:49152
	ds_read_b128 v[180:183], v144 offset:50176
	ds_read_b128 v[184:187], v144 offset:51200
	ds_read_b128 v[188:191], v144 offset:52224
	ds_read_b128 v[192:195], v144 offset:53248
	ds_read_b128 v[196:199], v144 offset:54272
	ds_read_b128 v[200:203], v144 offset:55296
	ds_read_b128 v[204:207], v144 offset:56320
	buffer_load_dwordx4 v139, s[76:79], s40 offen lds
	s_mov_b32 m0, s59
	s_add_i32 s23, s23, 0x100080
	buffer_load_dwordx4 v141, s[76:79], s40 offen lds
	s_mov_b32 m0, s73
	s_nop 0
	buffer_load_dwordx4 v139, s[76:79], s23 offen lds
	s_mov_b32 m0, s74
	s_nop 0
	buffer_load_dwordx4 v141, s[76:79], s23 offen lds
	s_mov_b32 m0, s70
	s_nop 0
	buffer_load_dwordx4 v138, s[16:19], s22 offen lds
	s_mov_b32 m0, s71
	s_nop 0
	buffer_load_dwordx4 v140, s[16:19], s22 offen lds
	s_waitcnt vmcnt(8)
	s_waitcnt lgkmcnt(0)
	s_barrier
	s_setprio 1
	s_waitcnt lgkmcnt(7)
	v_mfma_f32_16x16x32_bf16 v[62:65], v[134:137], v[176:179], v[62:65]
	v_mfma_f32_16x16x32_bf16 v[58:61], v[152:155], v[176:179], v[58:61]
	s_waitcnt lgkmcnt(5)
	v_mfma_f32_16x16x32_bf16 v[46:49], v[134:137], v[184:187], v[46:49]
	v_mfma_f32_16x16x32_bf16 v[42:45], v[152:155], v[184:187], v[42:45]
	s_waitcnt lgkmcnt(3)
	v_mfma_f32_16x16x32_bf16 v[30:33], v[134:137], v[192:195], v[30:33]
	v_mfma_f32_16x16x32_bf16 v[26:29], v[152:155], v[192:195], v[26:29]
	s_waitcnt lgkmcnt(1)
	v_mfma_f32_16x16x32_bf16 v[14:17], v[134:137], v[200:203], v[14:17]
	v_mfma_f32_16x16x32_bf16 v[10:13], v[152:155], v[200:203], v[10:13]
	v_mfma_f32_16x16x32_bf16 v[62:65], v[148:151], v[180:183], v[62:65]
	v_mfma_f32_16x16x32_bf16 v[58:61], v[156:159], v[180:183], v[58:61]
	v_mfma_f32_16x16x32_bf16 v[46:49], v[148:151], v[188:191], v[46:49]
	v_mfma_f32_16x16x32_bf16 v[42:45], v[156:159], v[188:191], v[42:45]
	v_mfma_f32_16x16x32_bf16 v[30:33], v[148:151], v[196:199], v[30:33]
	v_mfma_f32_16x16x32_bf16 v[26:29], v[156:159], v[196:199], v[26:29]
	s_waitcnt lgkmcnt(0)
	v_mfma_f32_16x16x32_bf16 v[14:17], v[148:151], v[204:207], v[14:17]
	v_mfma_f32_16x16x32_bf16 v[10:13], v[156:159], v[204:207], v[10:13]
	s_setprio 0
	s_setprio 1
	v_mfma_f32_16x16x32_bf16 v[54:57], v[160:163], v[176:179], v[54:57]
	v_mfma_f32_16x16x32_bf16 v[50:53], v[168:171], v[176:179], v[50:53]
	v_mfma_f32_16x16x32_bf16 v[38:41], v[160:163], v[184:187], v[38:41]
	v_mfma_f32_16x16x32_bf16 v[34:37], v[168:171], v[184:187], v[34:37]
	v_mfma_f32_16x16x32_bf16 v[22:25], v[160:163], v[192:195], v[22:25]
	v_mfma_f32_16x16x32_bf16 v[18:21], v[168:171], v[192:195], v[18:21]
	v_mfma_f32_16x16x32_bf16 v[6:9], v[160:163], v[200:203], v[6:9]
	v_mfma_f32_16x16x32_bf16 v[2:5], v[168:171], v[200:203], v[2:5]
	v_mfma_f32_16x16x32_bf16 v[54:57], v[164:167], v[180:183], v[54:57]
	v_mfma_f32_16x16x32_bf16 v[50:53], v[172:175], v[180:183], v[50:53]
	v_mfma_f32_16x16x32_bf16 v[38:41], v[164:167], v[188:191], v[38:41]
	v_mfma_f32_16x16x32_bf16 v[34:37], v[172:175], v[188:191], v[34:37]
	v_mfma_f32_16x16x32_bf16 v[22:25], v[164:167], v[196:199], v[22:25]
	v_mfma_f32_16x16x32_bf16 v[18:21], v[172:175], v[196:199], v[18:21]
	v_mfma_f32_16x16x32_bf16 v[6:9], v[164:167], v[204:207], v[6:9]
	v_mfma_f32_16x16x32_bf16 v[2:5], v[172:175], v[204:207], v[2:5]
	s_setprio 0
	s_add_i32 vcc_lo, vcc_lo, 2
	s_addk_i32 s46, 0x100
	s_addk_i32 s47, 0x100
	s_cmp_ge_i32 vcc_lo, s82
	s_barrier
	s_cbranch_scc0 .LBB0_652

.LBB0_701:
	v_add_u32_e32 v136, 0x10000, v179
	ds_read_b128 v[132:135], v136
	ds_read_b128 v[138:141], v136 offset:1024
	ds_read_b128 v[142:145], v136 offset:2048
	ds_read_b128 v[146:149], v136 offset:3072
	v_add_u32_e32 v136, 0x14000, v179
	ds_read_b128 v[150:153], v136
	ds_read_b128 v[156:159], v136 offset:1024
	ds_read_b128 v[160:163], v136 offset:2048
	ds_read_b128 v[164:167], v136 offset:3072
	s_add_i32 s22, s85, 0xfff80080
	s_cmp_eq_u32 s6, s87
	s_cselect_b32 s40, s82, s22
	s_cselect_b32 s23, s83, s86
	s_or_b32 s22, s40, 0x80
	s_mov_b32 m0, s7
	ds_read_b128 v[168:171], v182
	ds_read_b128 v[184:187], v182 offset:1024
	ds_read_b128 v[188:191], v182 offset:2048
	ds_read_b128 v[192:195], v182 offset:3072
	ds_read_b128 v[196:199], v182 offset:4096
	ds_read_b128 v[200:203], v182 offset:5120
	ds_read_b128 v[204:207], v182 offset:6144
	ds_read_b128 v[208:211], v182 offset:7168
	buffer_load_dwordx4 v137, s[88:91], s85 offen lds
	s_mov_b32 m0, s74
	s_nop 0
	buffer_load_dwordx4 v173, s[88:91], s85 offen lds
	s_waitcnt vmcnt(8)
	s_waitcnt lgkmcnt(0)
	s_barrier
	s_setprio 1
	s_waitcnt lgkmcnt(7)
	v_mfma_i32_16x16x64_i8 v[124:127], v[132:135], v[168:171], v[124:127]
	v_mfma_i32_16x16x64_i8 v[120:123], v[142:145], v[168:171], v[120:123]
	s_waitcnt lgkmcnt(5)
	v_mfma_i32_16x16x64_i8 v[116:119], v[132:135], v[188:191], v[116:119]
	v_mfma_i32_16x16x64_i8 v[112:115], v[142:145], v[188:191], v[112:115]
	s_waitcnt lgkmcnt(3)
	v_mfma_i32_16x16x64_i8 v[104:107], v[132:135], v[196:199], v[104:107]
	v_mfma_i32_16x16x64_i8 v[96:99], v[142:145], v[196:199], v[96:99]
	s_waitcnt lgkmcnt(1)
	v_mfma_i32_16x16x64_i8 v[88:91], v[132:135], v[204:207], v[88:91]
	v_mfma_i32_16x16x64_i8 v[80:83], v[142:145], v[204:207], v[80:83]
	v_mfma_i32_16x16x64_i8 v[124:127], v[138:141], v[184:187], v[124:127]
	v_mfma_i32_16x16x64_i8 v[120:123], v[146:149], v[184:187], v[120:123]
	v_mfma_i32_16x16x64_i8 v[116:119], v[138:141], v[192:195], v[116:119]
	v_mfma_i32_16x16x64_i8 v[112:115], v[146:149], v[192:195], v[112:115]
	v_mfma_i32_16x16x64_i8 v[104:107], v[138:141], v[200:203], v[104:107]
	v_mfma_i32_16x16x64_i8 v[96:99], v[146:149], v[200:203], v[96:99]
	s_waitcnt lgkmcnt(0)
	v_mfma_i32_16x16x64_i8 v[88:91], v[138:141], v[208:211], v[88:91]
	v_mfma_i32_16x16x64_i8 v[80:83], v[146:149], v[208:211], v[80:83]
	s_setprio 0
	s_setprio 1
	v_mfma_i32_16x16x64_i8 v[108:111], v[150:153], v[168:171], v[108:111]
	v_mfma_i32_16x16x64_i8 v[100:103], v[160:163], v[168:171], v[100:103]
	v_mfma_i32_16x16x64_i8 v[92:95], v[150:153], v[188:191], v[92:95]
	v_mfma_i32_16x16x64_i8 v[84:87], v[160:163], v[188:191], v[84:87]
	v_mfma_i32_16x16x64_i8 v[76:79], v[150:153], v[196:199], v[76:79]
	v_mfma_i32_16x16x64_i8 v[72:75], v[160:163], v[196:199], v[72:75]
	v_mfma_i32_16x16x64_i8 v[68:71], v[150:153], v[204:207], v[68:71]
	v_mfma_i32_16x16x64_i8 v[64:67], v[160:163], v[204:207], v[64:67]
	v_mfma_i32_16x16x64_i8 v[108:111], v[156:159], v[184:187], v[108:111]
	v_mfma_i32_16x16x64_i8 v[100:103], v[164:167], v[184:187], v[100:103]
	v_mfma_i32_16x16x64_i8 v[92:95], v[156:159], v[192:195], v[92:95]
	v_mfma_i32_16x16x64_i8 v[84:87], v[164:167], v[192:195], v[84:87]
	v_mfma_i32_16x16x64_i8 v[76:79], v[156:159], v[200:203], v[76:79]
	v_mfma_i32_16x16x64_i8 v[72:75], v[164:167], v[200:203], v[72:75]
	v_mfma_i32_16x16x64_i8 v[68:71], v[156:159], v[208:211], v[68:71]
	v_mfma_i32_16x16x64_i8 v[64:67], v[164:167], v[208:211], v[64:67]
	s_setprio 0
	s_barrier
	s_mov_b32 m0, s17
	ds_read_b128 v[168:171], v182 offset:16384
	ds_read_b128 v[184:187], v182 offset:17408
	ds_read_b128 v[188:191], v182 offset:18432
	ds_read_b128 v[192:195], v182 offset:19456
	ds_read_b128 v[196:199], v182 offset:20480
	ds_read_b128 v[200:203], v182 offset:21504
	ds_read_b128 v[204:207], v182 offset:22528
	ds_read_b128 v[208:211], v182 offset:23552
	buffer_load_dwordx4 v155, s[68:71], s23 offen lds
	s_mov_b32 m0, s19
	s_add_i32 s41, s23, 0x80000
	buffer_load_dwordx4 v175, s[68:71], s23 offen lds
	s_mov_b32 m0, s20
	s_nop 0
	buffer_load_dwordx4 v155, s[68:71], s41 offen lds
	s_mov_b32 m0, s21
	s_nop 0
	buffer_load_dwordx4 v175, s[68:71], s41 offen lds
	s_mov_b32 m0, s15
	s_nop 0
	buffer_load_dwordx4 v137, s[88:91], s40 offen lds
	s_mov_b32 m0, s26
	s_nop 0
	buffer_load_dwordx4 v173, s[88:91], s40 offen lds
	s_waitcnt vmcnt(8)
	s_waitcnt lgkmcnt(0)
	s_barrier
	s_setprio 1
	s_waitcnt lgkmcnt(7)
	v_mfma_i32_16x16x64_i8 v[60:63], v[132:135], v[168:171], v[60:63]
	v_mfma_i32_16x16x64_i8 v[56:59], v[142:145], v[168:171], v[56:59]
	s_waitcnt lgkmcnt(5)
	v_mfma_i32_16x16x64_i8 v[52:55], v[132:135], v[188:191], v[52:55]
	v_mfma_i32_16x16x64_i8 v[48:51], v[142:145], v[188:191], v[48:51]
	s_waitcnt lgkmcnt(3)
	v_mfma_i32_16x16x64_i8 v[40:43], v[132:135], v[196:199], v[40:43]
	v_mfma_i32_16x16x64_i8 v[32:35], v[142:145], v[196:199], v[32:35]
	s_waitcnt lgkmcnt(1)
	v_mfma_i32_16x16x64_i8 v[24:27], v[132:135], v[204:207], v[24:27]
	v_mfma_i32_16x16x64_i8 v[16:19], v[142:145], v[204:207], v[16:19]
	v_mfma_i32_16x16x64_i8 v[60:63], v[138:141], v[184:187], v[60:63]
	v_mfma_i32_16x16x64_i8 v[56:59], v[146:149], v[184:187], v[56:59]
	v_mfma_i32_16x16x64_i8 v[52:55], v[138:141], v[192:195], v[52:55]
	v_mfma_i32_16x16x64_i8 v[48:51], v[146:149], v[192:195], v[48:51]
	v_mfma_i32_16x16x64_i8 v[40:43], v[138:141], v[200:203], v[40:43]
	v_mfma_i32_16x16x64_i8 v[32:35], v[146:149], v[200:203], v[32:35]
	s_waitcnt lgkmcnt(0)
	v_mfma_i32_16x16x64_i8 v[24:27], v[138:141], v[208:211], v[24:27]
	v_mfma_i32_16x16x64_i8 v[16:19], v[146:149], v[208:211], v[16:19]
	s_setprio 0
	s_setprio 1
	v_mfma_i32_16x16x64_i8 v[44:47], v[150:153], v[168:171], v[44:47]
	v_mfma_i32_16x16x64_i8 v[36:39], v[160:163], v[168:171], v[36:39]
	v_mfma_i32_16x16x64_i8 v[28:31], v[150:153], v[188:191], v[28:31]
	v_mfma_i32_16x16x64_i8 v[20:23], v[160:163], v[188:191], v[20:23]
	v_mfma_i32_16x16x64_i8 v[12:15], v[150:153], v[196:199], v[12:15]
	v_mfma_i32_16x16x64_i8 v[8:11], v[160:163], v[196:199], v[8:11]
	v_mfma_i32_16x16x64_i8 v[4:7], v[150:153], v[204:207], v[4:7]
	v_mfma_i32_16x16x64_i8 v[0:3], v[160:163], v[204:207], v[0:3]
	v_mfma_i32_16x16x64_i8 v[44:47], v[156:159], v[184:187], v[44:47]
	v_mfma_i32_16x16x64_i8 v[36:39], v[164:167], v[184:187], v[36:39]
	v_mfma_i32_16x16x64_i8 v[28:31], v[156:159], v[192:195], v[28:31]
	v_mfma_i32_16x16x64_i8 v[20:23], v[164:167], v[192:195], v[20:23]
	v_mfma_i32_16x16x64_i8 v[12:15], v[156:159], v[200:203], v[12:15]
	v_mfma_i32_16x16x64_i8 v[8:11], v[164:167], v[200:203], v[8:11]
	v_mfma_i32_16x16x64_i8 v[4:7], v[156:159], v[208:211], v[4:7]
	v_mfma_i32_16x16x64_i8 v[0:3], v[164:167], v[208:211], v[0:3]
	s_setprio 0
	s_barrier
	v_add_u32_e32 v136, 0x18000, v179
	ds_read_b128 v[132:135], v136
	ds_read_b128 v[138:141], v136 offset:1024
	ds_read_b128 v[142:145], v136 offset:2048
	ds_read_b128 v[146:149], v136 offset:3072
	v_add_u32_e32 v136, 0x1c000, v179
	ds_read_b128 v[150:153], v136
	ds_read_b128 v[156:159], v136 offset:1024
	ds_read_b128 v[160:163], v136 offset:2048
	ds_read_b128 v[164:167], v136 offset:3072
	s_add_i32 s40, s40, 0x80000
	s_mov_b32 m0, s27
	ds_read_b128 v[168:171], v182 offset:32768
	ds_read_b128 v[184:187], v182 offset:33792
	ds_read_b128 v[188:191], v182 offset:34816
	ds_read_b128 v[192:195], v182 offset:35840
	ds_read_b128 v[196:199], v182 offset:36864
	ds_read_b128 v[200:203], v182 offset:37888
	ds_read_b128 v[204:207], v182 offset:38912
	ds_read_b128 v[208:211], v182 offset:39936
	buffer_load_dwordx4 v137, s[88:91], s40 offen lds
	s_mov_b32 m0, s30
	s_nop 0
	buffer_load_dwordx4 v173, s[88:91], s40 offen lds
	s_waitcnt vmcnt(8)
	s_waitcnt lgkmcnt(0)
	s_barrier
	s_setprio 1
	s_waitcnt lgkmcnt(7)
	v_mfma_i32_16x16x64_i8 v[124:127], v[132:135], v[168:171], v[124:127]
	v_mfma_i32_16x16x64_i8 v[120:123], v[142:145], v[168:171], v[120:123]
	s_waitcnt lgkmcnt(5)
	v_mfma_i32_16x16x64_i8 v[116:119], v[132:135], v[188:191], v[116:119]
	v_mfma_i32_16x16x64_i8 v[112:115], v[142:145], v[188:191], v[112:115]
	s_waitcnt lgkmcnt(3)
	v_mfma_i32_16x16x64_i8 v[104:107], v[132:135], v[196:199], v[104:107]
	v_mfma_i32_16x16x64_i8 v[96:99], v[142:145], v[196:199], v[96:99]
	s_waitcnt lgkmcnt(1)
	v_mfma_i32_16x16x64_i8 v[88:91], v[132:135], v[204:207], v[88:91]
	v_mfma_i32_16x16x64_i8 v[80:83], v[142:145], v[204:207], v[80:83]
	v_mfma_i32_16x16x64_i8 v[124:127], v[138:141], v[184:187], v[124:127]
	v_mfma_i32_16x16x64_i8 v[120:123], v[146:149], v[184:187], v[120:123]
	v_mfma_i32_16x16x64_i8 v[116:119], v[138:141], v[192:195], v[116:119]
	v_mfma_i32_16x16x64_i8 v[112:115], v[146:149], v[192:195], v[112:115]
	v_mfma_i32_16x16x64_i8 v[104:107], v[138:141], v[200:203], v[104:107]
	v_mfma_i32_16x16x64_i8 v[96:99], v[146:149], v[200:203], v[96:99]
	s_waitcnt lgkmcnt(0)
	v_mfma_i32_16x16x64_i8 v[88:91], v[138:141], v[208:211], v[88:91]
	v_mfma_i32_16x16x64_i8 v[80:83], v[146:149], v[208:211], v[80:83]
	s_setprio 0
	s_setprio 1
	v_mfma_i32_16x16x64_i8 v[108:111], v[150:153], v[168:171], v[108:111]
	v_mfma_i32_16x16x64_i8 v[100:103], v[160:163], v[168:171], v[100:103]
	v_mfma_i32_16x16x64_i8 v[92:95], v[150:153], v[188:191], v[92:95]
	v_mfma_i32_16x16x64_i8 v[84:87], v[160:163], v[188:191], v[84:87]
	v_mfma_i32_16x16x64_i8 v[76:79], v[150:153], v[196:199], v[76:79]
	v_mfma_i32_16x16x64_i8 v[72:75], v[160:163], v[196:199], v[72:75]
	v_mfma_i32_16x16x64_i8 v[68:71], v[150:153], v[204:207], v[68:71]
	v_mfma_i32_16x16x64_i8 v[64:67], v[160:163], v[204:207], v[64:67]
	v_mfma_i32_16x16x64_i8 v[108:111], v[156:159], v[184:187], v[108:111]
	v_mfma_i32_16x16x64_i8 v[100:103], v[164:167], v[184:187], v[100:103]
	v_mfma_i32_16x16x64_i8 v[92:95], v[156:159], v[192:195], v[92:95]
	v_mfma_i32_16x16x64_i8 v[84:87], v[164:167], v[192:195], v[84:87]
	v_mfma_i32_16x16x64_i8 v[76:79], v[156:159], v[200:203], v[76:79]
	v_mfma_i32_16x16x64_i8 v[72:75], v[164:167], v[200:203], v[72:75]
	v_mfma_i32_16x16x64_i8 v[68:71], v[156:159], v[208:211], v[68:71]
	v_mfma_i32_16x16x64_i8 v[64:67], v[164:167], v[208:211], v[64:67]
	s_setprio 0
	s_barrier
	s_mov_b32 m0, s46
	s_or_b32 s40, s23, 0x80
	ds_read_b128 v[168:171], v182 offset:49152
	ds_read_b128 v[184:187], v182 offset:50176
	ds_read_b128 v[188:191], v182 offset:51200
	ds_read_b128 v[192:195], v182 offset:52224
	ds_read_b128 v[196:199], v182 offset:53248
	ds_read_b128 v[200:203], v182 offset:54272
	ds_read_b128 v[204:207], v182 offset:55296
	ds_read_b128 v[208:211], v182 offset:56320
	buffer_load_dwordx4 v155, s[68:71], s40 offen lds
	s_mov_b32 m0, s47
	s_add_i32 s23, s23, 0x80080
	buffer_load_dwordx4 v175, s[68:71], s40 offen lds
	s_mov_b32 m0, s72
	s_nop 0
	buffer_load_dwordx4 v155, s[68:71], s23 offen lds
	s_mov_b32 m0, s94
	s_nop 0
	buffer_load_dwordx4 v175, s[68:71], s23 offen lds
	s_mov_b32 m0, s50
	s_nop 0
	buffer_load_dwordx4 v137, s[88:91], s22 offen lds
	s_mov_b32 m0, s51
	s_nop 0
	buffer_load_dwordx4 v173, s[88:91], s22 offen lds
	s_waitcnt vmcnt(8)
	s_waitcnt lgkmcnt(0)
	s_barrier
	s_setprio 1
	s_waitcnt lgkmcnt(7)
	v_mfma_i32_16x16x64_i8 v[60:63], v[132:135], v[168:171], v[60:63]
	v_mfma_i32_16x16x64_i8 v[56:59], v[142:145], v[168:171], v[56:59]
	s_waitcnt lgkmcnt(5)
	v_mfma_i32_16x16x64_i8 v[52:55], v[132:135], v[188:191], v[52:55]
	v_mfma_i32_16x16x64_i8 v[48:51], v[142:145], v[188:191], v[48:51]
	s_waitcnt lgkmcnt(3)
	v_mfma_i32_16x16x64_i8 v[40:43], v[132:135], v[196:199], v[40:43]
	v_mfma_i32_16x16x64_i8 v[32:35], v[142:145], v[196:199], v[32:35]
	s_waitcnt lgkmcnt(1)
	v_mfma_i32_16x16x64_i8 v[24:27], v[132:135], v[204:207], v[24:27]
	v_mfma_i32_16x16x64_i8 v[16:19], v[142:145], v[204:207], v[16:19]
	v_mfma_i32_16x16x64_i8 v[60:63], v[138:141], v[184:187], v[60:63]
	v_mfma_i32_16x16x64_i8 v[56:59], v[146:149], v[184:187], v[56:59]
	v_mfma_i32_16x16x64_i8 v[52:55], v[138:141], v[192:195], v[52:55]
	v_mfma_i32_16x16x64_i8 v[48:51], v[146:149], v[192:195], v[48:51]
	v_mfma_i32_16x16x64_i8 v[40:43], v[138:141], v[200:203], v[40:43]
	v_mfma_i32_16x16x64_i8 v[32:35], v[146:149], v[200:203], v[32:35]
	s_waitcnt lgkmcnt(0)
	v_mfma_i32_16x16x64_i8 v[24:27], v[138:141], v[208:211], v[24:27]
	v_mfma_i32_16x16x64_i8 v[16:19], v[146:149], v[208:211], v[16:19]
	s_setprio 0
	s_setprio 1
	v_mfma_i32_16x16x64_i8 v[44:47], v[150:153], v[168:171], v[44:47]
	v_mfma_i32_16x16x64_i8 v[36:39], v[160:163], v[168:171], v[36:39]
	v_mfma_i32_16x16x64_i8 v[28:31], v[150:153], v[188:191], v[28:31]
	v_mfma_i32_16x16x64_i8 v[20:23], v[160:163], v[188:191], v[20:23]
	v_mfma_i32_16x16x64_i8 v[12:15], v[150:153], v[196:199], v[12:15]
	v_mfma_i32_16x16x64_i8 v[8:11], v[160:163], v[196:199], v[8:11]
	v_mfma_i32_16x16x64_i8 v[4:7], v[150:153], v[204:207], v[4:7]
	v_mfma_i32_16x16x64_i8 v[0:3], v[160:163], v[204:207], v[0:3]
	v_mfma_i32_16x16x64_i8 v[44:47], v[156:159], v[184:187], v[44:47]
	v_mfma_i32_16x16x64_i8 v[36:39], v[164:167], v[184:187], v[36:39]
	v_mfma_i32_16x16x64_i8 v[28:31], v[156:159], v[192:195], v[28:31]
	v_mfma_i32_16x16x64_i8 v[20:23], v[164:167], v[192:195], v[20:23]
	v_mfma_i32_16x16x64_i8 v[12:15], v[156:159], v[200:203], v[12:15]
	v_mfma_i32_16x16x64_i8 v[8:11], v[164:167], v[200:203], v[8:11]
	v_mfma_i32_16x16x64_i8 v[4:7], v[156:159], v[208:211], v[4:7]
	v_mfma_i32_16x16x64_i8 v[0:3], v[164:167], v[208:211], v[0:3]
	s_setprio 0
	s_add_i32 s87, s87, 2
	s_addk_i32 s85, 0x100
	s_addk_i32 s86, 0x100
	s_cmp_ge_i32 s87, s73
	s_barrier
	s_cbranch_scc0 .LBB0_701
	v_cvt_f32_i32_e32 v166, v124
	v_cvt_f32_i32_e32 v167, v125
	v_cvt_f32_i32_e32 v168, v126
	v_cvt_f32_i32_e32 v169, v127
	v_cvt_f32_i32_e32 v164, v120
	v_cvt_f32_i32_e32 v165, v121
	v_cvt_f32_i32_e32 v170, v122
	v_cvt_f32_i32_e32 v171, v123
	v_cvt_f32_i32_e32 v158, v108
	v_cvt_f32_i32_e32 v159, v109
	v_cvt_f32_i32_e32 v162, v110
	v_cvt_f32_i32_e32 v163, v111
	v_cvt_f32_i32_e32 v156, v100
	v_cvt_f32_i32_e32 v157, v101
	v_cvt_f32_i32_e32 v160, v102
	v_cvt_f32_i32_e32 v161, v103
	v_cvt_f32_i32_e32 v148, v116
	v_cvt_f32_i32_e32 v149, v117
	v_cvt_f32_i32_e32 v152, v118
	v_cvt_f32_i32_e32 v153, v119
	v_cvt_f32_i32_e32 v146, v112
	v_cvt_f32_i32_e32 v147, v113
	v_cvt_f32_i32_e32 v150, v114
	v_cvt_f32_i32_e32 v151, v115
	v_cvt_f32_i32_e32 v140, v92
	v_cvt_f32_i32_e32 v141, v93
	v_cvt_f32_i32_e32 v144, v94
	v_cvt_f32_i32_e32 v145, v95
	v_cvt_f32_i32_e32 v138, v84
	v_cvt_f32_i32_e32 v139, v85
	v_cvt_f32_i32_e32 v142, v86
	v_cvt_f32_i32_e32 v143, v87
	v_cvt_f32_i32_e32 v110, v104
	v_cvt_f32_i32_e32 v111, v105
	v_cvt_f32_i32_e32 v114, v106
	v_cvt_f32_i32_e32 v115, v107
	v_cvt_f32_i32_e32 v108, v96
	v_cvt_f32_i32_e32 v109, v97
	v_cvt_f32_i32_e32 v112, v98
	v_cvt_f32_i32_e32 v113, v99
	v_cvt_f32_i32_e32 v100, v76
	v_cvt_f32_i32_e32 v101, v77
	v_cvt_f32_i32_e32 v106, v78
	v_cvt_f32_i32_e32 v107, v79
	v_cvt_f32_i32_e32 v98, v72
	v_cvt_f32_i32_e32 v99, v73
	v_cvt_f32_i32_e32 v104, v74
	v_cvt_f32_i32_e32 v105, v75
	v_cvt_f32_i32_e32 v86, v88
	v_cvt_f32_i32_e32 v87, v89
	v_cvt_f32_i32_e32 v90, v90
	v_cvt_f32_i32_e32 v91, v91
	v_cvt_f32_i32_e32 v84, v80
	v_cvt_f32_i32_e32 v85, v81
	v_cvt_f32_i32_e32 v88, v82
	v_cvt_f32_i32_e32 v89, v83
	v_cvt_f32_i32_e32 v78, v68
	v_cvt_f32_i32_e32 v79, v69
	v_cvt_f32_i32_e32 v82, v70
	v_cvt_f32_i32_e32 v83, v71
	v_cvt_f32_i32_e32 v76, v64
	v_cvt_f32_i32_e32 v77, v65
	v_cvt_f32_i32_e32 v80, v66
	v_cvt_f32_i32_e32 v81, v67
	v_cvt_f32_i32_e32 v70, v60
	v_cvt_f32_i32_e32 v71, v61
	v_cvt_f32_i32_e32 v74, v62
	v_cvt_f32_i32_e32 v75, v63
	v_cvt_f32_i32_e32 v68, v56
	v_cvt_f32_i32_e32 v69, v57
	v_cvt_f32_i32_e32 v72, v58
	v_cvt_f32_i32_e32 v73, v59
	v_cvt_f32_i32_e32 v62, v44
	v_cvt_f32_i32_e32 v63, v45
	v_cvt_f32_i32_e32 v66, v46
	v_cvt_f32_i32_e32 v67, v47
	v_cvt_f32_i32_e32 v60, v36
	v_cvt_f32_i32_e32 v61, v37
	v_cvt_f32_i32_e32 v64, v38
	v_cvt_f32_i32_e32 v65, v39
	v_cvt_f32_i32_e32 v56, v52
	v_cvt_f32_i32_e32 v57, v53
	v_cvt_f32_i32_e32 v58, v54
	v_cvt_f32_i32_e32 v59, v55
	v_cvt_f32_i32_e32 v52, v48
	v_cvt_f32_i32_e32 v53, v49
	v_cvt_f32_i32_e32 v54, v50
	v_cvt_f32_i32_e32 v55, v51
	v_cvt_f32_i32_e32 v46, v28
	v_cvt_f32_i32_e32 v47, v29
	v_cvt_f32_i32_e32 v50, v30
	v_cvt_f32_i32_e32 v51, v31
	v_cvt_f32_i32_e32 v44, v20
	v_cvt_f32_i32_e32 v45, v21
	v_cvt_f32_i32_e32 v48, v22
	v_cvt_f32_i32_e32 v49, v23
	v_cvt_f32_i32_e32 v36, v40
	v_cvt_f32_i32_e32 v37, v41
	v_cvt_f32_i32_e32 v38, v42
	v_cvt_f32_i32_e32 v39, v43
	v_cvt_f32_i32_e32 v32, v32
	v_cvt_f32_i32_e32 v33, v33
	v_cvt_f32_i32_e32 v34, v34
	v_cvt_f32_i32_e32 v35, v35
	v_cvt_f32_i32_e32 v22, v12
	v_cvt_f32_i32_e32 v23, v13
	v_cvt_f32_i32_e32 v30, v14
	v_cvt_f32_i32_e32 v31, v15
	v_cvt_f32_i32_e32 v20, v8
	v_cvt_f32_i32_e32 v21, v9
	v_cvt_f32_i32_e32 v28, v10
	v_cvt_f32_i32_e32 v29, v11
	v_cvt_f32_i32_e32 v10, v24
	v_cvt_f32_i32_e32 v11, v25
	v_cvt_f32_i32_e32 v14, v26
	v_cvt_f32_i32_e32 v15, v27
	v_cvt_f32_i32_e32 v8, v16
	v_cvt_f32_i32_e32 v9, v17
	v_cvt_f32_i32_e32 v12, v18
	v_cvt_f32_i32_e32 v13, v19
	v_cvt_f32_i32_e32 v4, v4
	v_cvt_f32_i32_e32 v5, v5
	v_cvt_f32_i32_e32 v6, v6
	v_cvt_f32_i32_e32 v7, v7
	v_cvt_f32_i32_e32 v0, v0
	v_cvt_f32_i32_e32 v1, v1
	v_cvt_f32_i32_e32 v2, v2
	v_cvt_f32_i32_e32 v3, v3

.LBB0_953:
	ds_read_b128 v[128:131], v158
	ds_read_b128 v[132:135], v158 offset:1024
	ds_read_b128 v[136:139], v158 offset:2048
	ds_read_b128 v[140:143], v158 offset:3072
	ds_read_b128 v[148:151], v159
	ds_read_b128 v[164:167], v159 offset:1024
	ds_read_b128 v[168:171], v159 offset:2048
	ds_read_b128 v[172:175], v159 offset:3072
	s_add_i32 s22, s5, 0xfff80080
	s_cmp_eq_u32 s87, s77
	s_cselect_b32 s44, s71, s22
	s_cselect_b32 s23, s4, s76
	s_add_i32 s22, s44, 0x80
	s_mov_b32 m0, s83
	ds_read_b128 v[176:179], v160
	ds_read_b128 v[180:183], v160 offset:1024
	ds_read_b128 v[184:187], v160 offset:2048
	ds_read_b128 v[188:191], v160 offset:3072
	ds_read_b128 v[192:195], v160 offset:4096
	ds_read_b128 v[196:199], v160 offset:5120
	ds_read_b128 v[200:203], v160 offset:6144
	ds_read_b128 v[204:207], v160 offset:7168
	buffer_load_dwordx4 v154, s[16:19], s5 offen lds
	s_mov_b32 m0, s85
	s_nop 0
	buffer_load_dwordx4 v156, s[16:19], s5 offen lds
	s_waitcnt vmcnt(8)
	s_waitcnt lgkmcnt(0)
	s_barrier
	s_setprio 1
	s_waitcnt lgkmcnt(7)
	v_mfma_f32_16x16x32_bf16 v[120:123], v[128:131], v[176:179], v[120:123]
	v_mfma_f32_16x16x32_bf16 v[124:127], v[136:139], v[176:179], v[124:127]
	s_waitcnt lgkmcnt(5)
	v_mfma_f32_16x16x32_bf16 v[108:111], v[128:131], v[184:187], v[108:111]
	v_mfma_f32_16x16x32_bf16 v[104:107], v[136:139], v[184:187], v[104:107]
	s_waitcnt lgkmcnt(3)
	v_mfma_f32_16x16x32_bf16 v[92:95], v[128:131], v[192:195], v[92:95]
	v_mfma_f32_16x16x32_bf16 v[88:91], v[136:139], v[192:195], v[88:91]
	s_waitcnt lgkmcnt(1)
	v_mfma_f32_16x16x32_bf16 v[76:79], v[128:131], v[200:203], v[76:79]
	v_mfma_f32_16x16x32_bf16 v[72:75], v[136:139], v[200:203], v[72:75]
	v_mfma_f32_16x16x32_bf16 v[120:123], v[132:135], v[180:183], v[120:123]
	v_mfma_f32_16x16x32_bf16 v[124:127], v[140:143], v[180:183], v[124:127]
	v_mfma_f32_16x16x32_bf16 v[108:111], v[132:135], v[188:191], v[108:111]
	v_mfma_f32_16x16x32_bf16 v[104:107], v[140:143], v[188:191], v[104:107]
	v_mfma_f32_16x16x32_bf16 v[92:95], v[132:135], v[196:199], v[92:95]
	v_mfma_f32_16x16x32_bf16 v[88:91], v[140:143], v[196:199], v[88:91]
	s_waitcnt lgkmcnt(0)
	v_mfma_f32_16x16x32_bf16 v[76:79], v[132:135], v[204:207], v[76:79]
	v_mfma_f32_16x16x32_bf16 v[72:75], v[140:143], v[204:207], v[72:75]
	s_setprio 0
	s_setprio 1
	v_mfma_f32_16x16x32_bf16 v[116:119], v[148:151], v[176:179], v[116:119]
	v_mfma_f32_16x16x32_bf16 v[112:115], v[168:171], v[176:179], v[112:115]
	v_mfma_f32_16x16x32_bf16 v[100:103], v[148:151], v[184:187], v[100:103]
	v_mfma_f32_16x16x32_bf16 v[96:99], v[168:171], v[184:187], v[96:99]
	v_mfma_f32_16x16x32_bf16 v[84:87], v[148:151], v[192:195], v[84:87]
	v_mfma_f32_16x16x32_bf16 v[80:83], v[168:171], v[192:195], v[80:83]
	v_mfma_f32_16x16x32_bf16 v[68:71], v[148:151], v[200:203], v[68:71]
	v_mfma_f32_16x16x32_bf16 v[64:67], v[168:171], v[200:203], v[64:67]
	v_mfma_f32_16x16x32_bf16 v[116:119], v[164:167], v[180:183], v[116:119]
	v_mfma_f32_16x16x32_bf16 v[112:115], v[172:175], v[180:183], v[112:115]
	v_mfma_f32_16x16x32_bf16 v[100:103], v[164:167], v[188:191], v[100:103]
	v_mfma_f32_16x16x32_bf16 v[96:99], v[172:175], v[188:191], v[96:99]
	v_mfma_f32_16x16x32_bf16 v[84:87], v[164:167], v[196:199], v[84:87]
	v_mfma_f32_16x16x32_bf16 v[80:83], v[172:175], v[196:199], v[80:83]
	v_mfma_f32_16x16x32_bf16 v[68:71], v[164:167], v[204:207], v[68:71]
	v_mfma_f32_16x16x32_bf16 v[64:67], v[172:175], v[204:207], v[64:67]
	s_setprio 0
	s_barrier
	s_mov_b32 m0, s14
	s_mov_b32 s26, s18
	s_mov_b32 s27, s19
	ds_read_b128 v[176:179], v160 offset:16384
	ds_read_b128 v[180:183], v160 offset:17408
	ds_read_b128 v[184:187], v160 offset:18432
	ds_read_b128 v[188:191], v160 offset:19456
	ds_read_b128 v[192:195], v160 offset:20480
	ds_read_b128 v[196:199], v160 offset:21504
	ds_read_b128 v[200:203], v160 offset:22528
	ds_read_b128 v[204:207], v160 offset:23552
	buffer_load_dwordx4 v155, s[24:27], s23 offen lds
	s_mov_b32 m0, s20
	s_add_i32 s45, s23, 0x20000
	buffer_load_dwordx4 v157, s[24:27], s23 offen lds
	s_mov_b32 m0, s21
	s_nop 0
	buffer_load_dwordx4 v155, s[24:27], s45 offen lds
	s_mov_b32 m0, s31
	s_nop 0
	buffer_load_dwordx4 v157, s[24:27], s45 offen lds
	s_mov_b32 m0, s3
	s_nop 0
	buffer_load_dwordx4 v154, s[16:19], s44 offen lds
	s_mov_b32 m0, s41
	s_nop 0
	buffer_load_dwordx4 v156, s[16:19], s44 offen lds
	s_waitcnt vmcnt(8)
	s_waitcnt lgkmcnt(0)
	s_barrier
	s_setprio 1
	s_waitcnt lgkmcnt(7)
	v_mfma_f32_16x16x32_bf16 v[60:63], v[128:131], v[176:179], v[60:63]
	v_mfma_f32_16x16x32_bf16 v[56:59], v[136:139], v[176:179], v[56:59]
	s_waitcnt lgkmcnt(5)
	v_mfma_f32_16x16x32_bf16 v[44:47], v[128:131], v[184:187], v[44:47]
	v_mfma_f32_16x16x32_bf16 v[40:43], v[136:139], v[184:187], v[40:43]
	s_waitcnt lgkmcnt(3)
	v_mfma_f32_16x16x32_bf16 v[28:31], v[128:131], v[192:195], v[28:31]
	v_mfma_f32_16x16x32_bf16 v[24:27], v[136:139], v[192:195], v[24:27]
	s_waitcnt lgkmcnt(1)
	v_mfma_f32_16x16x32_bf16 v[12:15], v[128:131], v[200:203], v[12:15]
	v_mfma_f32_16x16x32_bf16 v[8:11], v[136:139], v[200:203], v[8:11]
	v_mfma_f32_16x16x32_bf16 v[60:63], v[132:135], v[180:183], v[60:63]
	v_mfma_f32_16x16x32_bf16 v[56:59], v[140:143], v[180:183], v[56:59]
	v_mfma_f32_16x16x32_bf16 v[44:47], v[132:135], v[188:191], v[44:47]
	v_mfma_f32_16x16x32_bf16 v[40:43], v[140:143], v[188:191], v[40:43]
	v_mfma_f32_16x16x32_bf16 v[28:31], v[132:135], v[196:199], v[28:31]
	v_mfma_f32_16x16x32_bf16 v[24:27], v[140:143], v[196:199], v[24:27]
	s_waitcnt lgkmcnt(0)
	v_mfma_f32_16x16x32_bf16 v[12:15], v[132:135], v[204:207], v[12:15]
	v_mfma_f32_16x16x32_bf16 v[8:11], v[140:143], v[204:207], v[8:11]
	s_setprio 0
	s_setprio 1
	v_mfma_f32_16x16x32_bf16 v[52:55], v[148:151], v[176:179], v[52:55]
	v_mfma_f32_16x16x32_bf16 v[48:51], v[168:171], v[176:179], v[48:51]
	v_mfma_f32_16x16x32_bf16 v[36:39], v[148:151], v[184:187], v[36:39]
	v_mfma_f32_16x16x32_bf16 v[32:35], v[168:171], v[184:187], v[32:35]
	v_mfma_f32_16x16x32_bf16 v[20:23], v[148:151], v[192:195], v[20:23]
	v_mfma_f32_16x16x32_bf16 v[16:19], v[168:171], v[192:195], v[16:19]
	v_mfma_f32_16x16x32_bf16 v[4:7], v[148:151], v[200:203], v[4:7]
	v_mfma_f32_16x16x32_bf16 v[0:3], v[168:171], v[200:203], v[0:3]
	v_mfma_f32_16x16x32_bf16 v[52:55], v[164:167], v[180:183], v[52:55]
	v_mfma_f32_16x16x32_bf16 v[48:51], v[172:175], v[180:183], v[48:51]
	v_mfma_f32_16x16x32_bf16 v[36:39], v[164:167], v[188:191], v[36:39]
	v_mfma_f32_16x16x32_bf16 v[32:35], v[172:175], v[188:191], v[32:35]
	v_mfma_f32_16x16x32_bf16 v[20:23], v[164:167], v[196:199], v[20:23]
	v_mfma_f32_16x16x32_bf16 v[16:19], v[172:175], v[196:199], v[16:19]
	v_mfma_f32_16x16x32_bf16 v[4:7], v[164:167], v[204:207], v[4:7]
	v_mfma_f32_16x16x32_bf16 v[0:3], v[172:175], v[204:207], v[0:3]
	s_setprio 0
	s_barrier
	ds_read_b128 v[128:131], v161
	ds_read_b128 v[132:135], v161 offset:1024
	ds_read_b128 v[136:139], v161 offset:2048
	ds_read_b128 v[140:143], v161 offset:3072
	ds_read_b128 v[148:151], v162
	ds_read_b128 v[164:167], v162 offset:1024
	ds_read_b128 v[168:171], v162 offset:2048
	ds_read_b128 v[172:175], v162 offset:3072
	s_add_i32 s44, s44, 0x80000
	s_mov_b32 m0, s42
	ds_read_b128 v[176:179], v160 offset:32768
	ds_read_b128 v[180:183], v160 offset:33792
	ds_read_b128 v[184:187], v160 offset:34816
	ds_read_b128 v[188:191], v160 offset:35840
	ds_read_b128 v[192:195], v160 offset:36864
	ds_read_b128 v[196:199], v160 offset:37888
	ds_read_b128 v[200:203], v160 offset:38912
	ds_read_b128 v[204:207], v160 offset:39936
	buffer_load_dwordx4 v154, s[16:19], s44 offen lds
	s_mov_b32 m0, s43
	s_nop 0
	buffer_load_dwordx4 v156, s[16:19], s44 offen lds
	s_waitcnt vmcnt(8)
	s_waitcnt lgkmcnt(0)
	s_barrier
	s_setprio 1
	s_waitcnt lgkmcnt(7)
	v_mfma_f32_16x16x32_bf16 v[120:123], v[128:131], v[176:179], v[120:123]
	v_mfma_f32_16x16x32_bf16 v[124:127], v[136:139], v[176:179], v[124:127]
	s_waitcnt lgkmcnt(5)
	v_mfma_f32_16x16x32_bf16 v[108:111], v[128:131], v[184:187], v[108:111]
	v_mfma_f32_16x16x32_bf16 v[104:107], v[136:139], v[184:187], v[104:107]
	s_waitcnt lgkmcnt(3)
	v_mfma_f32_16x16x32_bf16 v[92:95], v[128:131], v[192:195], v[92:95]
	v_mfma_f32_16x16x32_bf16 v[88:91], v[136:139], v[192:195], v[88:91]
	s_waitcnt lgkmcnt(1)
	v_mfma_f32_16x16x32_bf16 v[76:79], v[128:131], v[200:203], v[76:79]
	v_mfma_f32_16x16x32_bf16 v[72:75], v[136:139], v[200:203], v[72:75]
	v_mfma_f32_16x16x32_bf16 v[120:123], v[132:135], v[180:183], v[120:123]
	v_mfma_f32_16x16x32_bf16 v[124:127], v[140:143], v[180:183], v[124:127]
	v_mfma_f32_16x16x32_bf16 v[108:111], v[132:135], v[188:191], v[108:111]
	v_mfma_f32_16x16x32_bf16 v[104:107], v[140:143], v[188:191], v[104:107]
	v_mfma_f32_16x16x32_bf16 v[92:95], v[132:135], v[196:199], v[92:95]
	v_mfma_f32_16x16x32_bf16 v[88:91], v[140:143], v[196:199], v[88:91]
	s_waitcnt lgkmcnt(0)
	v_mfma_f32_16x16x32_bf16 v[76:79], v[132:135], v[204:207], v[76:79]
	v_mfma_f32_16x16x32_bf16 v[72:75], v[140:143], v[204:207], v[72:75]
	s_setprio 0
	s_setprio 1
	v_mfma_f32_16x16x32_bf16 v[116:119], v[148:151], v[176:179], v[116:119]
	v_mfma_f32_16x16x32_bf16 v[112:115], v[168:171], v[176:179], v[112:115]
	v_mfma_f32_16x16x32_bf16 v[100:103], v[148:151], v[184:187], v[100:103]
	v_mfma_f32_16x16x32_bf16 v[96:99], v[168:171], v[184:187], v[96:99]
	v_mfma_f32_16x16x32_bf16 v[84:87], v[148:151], v[192:195], v[84:87]
	v_mfma_f32_16x16x32_bf16 v[80:83], v[168:171], v[192:195], v[80:83]
	v_mfma_f32_16x16x32_bf16 v[68:71], v[148:151], v[200:203], v[68:71]
	v_mfma_f32_16x16x32_bf16 v[64:67], v[168:171], v[200:203], v[64:67]
	v_mfma_f32_16x16x32_bf16 v[116:119], v[164:167], v[180:183], v[116:119]
	v_mfma_f32_16x16x32_bf16 v[112:115], v[172:175], v[180:183], v[112:115]
	v_mfma_f32_16x16x32_bf16 v[100:103], v[164:167], v[188:191], v[100:103]
	v_mfma_f32_16x16x32_bf16 v[96:99], v[172:175], v[188:191], v[96:99]
	v_mfma_f32_16x16x32_bf16 v[84:87], v[164:167], v[196:199], v[84:87]
	v_mfma_f32_16x16x32_bf16 v[80:83], v[172:175], v[196:199], v[80:83]
	v_mfma_f32_16x16x32_bf16 v[68:71], v[164:167], v[204:207], v[68:71]
	v_mfma_f32_16x16x32_bf16 v[64:67], v[172:175], v[204:207], v[64:67]
	s_setprio 0
	s_barrier
	s_mov_b32 m0, s50
	s_or_b32 s44, s23, 0x80
	ds_read_b128 v[176:179], v160 offset:49152
	ds_read_b128 v[180:183], v160 offset:50176
	ds_read_b128 v[184:187], v160 offset:51200
	ds_read_b128 v[188:191], v160 offset:52224
	ds_read_b128 v[192:195], v160 offset:53248
	ds_read_b128 v[196:199], v160 offset:54272
	ds_read_b128 v[200:203], v160 offset:55296
	ds_read_b128 v[204:207], v160 offset:56320
	buffer_load_dwordx4 v155, s[24:27], s44 offen lds
	s_mov_b32 m0, s51
	s_add_i32 s23, s23, 0x20080
	buffer_load_dwordx4 v157, s[24:27], s44 offen lds
	s_mov_b32 m0, s79
	s_nop 0
	buffer_load_dwordx4 v155, s[24:27], s23 offen lds
	s_mov_b32 m0, s82
	s_nop 0
	buffer_load_dwordx4 v157, s[24:27], s23 offen lds
	s_mov_b32 m0, s72
	s_nop 0
	buffer_load_dwordx4 v154, s[16:19], s22 offen lds
	s_mov_b32 m0, s78
	s_nop 0
	buffer_load_dwordx4 v156, s[16:19], s22 offen lds
	s_waitcnt vmcnt(8)
	s_waitcnt lgkmcnt(0)
	s_barrier
	s_setprio 1
	s_waitcnt lgkmcnt(7)
	v_mfma_f32_16x16x32_bf16 v[60:63], v[128:131], v[176:179], v[60:63]
	v_mfma_f32_16x16x32_bf16 v[56:59], v[136:139], v[176:179], v[56:59]
	s_waitcnt lgkmcnt(5)
	v_mfma_f32_16x16x32_bf16 v[44:47], v[128:131], v[184:187], v[44:47]
	v_mfma_f32_16x16x32_bf16 v[40:43], v[136:139], v[184:187], v[40:43]
	s_waitcnt lgkmcnt(3)
	v_mfma_f32_16x16x32_bf16 v[28:31], v[128:131], v[192:195], v[28:31]
	v_mfma_f32_16x16x32_bf16 v[24:27], v[136:139], v[192:195], v[24:27]
	s_waitcnt lgkmcnt(1)
	v_mfma_f32_16x16x32_bf16 v[12:15], v[128:131], v[200:203], v[12:15]
	v_mfma_f32_16x16x32_bf16 v[8:11], v[136:139], v[200:203], v[8:11]
	v_mfma_f32_16x16x32_bf16 v[60:63], v[132:135], v[180:183], v[60:63]
	v_mfma_f32_16x16x32_bf16 v[56:59], v[140:143], v[180:183], v[56:59]
	v_mfma_f32_16x16x32_bf16 v[44:47], v[132:135], v[188:191], v[44:47]
	v_mfma_f32_16x16x32_bf16 v[40:43], v[140:143], v[188:191], v[40:43]
	v_mfma_f32_16x16x32_bf16 v[28:31], v[132:135], v[196:199], v[28:31]
	v_mfma_f32_16x16x32_bf16 v[24:27], v[140:143], v[196:199], v[24:27]
	s_waitcnt lgkmcnt(0)
	v_mfma_f32_16x16x32_bf16 v[12:15], v[132:135], v[204:207], v[12:15]
	v_mfma_f32_16x16x32_bf16 v[8:11], v[140:143], v[204:207], v[8:11]
	s_setprio 0
	s_setprio 1
	v_mfma_f32_16x16x32_bf16 v[52:55], v[148:151], v[176:179], v[52:55]
	v_mfma_f32_16x16x32_bf16 v[48:51], v[168:171], v[176:179], v[48:51]
	v_mfma_f32_16x16x32_bf16 v[36:39], v[148:151], v[184:187], v[36:39]
	v_mfma_f32_16x16x32_bf16 v[32:35], v[168:171], v[184:187], v[32:35]
	v_mfma_f32_16x16x32_bf16 v[20:23], v[148:151], v[192:195], v[20:23]
	v_mfma_f32_16x16x32_bf16 v[16:19], v[168:171], v[192:195], v[16:19]
	v_mfma_f32_16x16x32_bf16 v[4:7], v[148:151], v[200:203], v[4:7]
	v_mfma_f32_16x16x32_bf16 v[0:3], v[168:171], v[200:203], v[0:3]
	v_mfma_f32_16x16x32_bf16 v[52:55], v[164:167], v[180:183], v[52:55]
	v_mfma_f32_16x16x32_bf16 v[48:51], v[172:175], v[180:183], v[48:51]
	v_mfma_f32_16x16x32_bf16 v[36:39], v[164:167], v[188:191], v[36:39]
	v_mfma_f32_16x16x32_bf16 v[32:35], v[172:175], v[188:191], v[32:35]
	v_mfma_f32_16x16x32_bf16 v[20:23], v[164:167], v[196:199], v[20:23]
	v_mfma_f32_16x16x32_bf16 v[16:19], v[172:175], v[196:199], v[16:19]
	v_mfma_f32_16x16x32_bf16 v[4:7], v[164:167], v[204:207], v[4:7]
	v_mfma_f32_16x16x32_bf16 v[0:3], v[172:175], v[204:207], v[0:3]
	s_setprio 0
	s_add_i32 s77, s77, 2
	s_addk_i32 s5, 0x100
	s_addk_i32 s76, 0x100
	s_cmp_ge_i32 s77, s86
	s_barrier
	s_cbranch_scc0 .LBB0_953
	v_readlane_b32 s44, v254, 52
	v_readlane_b32 s45, v254, 53

.LBB0_973:
	ds_read_b128 v[104:107], v196
	ds_read_b128 v[108:111], v196 offset:1024
	ds_read_b128 v[112:115], v196 offset:2048
	ds_read_b128 v[124:127], v196 offset:3072
	ds_read_b128 v[128:131], v197
	ds_read_b128 v[132:135], v197 offset:1024
	ds_read_b128 v[136:139], v197 offset:2048
	ds_read_b128 v[156:159], v197 offset:3072
	s_add_i32 s22, s5, 0xfff00080
	s_cmp_eq_u32 s46, s66
	s_cselect_b32 s44, s71, s22
	s_cselect_b32 s23, s4, s65
	s_add_i32 s22, s44, 0x80
	s_mov_b32 m0, s47
	ds_read_b128 v[160:163], v198
	ds_read_b128 v[164:167], v198 offset:1024
	ds_read_b128 v[168:171], v198 offset:2048
	ds_read_b128 v[172:175], v198 offset:3072
	ds_read_b128 v[176:179], v198 offset:4096
	ds_read_b128 v[184:187], v198 offset:5120
	ds_read_b128 v[188:191], v198 offset:6144
	ds_read_b128 v[202:205], v198 offset:7168
	buffer_load_dwordx4 v192, s[84:87], s5 offen lds
	s_mov_b32 m0, s49
	s_nop 0
	buffer_load_dwordx4 v194, s[84:87], s5 offen lds
	s_waitcnt vmcnt(8)
	s_waitcnt lgkmcnt(0)
	s_barrier
	s_setprio 1
	s_waitcnt lgkmcnt(7)
	v_mfma_f32_16x16x32_bf16 v[148:151], v[104:107], v[160:163], v[148:151]
	v_mfma_f32_16x16x32_bf16 v[144:147], v[112:115], v[160:163], v[144:147]
	s_waitcnt lgkmcnt(5)
	v_mfma_f32_16x16x32_bf16 v[120:123], v[104:107], v[168:171], v[120:123]
	v_mfma_f32_16x16x32_bf16 v[100:103], v[112:115], v[168:171], v[100:103]
	s_waitcnt lgkmcnt(3)
	v_mfma_f32_16x16x32_bf16 v[92:95], v[104:107], v[176:179], v[92:95]
	v_mfma_f32_16x16x32_bf16 v[84:87], v[112:115], v[176:179], v[84:87]
	s_waitcnt lgkmcnt(1)
	v_mfma_f32_16x16x32_bf16 v[76:79], v[104:107], v[188:191], v[76:79]
	v_mfma_f32_16x16x32_bf16 v[68:71], v[112:115], v[188:191], v[68:71]
	v_mfma_f32_16x16x32_bf16 v[148:151], v[108:111], v[164:167], v[148:151]
	v_mfma_f32_16x16x32_bf16 v[144:147], v[124:127], v[164:167], v[144:147]
	v_mfma_f32_16x16x32_bf16 v[120:123], v[108:111], v[172:175], v[120:123]
	v_mfma_f32_16x16x32_bf16 v[100:103], v[124:127], v[172:175], v[100:103]
	v_mfma_f32_16x16x32_bf16 v[92:95], v[108:111], v[184:187], v[92:95]
	v_mfma_f32_16x16x32_bf16 v[84:87], v[124:127], v[184:187], v[84:87]
	s_waitcnt lgkmcnt(0)
	v_mfma_f32_16x16x32_bf16 v[76:79], v[108:111], v[202:205], v[76:79]
	v_mfma_f32_16x16x32_bf16 v[68:71], v[124:127], v[202:205], v[68:71]
	s_setprio 0
	s_setprio 1
	v_mfma_f32_16x16x32_bf16 v[152:155], v[128:131], v[160:163], v[152:155]
	v_mfma_f32_16x16x32_bf16 v[140:143], v[136:139], v[160:163], v[140:143]
	v_mfma_f32_16x16x32_bf16 v[116:119], v[128:131], v[168:171], v[116:119]
	v_mfma_f32_16x16x32_bf16 v[96:99], v[136:139], v[168:171], v[96:99]
	v_mfma_f32_16x16x32_bf16 v[88:91], v[128:131], v[176:179], v[88:91]
	v_mfma_f32_16x16x32_bf16 v[80:83], v[136:139], v[176:179], v[80:83]
	v_mfma_f32_16x16x32_bf16 v[72:75], v[128:131], v[188:191], v[72:75]
	v_mfma_f32_16x16x32_bf16 v[64:67], v[136:139], v[188:191], v[64:67]
	v_mfma_f32_16x16x32_bf16 v[152:155], v[132:135], v[164:167], v[152:155]
	v_mfma_f32_16x16x32_bf16 v[140:143], v[156:159], v[164:167], v[140:143]
	v_mfma_f32_16x16x32_bf16 v[116:119], v[132:135], v[172:175], v[116:119]
	v_mfma_f32_16x16x32_bf16 v[96:99], v[156:159], v[172:175], v[96:99]
	v_mfma_f32_16x16x32_bf16 v[88:91], v[132:135], v[184:187], v[88:91]
	v_mfma_f32_16x16x32_bf16 v[80:83], v[156:159], v[184:187], v[80:83]
	v_mfma_f32_16x16x32_bf16 v[72:75], v[132:135], v[202:205], v[72:75]
	v_mfma_f32_16x16x32_bf16 v[64:67], v[156:159], v[202:205], v[64:67]
	s_setprio 0
	s_barrier
	s_mov_b32 m0, s18
	s_mov_b32 s94, s86
	s_mov_b32 s95, s87
	ds_read_b128 v[160:163], v198 offset:16384
	ds_read_b128 v[164:167], v198 offset:17408
	ds_read_b128 v[168:171], v198 offset:18432
	ds_read_b128 v[172:175], v198 offset:19456
	ds_read_b128 v[176:179], v198 offset:20480
	ds_read_b128 v[184:187], v198 offset:21504
	ds_read_b128 v[188:191], v198 offset:22528
	ds_read_b128 v[202:205], v198 offset:23552
	buffer_load_dwordx4 v193, s[92:95], s23 offen lds
	s_mov_b32 m0, s19
	s_add_i32 s45, s23, 0x10000
	buffer_load_dwordx4 v195, s[92:95], s23 offen lds
	s_mov_b32 m0, s20
	s_nop 0
	buffer_load_dwordx4 v193, s[92:95], s45 offen lds
	s_mov_b32 m0, s21
	s_nop 0
	buffer_load_dwordx4 v195, s[92:95], s45 offen lds
	s_mov_b32 m0, s15
	s_nop 0
	buffer_load_dwordx4 v192, s[84:87], s44 offen lds
	s_mov_b32 m0, s24
	s_nop 0
	buffer_load_dwordx4 v194, s[84:87], s44 offen lds
	s_waitcnt vmcnt(8)
	s_waitcnt lgkmcnt(0)
	s_barrier
	s_setprio 1
	s_waitcnt lgkmcnt(7)
	v_mfma_f32_16x16x32_bf16 v[60:63], v[104:107], v[160:163], v[60:63]
	v_mfma_f32_16x16x32_bf16 v[52:55], v[112:115], v[160:163], v[52:55]
	s_waitcnt lgkmcnt(5)
	v_mfma_f32_16x16x32_bf16 v[44:47], v[104:107], v[168:171], v[44:47]
	v_mfma_f32_16x16x32_bf16 v[36:39], v[112:115], v[168:171], v[36:39]
	s_waitcnt lgkmcnt(3)
	v_mfma_f32_16x16x32_bf16 v[28:31], v[104:107], v[176:179], v[28:31]
	v_mfma_f32_16x16x32_bf16 v[20:23], v[112:115], v[176:179], v[20:23]
	s_waitcnt lgkmcnt(1)
	v_mfma_f32_16x16x32_bf16 v[12:15], v[104:107], v[188:191], v[12:15]
	v_mfma_f32_16x16x32_bf16 v[4:7], v[112:115], v[188:191], v[4:7]
	v_mfma_f32_16x16x32_bf16 v[60:63], v[108:111], v[164:167], v[60:63]
	v_mfma_f32_16x16x32_bf16 v[52:55], v[124:127], v[164:167], v[52:55]
	v_mfma_f32_16x16x32_bf16 v[44:47], v[108:111], v[172:175], v[44:47]
	v_mfma_f32_16x16x32_bf16 v[36:39], v[124:127], v[172:175], v[36:39]
	v_mfma_f32_16x16x32_bf16 v[28:31], v[108:111], v[184:187], v[28:31]
	v_mfma_f32_16x16x32_bf16 v[20:23], v[124:127], v[184:187], v[20:23]
	s_waitcnt lgkmcnt(0)
	v_mfma_f32_16x16x32_bf16 v[12:15], v[108:111], v[202:205], v[12:15]
	v_mfma_f32_16x16x32_bf16 v[4:7], v[124:127], v[202:205], v[4:7]
	s_setprio 0
	s_setprio 1
	v_mfma_f32_16x16x32_bf16 v[56:59], v[128:131], v[160:163], v[56:59]
	v_mfma_f32_16x16x32_bf16 v[48:51], v[136:139], v[160:163], v[48:51]
	v_mfma_f32_16x16x32_bf16 v[40:43], v[128:131], v[168:171], v[40:43]
	v_mfma_f32_16x16x32_bf16 v[32:35], v[136:139], v[168:171], v[32:35]
	v_mfma_f32_16x16x32_bf16 v[24:27], v[128:131], v[176:179], v[24:27]
	v_mfma_f32_16x16x32_bf16 v[16:19], v[136:139], v[176:179], v[16:19]
	v_mfma_f32_16x16x32_bf16 v[8:11], v[128:131], v[188:191], v[8:11]
	v_mfma_f32_16x16x32_bf16 v[0:3], v[136:139], v[188:191], v[0:3]
	v_mfma_f32_16x16x32_bf16 v[56:59], v[132:135], v[164:167], v[56:59]
	v_mfma_f32_16x16x32_bf16 v[48:51], v[156:159], v[164:167], v[48:51]
	v_mfma_f32_16x16x32_bf16 v[40:43], v[132:135], v[172:175], v[40:43]
	v_mfma_f32_16x16x32_bf16 v[32:35], v[156:159], v[172:175], v[32:35]
	v_mfma_f32_16x16x32_bf16 v[24:27], v[132:135], v[184:187], v[24:27]
	v_mfma_f32_16x16x32_bf16 v[16:19], v[156:159], v[184:187], v[16:19]
	v_mfma_f32_16x16x32_bf16 v[8:11], v[132:135], v[202:205], v[8:11]
	v_mfma_f32_16x16x32_bf16 v[0:3], v[156:159], v[202:205], v[0:3]
	s_setprio 0
	s_barrier
	ds_read_b128 v[104:107], v199
	ds_read_b128 v[108:111], v199 offset:1024
	ds_read_b128 v[112:115], v199 offset:2048
	ds_read_b128 v[124:127], v199 offset:3072
	ds_read_b128 v[128:131], v200
	ds_read_b128 v[132:135], v200 offset:1024
	ds_read_b128 v[136:139], v200 offset:2048
	ds_read_b128 v[156:159], v200 offset:3072
	s_add_i32 s44, s44, 0x100000
	s_mov_b32 m0, s25
	ds_read_b128 v[160:163], v198 offset:32768
	ds_read_b128 v[164:167], v198 offset:33792
	ds_read_b128 v[168:171], v198 offset:34816
	ds_read_b128 v[172:175], v198 offset:35840
	ds_read_b128 v[176:179], v198 offset:36864
	ds_read_b128 v[184:187], v198 offset:37888
	ds_read_b128 v[188:191], v198 offset:38912
	ds_read_b128 v[202:205], v198 offset:39936
	buffer_load_dwordx4 v192, s[84:87], s44 offen lds
	s_mov_b32 m0, s26
	s_nop 0
	buffer_load_dwordx4 v194, s[84:87], s44 offen lds
	s_waitcnt vmcnt(8)
	s_waitcnt lgkmcnt(0)
	s_barrier
	s_setprio 1
	s_waitcnt lgkmcnt(7)
	v_mfma_f32_16x16x32_bf16 v[148:151], v[104:107], v[160:163], v[148:151]
	v_mfma_f32_16x16x32_bf16 v[144:147], v[112:115], v[160:163], v[144:147]
	s_waitcnt lgkmcnt(5)
	v_mfma_f32_16x16x32_bf16 v[120:123], v[104:107], v[168:171], v[120:123]
	v_mfma_f32_16x16x32_bf16 v[100:103], v[112:115], v[168:171], v[100:103]
	s_waitcnt lgkmcnt(3)
	v_mfma_f32_16x16x32_bf16 v[92:95], v[104:107], v[176:179], v[92:95]
	v_mfma_f32_16x16x32_bf16 v[84:87], v[112:115], v[176:179], v[84:87]
	s_waitcnt lgkmcnt(1)
	v_mfma_f32_16x16x32_bf16 v[76:79], v[104:107], v[188:191], v[76:79]
	v_mfma_f32_16x16x32_bf16 v[68:71], v[112:115], v[188:191], v[68:71]
	v_mfma_f32_16x16x32_bf16 v[148:151], v[108:111], v[164:167], v[148:151]
	v_mfma_f32_16x16x32_bf16 v[144:147], v[124:127], v[164:167], v[144:147]
	v_mfma_f32_16x16x32_bf16 v[120:123], v[108:111], v[172:175], v[120:123]
	v_mfma_f32_16x16x32_bf16 v[100:103], v[124:127], v[172:175], v[100:103]
	v_mfma_f32_16x16x32_bf16 v[92:95], v[108:111], v[184:187], v[92:95]
	v_mfma_f32_16x16x32_bf16 v[84:87], v[124:127], v[184:187], v[84:87]
	s_waitcnt lgkmcnt(0)
	v_mfma_f32_16x16x32_bf16 v[76:79], v[108:111], v[202:205], v[76:79]
	v_mfma_f32_16x16x32_bf16 v[68:71], v[124:127], v[202:205], v[68:71]
	s_setprio 0
	s_setprio 1
	v_mfma_f32_16x16x32_bf16 v[152:155], v[128:131], v[160:163], v[152:155]
	v_mfma_f32_16x16x32_bf16 v[140:143], v[136:139], v[160:163], v[140:143]
	v_mfma_f32_16x16x32_bf16 v[116:119], v[128:131], v[168:171], v[116:119]
	v_mfma_f32_16x16x32_bf16 v[96:99], v[136:139], v[168:171], v[96:99]
	v_mfma_f32_16x16x32_bf16 v[88:91], v[128:131], v[176:179], v[88:91]
	v_mfma_f32_16x16x32_bf16 v[80:83], v[136:139], v[176:179], v[80:83]
	v_mfma_f32_16x16x32_bf16 v[72:75], v[128:131], v[188:191], v[72:75]
	v_mfma_f32_16x16x32_bf16 v[64:67], v[136:139], v[188:191], v[64:67]
	v_mfma_f32_16x16x32_bf16 v[152:155], v[132:135], v[164:167], v[152:155]
	v_mfma_f32_16x16x32_bf16 v[140:143], v[156:159], v[164:167], v[140:143]
	v_mfma_f32_16x16x32_bf16 v[116:119], v[132:135], v[172:175], v[116:119]
	v_mfma_f32_16x16x32_bf16 v[96:99], v[156:159], v[172:175], v[96:99]
	v_mfma_f32_16x16x32_bf16 v[88:91], v[132:135], v[184:187], v[88:91]
	v_mfma_f32_16x16x32_bf16 v[80:83], v[156:159], v[184:187], v[80:83]
	v_mfma_f32_16x16x32_bf16 v[72:75], v[132:135], v[202:205], v[72:75]
	v_mfma_f32_16x16x32_bf16 v[64:67], v[156:159], v[202:205], v[64:67]
	s_setprio 0
	s_barrier
	s_mov_b32 m0, s30
	s_or_b32 s44, s23, 0x80
	ds_read_b128 v[160:163], v198 offset:49152
	ds_read_b128 v[164:167], v198 offset:50176
	ds_read_b128 v[168:171], v198 offset:51200
	ds_read_b128 v[172:175], v198 offset:52224
	ds_read_b128 v[176:179], v198 offset:53248
	ds_read_b128 v[184:187], v198 offset:54272
	ds_read_b128 v[188:191], v198 offset:55296
	ds_read_b128 v[202:205], v198 offset:56320
	buffer_load_dwordx4 v193, s[92:95], s44 offen lds
	s_mov_b32 m0, s31
	s_add_i32 s23, s23, 0x10080
	buffer_load_dwordx4 v195, s[92:95], s44 offen lds
	s_mov_b32 m0, s41
	s_nop 0
	buffer_load_dwordx4 v193, s[92:95], s23 offen lds
	s_mov_b32 m0, s42
	s_nop 0
	buffer_load_dwordx4 v195, s[92:95], s23 offen lds
	s_mov_b32 m0, s38
	s_nop 0
	buffer_load_dwordx4 v192, s[84:87], s22 offen lds
	s_mov_b32 m0, s39
	s_nop 0
	buffer_load_dwordx4 v194, s[84:87], s22 offen lds
	s_waitcnt vmcnt(8)
	s_waitcnt lgkmcnt(0)
	s_barrier
	s_setprio 1
	s_waitcnt lgkmcnt(7)
	v_mfma_f32_16x16x32_bf16 v[60:63], v[104:107], v[160:163], v[60:63]
	v_mfma_f32_16x16x32_bf16 v[52:55], v[112:115], v[160:163], v[52:55]
	s_waitcnt lgkmcnt(5)
	v_mfma_f32_16x16x32_bf16 v[44:47], v[104:107], v[168:171], v[44:47]
	v_mfma_f32_16x16x32_bf16 v[36:39], v[112:115], v[168:171], v[36:39]
	s_waitcnt lgkmcnt(3)
	v_mfma_f32_16x16x32_bf16 v[28:31], v[104:107], v[176:179], v[28:31]
	v_mfma_f32_16x16x32_bf16 v[20:23], v[112:115], v[176:179], v[20:23]
	s_waitcnt lgkmcnt(1)
	v_mfma_f32_16x16x32_bf16 v[12:15], v[104:107], v[188:191], v[12:15]
	v_mfma_f32_16x16x32_bf16 v[4:7], v[112:115], v[188:191], v[4:7]
	v_mfma_f32_16x16x32_bf16 v[60:63], v[108:111], v[164:167], v[60:63]
	v_mfma_f32_16x16x32_bf16 v[52:55], v[124:127], v[164:167], v[52:55]
	v_mfma_f32_16x16x32_bf16 v[44:47], v[108:111], v[172:175], v[44:47]
	v_mfma_f32_16x16x32_bf16 v[36:39], v[124:127], v[172:175], v[36:39]
	v_mfma_f32_16x16x32_bf16 v[28:31], v[108:111], v[184:187], v[28:31]
	v_mfma_f32_16x16x32_bf16 v[20:23], v[124:127], v[184:187], v[20:23]
	s_waitcnt lgkmcnt(0)
	v_mfma_f32_16x16x32_bf16 v[12:15], v[108:111], v[202:205], v[12:15]
	v_mfma_f32_16x16x32_bf16 v[4:7], v[124:127], v[202:205], v[4:7]
	s_setprio 0
	s_setprio 1
	v_mfma_f32_16x16x32_bf16 v[56:59], v[128:131], v[160:163], v[56:59]
	v_mfma_f32_16x16x32_bf16 v[48:51], v[136:139], v[160:163], v[48:51]
	v_mfma_f32_16x16x32_bf16 v[40:43], v[128:131], v[168:171], v[40:43]
	v_mfma_f32_16x16x32_bf16 v[32:35], v[136:139], v[168:171], v[32:35]
	v_mfma_f32_16x16x32_bf16 v[24:27], v[128:131], v[176:179], v[24:27]
	v_mfma_f32_16x16x32_bf16 v[16:19], v[136:139], v[176:179], v[16:19]
	v_mfma_f32_16x16x32_bf16 v[8:11], v[128:131], v[188:191], v[8:11]
	v_mfma_f32_16x16x32_bf16 v[0:3], v[136:139], v[188:191], v[0:3]
	v_mfma_f32_16x16x32_bf16 v[56:59], v[132:135], v[164:167], v[56:59]
	v_mfma_f32_16x16x32_bf16 v[48:51], v[156:159], v[164:167], v[48:51]
	v_mfma_f32_16x16x32_bf16 v[40:43], v[132:135], v[172:175], v[40:43]
	v_mfma_f32_16x16x32_bf16 v[32:35], v[156:159], v[172:175], v[32:35]
	v_mfma_f32_16x16x32_bf16 v[24:27], v[132:135], v[184:187], v[24:27]
	v_mfma_f32_16x16x32_bf16 v[16:19], v[156:159], v[184:187], v[16:19]
	v_mfma_f32_16x16x32_bf16 v[8:11], v[132:135], v[202:205], v[8:11]
	v_mfma_f32_16x16x32_bf16 v[0:3], v[156:159], v[202:205], v[0:3]
	s_setprio 0
	s_add_i32 s66, s66, 2
	s_addk_i32 s5, 0x100
	s_addk_i32 s65, 0x100
	s_cmp_ge_i32 s66, s43
	s_barrier
	s_cbranch_scc0 .LBB0_973
	v_readlane_b32 s95, v254, 22
	v_readlane_b32 s44, v254, 52
	v_readlane_b32 s45, v254, 53

.LBB0_1138:
	ds_read_b128 v[128:131], v180
	ds_read_b128 v[132:135], v180 offset:1024
	ds_read_b128 v[136:139], v180 offset:2048
	ds_read_b128 v[140:143], v180 offset:3072
	ds_read_b128 v[144:147], v181
	ds_read_b128 v[148:151], v181 offset:1024
	ds_read_b128 v[152:155], v181 offset:2048
	ds_read_b128 v[160:163], v181 offset:3072
	s_add_i32 s14, s68, 0xfff80080
	s_cmp_eq_u32 s67, s70
	s_cselect_b32 s71, s0, s14
	s_cselect_b32 s23, s1, s69
	s_add_i32 s22, s71, 0x80
	s_mov_b32 m0, s51
	ds_read_b128 v[164:167], v182
	ds_read_b128 v[168:171], v182 offset:1024
	ds_read_b128 v[172:175], v182 offset:2048
	ds_read_b128 v[186:189], v182 offset:3072
	ds_read_b128 v[190:193], v182 offset:4096
	ds_read_b128 v[194:197], v182 offset:5120
	ds_read_b128 v[198:201], v182 offset:6144
	ds_read_b128 v[202:205], v182 offset:7168
	buffer_load_dwordx4 v176, s[8:11], s68 offen lds
	s_mov_b32 m0, s52
	s_nop 0
	buffer_load_dwordx4 v178, s[8:11], s68 offen lds
	s_waitcnt vmcnt(8)
	s_waitcnt lgkmcnt(0)
	s_barrier
	s_setprio 1
	s_waitcnt lgkmcnt(7)
	v_mfma_f32_16x16x32_bf16 v[124:127], v[128:131], v[164:167], v[124:127]
	v_mfma_f32_16x16x32_bf16 v[120:123], v[136:139], v[164:167], v[120:123]
	s_waitcnt lgkmcnt(5)
	v_mfma_f32_16x16x32_bf16 v[108:111], v[128:131], v[172:175], v[108:111]
	v_mfma_f32_16x16x32_bf16 v[104:107], v[136:139], v[172:175], v[104:107]
	s_waitcnt lgkmcnt(3)
	v_mfma_f32_16x16x32_bf16 v[92:95], v[128:131], v[190:193], v[92:95]
	v_mfma_f32_16x16x32_bf16 v[88:91], v[136:139], v[190:193], v[88:91]
	s_waitcnt lgkmcnt(1)
	v_mfma_f32_16x16x32_bf16 v[76:79], v[128:131], v[198:201], v[76:79]
	v_mfma_f32_16x16x32_bf16 v[72:75], v[136:139], v[198:201], v[72:75]
	v_mfma_f32_16x16x32_bf16 v[124:127], v[132:135], v[168:171], v[124:127]
	v_mfma_f32_16x16x32_bf16 v[120:123], v[140:143], v[168:171], v[120:123]
	v_mfma_f32_16x16x32_bf16 v[108:111], v[132:135], v[186:189], v[108:111]
	v_mfma_f32_16x16x32_bf16 v[104:107], v[140:143], v[186:189], v[104:107]
	v_mfma_f32_16x16x32_bf16 v[92:95], v[132:135], v[194:197], v[92:95]
	v_mfma_f32_16x16x32_bf16 v[88:91], v[140:143], v[194:197], v[88:91]
	s_waitcnt lgkmcnt(0)
	v_mfma_f32_16x16x32_bf16 v[76:79], v[132:135], v[202:205], v[76:79]
	v_mfma_f32_16x16x32_bf16 v[72:75], v[140:143], v[202:205], v[72:75]
	s_setprio 0
	s_setprio 1
	v_mfma_f32_16x16x32_bf16 v[116:119], v[144:147], v[164:167], v[116:119]
	v_mfma_f32_16x16x32_bf16 v[112:115], v[152:155], v[164:167], v[112:115]
	v_mfma_f32_16x16x32_bf16 v[100:103], v[144:147], v[172:175], v[100:103]
	v_mfma_f32_16x16x32_bf16 v[96:99], v[152:155], v[172:175], v[96:99]
	v_mfma_f32_16x16x32_bf16 v[84:87], v[144:147], v[190:193], v[84:87]
	v_mfma_f32_16x16x32_bf16 v[80:83], v[152:155], v[190:193], v[80:83]
	v_mfma_f32_16x16x32_bf16 v[68:71], v[144:147], v[198:201], v[68:71]
	v_mfma_f32_16x16x32_bf16 v[64:67], v[152:155], v[198:201], v[64:67]
	v_mfma_f32_16x16x32_bf16 v[116:119], v[148:151], v[168:171], v[116:119]
	v_mfma_f32_16x16x32_bf16 v[112:115], v[160:163], v[168:171], v[112:115]
	v_mfma_f32_16x16x32_bf16 v[100:103], v[148:151], v[186:189], v[100:103]
	v_mfma_f32_16x16x32_bf16 v[96:99], v[160:163], v[186:189], v[96:99]
	v_mfma_f32_16x16x32_bf16 v[84:87], v[148:151], v[194:197], v[84:87]
	v_mfma_f32_16x16x32_bf16 v[80:83], v[160:163], v[194:197], v[80:83]
	v_mfma_f32_16x16x32_bf16 v[68:71], v[148:151], v[202:205], v[68:71]
	v_mfma_f32_16x16x32_bf16 v[64:67], v[160:163], v[202:205], v[64:67]
	s_setprio 0
	s_barrier
	s_mov_b32 m0, s20
	s_mov_b32 s14, s10
	s_mov_b32 s15, s11
	ds_read_b128 v[164:167], v182 offset:16384
	ds_read_b128 v[168:171], v182 offset:17408
	ds_read_b128 v[172:175], v182 offset:18432
	ds_read_b128 v[186:189], v182 offset:19456
	ds_read_b128 v[190:193], v182 offset:20480
	ds_read_b128 v[194:197], v182 offset:21504
	ds_read_b128 v[198:201], v182 offset:22528
	ds_read_b128 v[202:205], v182 offset:23552
	buffer_load_dwordx4 v177, s[12:15], s23 offen lds
	s_mov_b32 m0, s21
	s_add_i32 s73, s23, 0x80000
	buffer_load_dwordx4 v179, s[12:15], s23 offen lds
	s_mov_b32 m0, s29
	s_nop 0
	buffer_load_dwordx4 v177, s[12:15], s73 offen lds
	s_mov_b32 m0, s30
	s_nop 0
	buffer_load_dwordx4 v179, s[12:15], s73 offen lds
	s_mov_b32 m0, s3
	s_nop 0
	buffer_load_dwordx4 v176, s[8:11], s71 offen lds
	s_mov_b32 m0, s31
	s_nop 0
	buffer_load_dwordx4 v178, s[8:11], s71 offen lds
	s_waitcnt vmcnt(8)
	s_waitcnt lgkmcnt(0)
	s_barrier
	s_setprio 1
	s_waitcnt lgkmcnt(7)
	v_mfma_f32_16x16x32_bf16 v[60:63], v[128:131], v[164:167], v[60:63]
	v_mfma_f32_16x16x32_bf16 v[56:59], v[136:139], v[164:167], v[56:59]
	s_waitcnt lgkmcnt(5)
	v_mfma_f32_16x16x32_bf16 v[44:47], v[128:131], v[172:175], v[44:47]
	v_mfma_f32_16x16x32_bf16 v[40:43], v[136:139], v[172:175], v[40:43]
	s_waitcnt lgkmcnt(3)
	v_mfma_f32_16x16x32_bf16 v[28:31], v[128:131], v[190:193], v[28:31]
	v_mfma_f32_16x16x32_bf16 v[24:27], v[136:139], v[190:193], v[24:27]
	s_waitcnt lgkmcnt(1)
	v_mfma_f32_16x16x32_bf16 v[12:15], v[128:131], v[198:201], v[12:15]
	v_mfma_f32_16x16x32_bf16 v[8:11], v[136:139], v[198:201], v[8:11]
	v_mfma_f32_16x16x32_bf16 v[60:63], v[132:135], v[168:171], v[60:63]
	v_mfma_f32_16x16x32_bf16 v[56:59], v[140:143], v[168:171], v[56:59]
	v_mfma_f32_16x16x32_bf16 v[44:47], v[132:135], v[186:189], v[44:47]
	v_mfma_f32_16x16x32_bf16 v[40:43], v[140:143], v[186:189], v[40:43]
	v_mfma_f32_16x16x32_bf16 v[28:31], v[132:135], v[194:197], v[28:31]
	v_mfma_f32_16x16x32_bf16 v[24:27], v[140:143], v[194:197], v[24:27]
	s_waitcnt lgkmcnt(0)
	v_mfma_f32_16x16x32_bf16 v[12:15], v[132:135], v[202:205], v[12:15]
	v_mfma_f32_16x16x32_bf16 v[8:11], v[140:143], v[202:205], v[8:11]
	s_setprio 0
	s_setprio 1
	v_mfma_f32_16x16x32_bf16 v[52:55], v[144:147], v[164:167], v[52:55]
	v_mfma_f32_16x16x32_bf16 v[48:51], v[152:155], v[164:167], v[48:51]
	v_mfma_f32_16x16x32_bf16 v[36:39], v[144:147], v[172:175], v[36:39]
	v_mfma_f32_16x16x32_bf16 v[32:35], v[152:155], v[172:175], v[32:35]
	v_mfma_f32_16x16x32_bf16 v[20:23], v[144:147], v[190:193], v[20:23]
	v_mfma_f32_16x16x32_bf16 v[16:19], v[152:155], v[190:193], v[16:19]
	v_mfma_f32_16x16x32_bf16 v[4:7], v[144:147], v[198:201], v[4:7]
	v_mfma_f32_16x16x32_bf16 v[0:3], v[152:155], v[198:201], v[0:3]
	v_mfma_f32_16x16x32_bf16 v[52:55], v[148:151], v[168:171], v[52:55]
	v_mfma_f32_16x16x32_bf16 v[48:51], v[160:163], v[168:171], v[48:51]
	v_mfma_f32_16x16x32_bf16 v[36:39], v[148:151], v[186:189], v[36:39]
	v_mfma_f32_16x16x32_bf16 v[32:35], v[160:163], v[186:189], v[32:35]
	v_mfma_f32_16x16x32_bf16 v[20:23], v[148:151], v[194:197], v[20:23]
	v_mfma_f32_16x16x32_bf16 v[16:19], v[160:163], v[194:197], v[16:19]
	v_mfma_f32_16x16x32_bf16 v[4:7], v[148:151], v[202:205], v[4:7]
	v_mfma_f32_16x16x32_bf16 v[0:3], v[160:163], v[202:205], v[0:3]
	s_setprio 0
	s_barrier
	ds_read_b128 v[128:131], v183
	ds_read_b128 v[132:135], v183 offset:1024
	ds_read_b128 v[136:139], v183 offset:2048
	ds_read_b128 v[140:143], v183 offset:3072
	ds_read_b128 v[144:147], v184
	ds_read_b128 v[148:151], v184 offset:1024
	ds_read_b128 v[152:155], v184 offset:2048
	ds_read_b128 v[160:163], v184 offset:3072
	s_add_i32 s71, s71, 0x80000
	s_mov_b32 m0, s40
	ds_read_b128 v[164:167], v182 offset:32768
	ds_read_b128 v[168:171], v182 offset:33792
	ds_read_b128 v[172:175], v182 offset:34816
	ds_read_b128 v[186:189], v182 offset:35840
	ds_read_b128 v[190:193], v182 offset:36864
	ds_read_b128 v[194:197], v182 offset:37888
	ds_read_b128 v[198:201], v182 offset:38912
	ds_read_b128 v[202:205], v182 offset:39936
	buffer_load_dwordx4 v176, s[8:11], s71 offen lds
	s_mov_b32 m0, s41
	s_nop 0
	buffer_load_dwordx4 v178, s[8:11], s71 offen lds
	s_waitcnt vmcnt(8)
	s_waitcnt lgkmcnt(0)
	s_barrier
	s_setprio 1
	s_waitcnt lgkmcnt(7)
	v_mfma_f32_16x16x32_bf16 v[124:127], v[128:131], v[164:167], v[124:127]
	v_mfma_f32_16x16x32_bf16 v[120:123], v[136:139], v[164:167], v[120:123]
	s_waitcnt lgkmcnt(5)
	v_mfma_f32_16x16x32_bf16 v[108:111], v[128:131], v[172:175], v[108:111]
	v_mfma_f32_16x16x32_bf16 v[104:107], v[136:139], v[172:175], v[104:107]
	s_waitcnt lgkmcnt(3)
	v_mfma_f32_16x16x32_bf16 v[92:95], v[128:131], v[190:193], v[92:95]
	v_mfma_f32_16x16x32_bf16 v[88:91], v[136:139], v[190:193], v[88:91]
	s_waitcnt lgkmcnt(1)
	v_mfma_f32_16x16x32_bf16 v[76:79], v[128:131], v[198:201], v[76:79]
	v_mfma_f32_16x16x32_bf16 v[72:75], v[136:139], v[198:201], v[72:75]
	v_mfma_f32_16x16x32_bf16 v[124:127], v[132:135], v[168:171], v[124:127]
	v_mfma_f32_16x16x32_bf16 v[120:123], v[140:143], v[168:171], v[120:123]
	v_mfma_f32_16x16x32_bf16 v[108:111], v[132:135], v[186:189], v[108:111]
	v_mfma_f32_16x16x32_bf16 v[104:107], v[140:143], v[186:189], v[104:107]
	v_mfma_f32_16x16x32_bf16 v[92:95], v[132:135], v[194:197], v[92:95]
	v_mfma_f32_16x16x32_bf16 v[88:91], v[140:143], v[194:197], v[88:91]
	s_waitcnt lgkmcnt(0)
	v_mfma_f32_16x16x32_bf16 v[76:79], v[132:135], v[202:205], v[76:79]
	v_mfma_f32_16x16x32_bf16 v[72:75], v[140:143], v[202:205], v[72:75]
	s_setprio 0
	s_setprio 1
	v_mfma_f32_16x16x32_bf16 v[116:119], v[144:147], v[164:167], v[116:119]
	v_mfma_f32_16x16x32_bf16 v[112:115], v[152:155], v[164:167], v[112:115]
	v_mfma_f32_16x16x32_bf16 v[100:103], v[144:147], v[172:175], v[100:103]
	v_mfma_f32_16x16x32_bf16 v[96:99], v[152:155], v[172:175], v[96:99]
	v_mfma_f32_16x16x32_bf16 v[84:87], v[144:147], v[190:193], v[84:87]
	v_mfma_f32_16x16x32_bf16 v[80:83], v[152:155], v[190:193], v[80:83]
	v_mfma_f32_16x16x32_bf16 v[68:71], v[144:147], v[198:201], v[68:71]
	v_mfma_f32_16x16x32_bf16 v[64:67], v[152:155], v[198:201], v[64:67]
	v_mfma_f32_16x16x32_bf16 v[116:119], v[148:151], v[168:171], v[116:119]
	v_mfma_f32_16x16x32_bf16 v[112:115], v[160:163], v[168:171], v[112:115]
	v_mfma_f32_16x16x32_bf16 v[100:103], v[148:151], v[186:189], v[100:103]
	v_mfma_f32_16x16x32_bf16 v[96:99], v[160:163], v[186:189], v[96:99]
	v_mfma_f32_16x16x32_bf16 v[84:87], v[148:151], v[194:197], v[84:87]
	v_mfma_f32_16x16x32_bf16 v[80:83], v[160:163], v[194:197], v[80:83]
	v_mfma_f32_16x16x32_bf16 v[68:71], v[148:151], v[202:205], v[68:71]
	v_mfma_f32_16x16x32_bf16 v[64:67], v[160:163], v[202:205], v[64:67]
	s_setprio 0
	s_barrier
	s_mov_b32 m0, s42
	s_add_i32 s71, s23, 0x80
	ds_read_b128 v[164:167], v182 offset:49152
	ds_read_b128 v[168:171], v182 offset:50176
	ds_read_b128 v[172:175], v182 offset:51200
	ds_read_b128 v[186:189], v182 offset:52224
	ds_read_b128 v[190:193], v182 offset:53248
	ds_read_b128 v[194:197], v182 offset:54272
	ds_read_b128 v[198:201], v182 offset:55296
	ds_read_b128 v[202:205], v182 offset:56320
	buffer_load_dwordx4 v177, s[12:15], s71 offen lds
	s_mov_b32 m0, s43
	s_add_i32 s23, s23, 0x80080
	buffer_load_dwordx4 v179, s[12:15], s71 offen lds
	s_mov_b32 m0, s46
	s_nop 0
	buffer_load_dwordx4 v177, s[12:15], s23 offen lds
	s_mov_b32 m0, s47
	s_nop 0
	buffer_load_dwordx4 v179, s[12:15], s23 offen lds
	s_mov_b32 m0, s44
	s_nop 0
	buffer_load_dwordx4 v176, s[8:11], s22 offen lds
	s_mov_b32 m0, s45
	s_nop 0
	buffer_load_dwordx4 v178, s[8:11], s22 offen lds
	s_waitcnt vmcnt(8)
	s_waitcnt lgkmcnt(0)
	s_barrier
	s_setprio 1
	s_waitcnt lgkmcnt(7)
	v_mfma_f32_16x16x32_bf16 v[60:63], v[128:131], v[164:167], v[60:63]
	v_mfma_f32_16x16x32_bf16 v[56:59], v[136:139], v[164:167], v[56:59]
	s_waitcnt lgkmcnt(5)
	v_mfma_f32_16x16x32_bf16 v[44:47], v[128:131], v[172:175], v[44:47]
	v_mfma_f32_16x16x32_bf16 v[40:43], v[136:139], v[172:175], v[40:43]
	s_waitcnt lgkmcnt(3)
	v_mfma_f32_16x16x32_bf16 v[28:31], v[128:131], v[190:193], v[28:31]
	v_mfma_f32_16x16x32_bf16 v[24:27], v[136:139], v[190:193], v[24:27]
	s_waitcnt lgkmcnt(1)
	v_mfma_f32_16x16x32_bf16 v[12:15], v[128:131], v[198:201], v[12:15]
	v_mfma_f32_16x16x32_bf16 v[8:11], v[136:139], v[198:201], v[8:11]
	v_mfma_f32_16x16x32_bf16 v[60:63], v[132:135], v[168:171], v[60:63]
	v_mfma_f32_16x16x32_bf16 v[56:59], v[140:143], v[168:171], v[56:59]
	v_mfma_f32_16x16x32_bf16 v[44:47], v[132:135], v[186:189], v[44:47]
	v_mfma_f32_16x16x32_bf16 v[40:43], v[140:143], v[186:189], v[40:43]
	v_mfma_f32_16x16x32_bf16 v[28:31], v[132:135], v[194:197], v[28:31]
	v_mfma_f32_16x16x32_bf16 v[24:27], v[140:143], v[194:197], v[24:27]
	s_waitcnt lgkmcnt(0)
	v_mfma_f32_16x16x32_bf16 v[12:15], v[132:135], v[202:205], v[12:15]
	v_mfma_f32_16x16x32_bf16 v[8:11], v[140:143], v[202:205], v[8:11]
	s_setprio 0
	s_setprio 1
	v_mfma_f32_16x16x32_bf16 v[52:55], v[144:147], v[164:167], v[52:55]
	v_mfma_f32_16x16x32_bf16 v[48:51], v[152:155], v[164:167], v[48:51]
	v_mfma_f32_16x16x32_bf16 v[36:39], v[144:147], v[172:175], v[36:39]
	v_mfma_f32_16x16x32_bf16 v[32:35], v[152:155], v[172:175], v[32:35]
	v_mfma_f32_16x16x32_bf16 v[20:23], v[144:147], v[190:193], v[20:23]
	v_mfma_f32_16x16x32_bf16 v[16:19], v[152:155], v[190:193], v[16:19]
	v_mfma_f32_16x16x32_bf16 v[4:7], v[144:147], v[198:201], v[4:7]
	v_mfma_f32_16x16x32_bf16 v[0:3], v[152:155], v[198:201], v[0:3]
	v_mfma_f32_16x16x32_bf16 v[52:55], v[148:151], v[168:171], v[52:55]
	v_mfma_f32_16x16x32_bf16 v[48:51], v[160:163], v[168:171], v[48:51]
	v_mfma_f32_16x16x32_bf16 v[36:39], v[148:151], v[186:189], v[36:39]
	v_mfma_f32_16x16x32_bf16 v[32:35], v[160:163], v[186:189], v[32:35]
	v_mfma_f32_16x16x32_bf16 v[20:23], v[148:151], v[194:197], v[20:23]
	v_mfma_f32_16x16x32_bf16 v[16:19], v[160:163], v[194:197], v[16:19]
	v_mfma_f32_16x16x32_bf16 v[4:7], v[148:151], v[202:205], v[4:7]
	v_mfma_f32_16x16x32_bf16 v[0:3], v[160:163], v[202:205], v[0:3]
	s_setprio 0
	s_add_i32 s70, s70, 2
	s_addk_i32 s68, 0x100
	s_addk_i32 s69, 0x100
	s_cmp_ge_i32 s70, s39
	s_barrier
	s_cbranch_scc0 .LBB0_1138
	s_and_b64 vcc, exec, s[18:19]
	s_cbranch_vccz .LBB0_1141

.LBB0_1247:
	ds_read_b128 v[128:131], v185
	ds_read_b128 v[132:135], v185 offset:1024
	ds_read_b128 v[136:139], v185 offset:2048
	ds_read_b128 v[140:143], v185 offset:3072
	ds_read_b128 v[144:147], v186
	ds_read_b128 v[148:151], v186 offset:1024
	ds_read_b128 v[152:155], v186 offset:2048
	ds_read_b128 v[160:163], v186 offset:3072
	s_add_i32 s22, s59, 0xfff00080
	s_cmp_eq_u32 s58, s76
	s_cselect_b32 s77, s18, s22
	s_cselect_b32 s23, s19, s75
	s_add_i32 s22, s77, 0x80
	s_mov_b32 m0, s57
	ds_read_b128 v[164:167], v187
	ds_read_b128 v[168:171], v187 offset:1024
	ds_read_b128 v[172:175], v187 offset:2048
	ds_read_b128 v[176:179], v187 offset:3072
	ds_read_b128 v[190:193], v187 offset:4096
	ds_read_b128 v[194:197], v187 offset:5120
	ds_read_b128 v[198:201], v187 offset:6144
	ds_read_b128 v[202:205], v187 offset:7168
	buffer_load_dwordx4 v181, s[4:7], s59 offen lds
	s_mov_b32 m0, s54
	s_nop 0
	buffer_load_dwordx4 v183, s[4:7], s59 offen lds
	s_waitcnt vmcnt(8)
	s_waitcnt lgkmcnt(0)
	s_barrier
	s_setprio 1
	s_waitcnt lgkmcnt(7)
	v_mfma_f32_16x16x32_bf16 v[124:127], v[128:131], v[164:167], v[124:127]
	v_mfma_f32_16x16x32_bf16 v[120:123], v[136:139], v[164:167], v[120:123]
	s_waitcnt lgkmcnt(5)
	v_mfma_f32_16x16x32_bf16 v[108:111], v[128:131], v[172:175], v[108:111]
	v_mfma_f32_16x16x32_bf16 v[104:107], v[136:139], v[172:175], v[104:107]
	s_waitcnt lgkmcnt(3)
	v_mfma_f32_16x16x32_bf16 v[92:95], v[128:131], v[190:193], v[92:95]
	v_mfma_f32_16x16x32_bf16 v[88:91], v[136:139], v[190:193], v[88:91]
	s_waitcnt lgkmcnt(1)
	v_mfma_f32_16x16x32_bf16 v[76:79], v[128:131], v[198:201], v[76:79]
	v_mfma_f32_16x16x32_bf16 v[72:75], v[136:139], v[198:201], v[72:75]
	v_mfma_f32_16x16x32_bf16 v[124:127], v[132:135], v[168:171], v[124:127]
	v_mfma_f32_16x16x32_bf16 v[120:123], v[140:143], v[168:171], v[120:123]
	v_mfma_f32_16x16x32_bf16 v[108:111], v[132:135], v[176:179], v[108:111]
	v_mfma_f32_16x16x32_bf16 v[104:107], v[140:143], v[176:179], v[104:107]
	v_mfma_f32_16x16x32_bf16 v[92:95], v[132:135], v[194:197], v[92:95]
	v_mfma_f32_16x16x32_bf16 v[88:91], v[140:143], v[194:197], v[88:91]
	s_waitcnt lgkmcnt(0)
	v_mfma_f32_16x16x32_bf16 v[76:79], v[132:135], v[202:205], v[76:79]
	v_mfma_f32_16x16x32_bf16 v[72:75], v[140:143], v[202:205], v[72:75]
	s_setprio 0
	s_setprio 1
	v_mfma_f32_16x16x32_bf16 v[116:119], v[144:147], v[164:167], v[116:119]
	v_mfma_f32_16x16x32_bf16 v[112:115], v[152:155], v[164:167], v[112:115]
	v_mfma_f32_16x16x32_bf16 v[100:103], v[144:147], v[172:175], v[100:103]
	v_mfma_f32_16x16x32_bf16 v[96:99], v[152:155], v[172:175], v[96:99]
	v_mfma_f32_16x16x32_bf16 v[84:87], v[144:147], v[190:193], v[84:87]
	v_mfma_f32_16x16x32_bf16 v[80:83], v[152:155], v[190:193], v[80:83]
	v_mfma_f32_16x16x32_bf16 v[68:71], v[144:147], v[198:201], v[68:71]
	v_mfma_f32_16x16x32_bf16 v[64:67], v[152:155], v[198:201], v[64:67]
	v_mfma_f32_16x16x32_bf16 v[116:119], v[148:151], v[168:171], v[116:119]
	v_mfma_f32_16x16x32_bf16 v[112:115], v[160:163], v[168:171], v[112:115]
	v_mfma_f32_16x16x32_bf16 v[100:103], v[148:151], v[176:179], v[100:103]
	v_mfma_f32_16x16x32_bf16 v[96:99], v[160:163], v[176:179], v[96:99]
	v_mfma_f32_16x16x32_bf16 v[84:87], v[148:151], v[194:197], v[84:87]
	v_mfma_f32_16x16x32_bf16 v[80:83], v[160:163], v[194:197], v[80:83]
	v_mfma_f32_16x16x32_bf16 v[68:71], v[148:151], v[202:205], v[68:71]
	v_mfma_f32_16x16x32_bf16 v[64:67], v[160:163], v[202:205], v[64:67]
	s_setprio 0
	s_barrier
	s_mov_b32 m0, s26
	s_mov_b32 s82, s6
	s_mov_b32 s83, s7
	ds_read_b128 v[164:167], v187 offset:16384
	ds_read_b128 v[168:171], v187 offset:17408
	ds_read_b128 v[172:175], v187 offset:18432
	ds_read_b128 v[176:179], v187 offset:19456
	ds_read_b128 v[190:193], v187 offset:20480
	ds_read_b128 v[194:197], v187 offset:21504
	ds_read_b128 v[198:201], v187 offset:22528
	ds_read_b128 v[202:205], v187 offset:23552
	buffer_load_dwordx4 v182, s[80:83], s23 offen lds
	s_mov_b32 m0, s27
	s_add_i32 s78, s23, 0x100000
	buffer_load_dwordx4 v184, s[80:83], s23 offen lds
	s_mov_b32 m0, s29
	s_nop 0
	buffer_load_dwordx4 v182, s[80:83], s78 offen lds
	s_mov_b32 m0, s30
	s_nop 0
	buffer_load_dwordx4 v184, s[80:83], s78 offen lds
	s_mov_b32 m0, s21
	s_nop 0
	buffer_load_dwordx4 v181, s[4:7], s77 offen lds
	s_mov_b32 m0, s31
	s_nop 0
	buffer_load_dwordx4 v183, s[4:7], s77 offen lds
	s_waitcnt vmcnt(8)
	s_waitcnt lgkmcnt(0)
	s_barrier
	s_setprio 1
	s_waitcnt lgkmcnt(7)
	v_mfma_f32_16x16x32_bf16 v[60:63], v[128:131], v[164:167], v[60:63]
	v_mfma_f32_16x16x32_bf16 v[56:59], v[136:139], v[164:167], v[56:59]
	s_waitcnt lgkmcnt(5)
	v_mfma_f32_16x16x32_bf16 v[44:47], v[128:131], v[172:175], v[44:47]
	v_mfma_f32_16x16x32_bf16 v[40:43], v[136:139], v[172:175], v[40:43]
	s_waitcnt lgkmcnt(3)
	v_mfma_f32_16x16x32_bf16 v[28:31], v[128:131], v[190:193], v[28:31]
	v_mfma_f32_16x16x32_bf16 v[24:27], v[136:139], v[190:193], v[24:27]
	s_waitcnt lgkmcnt(1)
	v_mfma_f32_16x16x32_bf16 v[12:15], v[128:131], v[198:201], v[12:15]
	v_mfma_f32_16x16x32_bf16 v[8:11], v[136:139], v[198:201], v[8:11]
	v_mfma_f32_16x16x32_bf16 v[60:63], v[132:135], v[168:171], v[60:63]
	v_mfma_f32_16x16x32_bf16 v[56:59], v[140:143], v[168:171], v[56:59]
	v_mfma_f32_16x16x32_bf16 v[44:47], v[132:135], v[176:179], v[44:47]
	v_mfma_f32_16x16x32_bf16 v[40:43], v[140:143], v[176:179], v[40:43]
	v_mfma_f32_16x16x32_bf16 v[28:31], v[132:135], v[194:197], v[28:31]
	v_mfma_f32_16x16x32_bf16 v[24:27], v[140:143], v[194:197], v[24:27]
	s_waitcnt lgkmcnt(0)
	v_mfma_f32_16x16x32_bf16 v[12:15], v[132:135], v[202:205], v[12:15]
	v_mfma_f32_16x16x32_bf16 v[8:11], v[140:143], v[202:205], v[8:11]
	s_setprio 0
	s_setprio 1
	v_mfma_f32_16x16x32_bf16 v[52:55], v[144:147], v[164:167], v[52:55]
	v_mfma_f32_16x16x32_bf16 v[48:51], v[152:155], v[164:167], v[48:51]
	v_mfma_f32_16x16x32_bf16 v[36:39], v[144:147], v[172:175], v[36:39]
	v_mfma_f32_16x16x32_bf16 v[32:35], v[152:155], v[172:175], v[32:35]
	v_mfma_f32_16x16x32_bf16 v[20:23], v[144:147], v[190:193], v[20:23]
	v_mfma_f32_16x16x32_bf16 v[16:19], v[152:155], v[190:193], v[16:19]
	v_mfma_f32_16x16x32_bf16 v[4:7], v[144:147], v[198:201], v[4:7]
	v_mfma_f32_16x16x32_bf16 v[0:3], v[152:155], v[198:201], v[0:3]
	v_mfma_f32_16x16x32_bf16 v[52:55], v[148:151], v[168:171], v[52:55]
	v_mfma_f32_16x16x32_bf16 v[48:51], v[160:163], v[168:171], v[48:51]
	v_mfma_f32_16x16x32_bf16 v[36:39], v[148:151], v[176:179], v[36:39]
	v_mfma_f32_16x16x32_bf16 v[32:35], v[160:163], v[176:179], v[32:35]
	v_mfma_f32_16x16x32_bf16 v[20:23], v[148:151], v[194:197], v[20:23]
	v_mfma_f32_16x16x32_bf16 v[16:19], v[160:163], v[194:197], v[16:19]
	v_mfma_f32_16x16x32_bf16 v[4:7], v[148:151], v[202:205], v[4:7]
	v_mfma_f32_16x16x32_bf16 v[0:3], v[160:163], v[202:205], v[0:3]
	s_setprio 0
	s_barrier
	ds_read_b128 v[128:131], v188
	ds_read_b128 v[132:135], v188 offset:1024
	ds_read_b128 v[136:139], v188 offset:2048
	ds_read_b128 v[140:143], v188 offset:3072
	ds_read_b128 v[144:147], v189
	ds_read_b128 v[148:151], v189 offset:1024
	ds_read_b128 v[152:155], v189 offset:2048
	ds_read_b128 v[160:163], v189 offset:3072
	s_add_i32 s77, s77, 0x100000
	s_mov_b32 m0, s38
	ds_read_b128 v[164:167], v187 offset:32768
	ds_read_b128 v[168:171], v187 offset:33792
	ds_read_b128 v[172:175], v187 offset:34816
	ds_read_b128 v[176:179], v187 offset:35840
	ds_read_b128 v[190:193], v187 offset:36864
	ds_read_b128 v[194:197], v187 offset:37888
	ds_read_b128 v[198:201], v187 offset:38912
	ds_read_b128 v[202:205], v187 offset:39936
	buffer_load_dwordx4 v181, s[4:7], s77 offen lds
	s_mov_b32 m0, s39
	s_nop 0
	buffer_load_dwordx4 v183, s[4:7], s77 offen lds
	s_waitcnt vmcnt(8)
	s_waitcnt lgkmcnt(0)
	s_barrier
	s_setprio 1
	s_waitcnt lgkmcnt(7)
	v_mfma_f32_16x16x32_bf16 v[124:127], v[128:131], v[164:167], v[124:127]
	v_mfma_f32_16x16x32_bf16 v[120:123], v[136:139], v[164:167], v[120:123]
	s_waitcnt lgkmcnt(5)
	v_mfma_f32_16x16x32_bf16 v[108:111], v[128:131], v[172:175], v[108:111]
	v_mfma_f32_16x16x32_bf16 v[104:107], v[136:139], v[172:175], v[104:107]
	s_waitcnt lgkmcnt(3)
	v_mfma_f32_16x16x32_bf16 v[92:95], v[128:131], v[190:193], v[92:95]
	v_mfma_f32_16x16x32_bf16 v[88:91], v[136:139], v[190:193], v[88:91]
	s_waitcnt lgkmcnt(1)
	v_mfma_f32_16x16x32_bf16 v[76:79], v[128:131], v[198:201], v[76:79]
	v_mfma_f32_16x16x32_bf16 v[72:75], v[136:139], v[198:201], v[72:75]
	v_mfma_f32_16x16x32_bf16 v[124:127], v[132:135], v[168:171], v[124:127]
	v_mfma_f32_16x16x32_bf16 v[120:123], v[140:143], v[168:171], v[120:123]
	v_mfma_f32_16x16x32_bf16 v[108:111], v[132:135], v[176:179], v[108:111]
	v_mfma_f32_16x16x32_bf16 v[104:107], v[140:143], v[176:179], v[104:107]
	v_mfma_f32_16x16x32_bf16 v[92:95], v[132:135], v[194:197], v[92:95]
	v_mfma_f32_16x16x32_bf16 v[88:91], v[140:143], v[194:197], v[88:91]
	s_waitcnt lgkmcnt(0)
	v_mfma_f32_16x16x32_bf16 v[76:79], v[132:135], v[202:205], v[76:79]
	v_mfma_f32_16x16x32_bf16 v[72:75], v[140:143], v[202:205], v[72:75]
	s_setprio 0
	s_setprio 1
	v_mfma_f32_16x16x32_bf16 v[116:119], v[144:147], v[164:167], v[116:119]
	v_mfma_f32_16x16x32_bf16 v[112:115], v[152:155], v[164:167], v[112:115]
	v_mfma_f32_16x16x32_bf16 v[100:103], v[144:147], v[172:175], v[100:103]
	v_mfma_f32_16x16x32_bf16 v[96:99], v[152:155], v[172:175], v[96:99]
	v_mfma_f32_16x16x32_bf16 v[84:87], v[144:147], v[190:193], v[84:87]
	v_mfma_f32_16x16x32_bf16 v[80:83], v[152:155], v[190:193], v[80:83]
	v_mfma_f32_16x16x32_bf16 v[68:71], v[144:147], v[198:201], v[68:71]
	v_mfma_f32_16x16x32_bf16 v[64:67], v[152:155], v[198:201], v[64:67]
	v_mfma_f32_16x16x32_bf16 v[116:119], v[148:151], v[168:171], v[116:119]
	v_mfma_f32_16x16x32_bf16 v[112:115], v[160:163], v[168:171], v[112:115]
	v_mfma_f32_16x16x32_bf16 v[100:103], v[148:151], v[176:179], v[100:103]
	v_mfma_f32_16x16x32_bf16 v[96:99], v[160:163], v[176:179], v[96:99]
	v_mfma_f32_16x16x32_bf16 v[84:87], v[148:151], v[194:197], v[84:87]
	v_mfma_f32_16x16x32_bf16 v[80:83], v[160:163], v[194:197], v[80:83]
	v_mfma_f32_16x16x32_bf16 v[68:71], v[148:151], v[202:205], v[68:71]
	v_mfma_f32_16x16x32_bf16 v[64:67], v[160:163], v[202:205], v[64:67]
	s_setprio 0
	s_barrier
	s_mov_b32 m0, s45
	s_add_i32 s77, s23, 0x80
	ds_read_b128 v[164:167], v187 offset:49152
	ds_read_b128 v[168:171], v187 offset:50176
	ds_read_b128 v[172:175], v187 offset:51200
	ds_read_b128 v[176:179], v187 offset:52224
	ds_read_b128 v[190:193], v187 offset:53248
	ds_read_b128 v[194:197], v187 offset:54272
	ds_read_b128 v[198:201], v187 offset:55296
	ds_read_b128 v[202:205], v187 offset:56320
	buffer_load_dwordx4 v182, s[80:83], s77 offen lds
	s_mov_b32 m0, s46
	s_add_i32 s23, s23, 0x100080
	buffer_load_dwordx4 v184, s[80:83], s77 offen lds
	s_mov_b32 m0, s50
	s_nop 0
	buffer_load_dwordx4 v182, s[80:83], s23 offen lds
	s_mov_b32 m0, s51
	s_nop 0
	buffer_load_dwordx4 v184, s[80:83], s23 offen lds
	s_mov_b32 m0, s47
	s_nop 0
	buffer_load_dwordx4 v181, s[4:7], s22 offen lds
	s_mov_b32 m0, s49
	s_nop 0
	buffer_load_dwordx4 v183, s[4:7], s22 offen lds
	s_waitcnt vmcnt(8)
	s_waitcnt lgkmcnt(0)
	s_barrier
	s_setprio 1
	s_waitcnt lgkmcnt(7)
	v_mfma_f32_16x16x32_bf16 v[60:63], v[128:131], v[164:167], v[60:63]
	v_mfma_f32_16x16x32_bf16 v[56:59], v[136:139], v[164:167], v[56:59]
	s_waitcnt lgkmcnt(5)
	v_mfma_f32_16x16x32_bf16 v[44:47], v[128:131], v[172:175], v[44:47]
	v_mfma_f32_16x16x32_bf16 v[40:43], v[136:139], v[172:175], v[40:43]
	s_waitcnt lgkmcnt(3)
	v_mfma_f32_16x16x32_bf16 v[28:31], v[128:131], v[190:193], v[28:31]
	v_mfma_f32_16x16x32_bf16 v[24:27], v[136:139], v[190:193], v[24:27]
	s_waitcnt lgkmcnt(1)
	v_mfma_f32_16x16x32_bf16 v[12:15], v[128:131], v[198:201], v[12:15]
	v_mfma_f32_16x16x32_bf16 v[8:11], v[136:139], v[198:201], v[8:11]
	v_mfma_f32_16x16x32_bf16 v[60:63], v[132:135], v[168:171], v[60:63]
	v_mfma_f32_16x16x32_bf16 v[56:59], v[140:143], v[168:171], v[56:59]
	v_mfma_f32_16x16x32_bf16 v[44:47], v[132:135], v[176:179], v[44:47]
	v_mfma_f32_16x16x32_bf16 v[40:43], v[140:143], v[176:179], v[40:43]
	v_mfma_f32_16x16x32_bf16 v[28:31], v[132:135], v[194:197], v[28:31]
	v_mfma_f32_16x16x32_bf16 v[24:27], v[140:143], v[194:197], v[24:27]
	s_waitcnt lgkmcnt(0)
	v_mfma_f32_16x16x32_bf16 v[12:15], v[132:135], v[202:205], v[12:15]
	v_mfma_f32_16x16x32_bf16 v[8:11], v[140:143], v[202:205], v[8:11]
	s_setprio 0
	s_setprio 1
	v_mfma_f32_16x16x32_bf16 v[52:55], v[144:147], v[164:167], v[52:55]
	v_mfma_f32_16x16x32_bf16 v[48:51], v[152:155], v[164:167], v[48:51]
	v_mfma_f32_16x16x32_bf16 v[36:39], v[144:147], v[172:175], v[36:39]
	v_mfma_f32_16x16x32_bf16 v[32:35], v[152:155], v[172:175], v[32:35]
	v_mfma_f32_16x16x32_bf16 v[20:23], v[144:147], v[190:193], v[20:23]
	v_mfma_f32_16x16x32_bf16 v[16:19], v[152:155], v[190:193], v[16:19]
	v_mfma_f32_16x16x32_bf16 v[4:7], v[144:147], v[198:201], v[4:7]
	v_mfma_f32_16x16x32_bf16 v[0:3], v[152:155], v[198:201], v[0:3]
	v_mfma_f32_16x16x32_bf16 v[52:55], v[148:151], v[168:171], v[52:55]
	v_mfma_f32_16x16x32_bf16 v[48:51], v[160:163], v[168:171], v[48:51]
	v_mfma_f32_16x16x32_bf16 v[36:39], v[148:151], v[176:179], v[36:39]
	v_mfma_f32_16x16x32_bf16 v[32:35], v[160:163], v[176:179], v[32:35]
	v_mfma_f32_16x16x32_bf16 v[20:23], v[148:151], v[194:197], v[20:23]
	v_mfma_f32_16x16x32_bf16 v[16:19], v[160:163], v[194:197], v[16:19]
	v_mfma_f32_16x16x32_bf16 v[4:7], v[148:151], v[202:205], v[4:7]
	v_mfma_f32_16x16x32_bf16 v[0:3], v[160:163], v[202:205], v[0:3]
	s_setprio 0
	s_add_i32 s76, s76, 2
	s_addk_i32 s59, 0x100
	s_addk_i32 s75, 0x100
	s_cmp_ge_i32 s76, s20
	s_barrier
	s_cbranch_scc0 .LBB0_1247
	v_readlane_b32 s76, v254, 37
	v_readlane_b32 s77, v254, 38
	s_and_b64 vcc, exec, s[10:11]
	s_cbranch_vccz .LBB0_1250

.LBB0_1397:
	ds_read_b128 v[132:135], v142
	ds_read_b128 v[148:151], v142 offset:1024
	ds_read_b128 v[152:155], v142 offset:2048
	ds_read_b128 v[156:159], v142 offset:3072
	ds_read_b128 v[160:163], v143
	ds_read_b128 v[164:167], v143 offset:1024
	ds_read_b128 v[168:171], v143 offset:2048
	ds_read_b128 v[172:175], v143 offset:3072
	s_add_i32 s22, s59, 0xfff00080
	s_cmp_eq_u32 s58, s65
	s_cselect_b32 s66, s14, s22
	s_cselect_b32 s23, s15, s64
	s_add_i32 s22, s66, 0x80
	s_mov_b32 m0, s43
	ds_read_b128 v[176:179], v144
	ds_read_b128 v[180:183], v144 offset:1024
	ds_read_b128 v[184:187], v144 offset:2048
	ds_read_b128 v[188:191], v144 offset:3072
	ds_read_b128 v[192:195], v144 offset:4096
	ds_read_b128 v[196:199], v144 offset:5120
	ds_read_b128 v[200:203], v144 offset:6144
	ds_read_b128 v[204:207], v144 offset:7168
	buffer_load_dwordx4 v138, s[60:63], s59 offen lds
	s_mov_b32 m0, s44
	s_nop 0
	buffer_load_dwordx4 v140, s[60:63], s59 offen lds
	s_waitcnt vmcnt(8)
	s_waitcnt lgkmcnt(0)
	s_barrier
	s_setprio 1
	s_waitcnt lgkmcnt(7)
	v_mfma_f32_16x16x32_bf16 v[124:127], v[132:135], v[176:179], v[124:127]
	v_mfma_f32_16x16x32_bf16 v[120:123], v[152:155], v[176:179], v[120:123]
	s_waitcnt lgkmcnt(5)
	v_mfma_f32_16x16x32_bf16 v[108:111], v[132:135], v[184:187], v[108:111]
	v_mfma_f32_16x16x32_bf16 v[104:107], v[152:155], v[184:187], v[104:107]
	s_waitcnt lgkmcnt(3)
	v_mfma_f32_16x16x32_bf16 v[92:95], v[132:135], v[192:195], v[92:95]
	v_mfma_f32_16x16x32_bf16 v[88:91], v[152:155], v[192:195], v[88:91]
	s_waitcnt lgkmcnt(1)
	v_mfma_f32_16x16x32_bf16 v[76:79], v[132:135], v[200:203], v[76:79]
	v_mfma_f32_16x16x32_bf16 v[72:75], v[152:155], v[200:203], v[72:75]
	v_mfma_f32_16x16x32_bf16 v[124:127], v[148:151], v[180:183], v[124:127]
	v_mfma_f32_16x16x32_bf16 v[120:123], v[156:159], v[180:183], v[120:123]
	v_mfma_f32_16x16x32_bf16 v[108:111], v[148:151], v[188:191], v[108:111]
	v_mfma_f32_16x16x32_bf16 v[104:107], v[156:159], v[188:191], v[104:107]
	v_mfma_f32_16x16x32_bf16 v[92:95], v[148:151], v[196:199], v[92:95]
	v_mfma_f32_16x16x32_bf16 v[88:91], v[156:159], v[196:199], v[88:91]
	s_waitcnt lgkmcnt(0)
	v_mfma_f32_16x16x32_bf16 v[76:79], v[148:151], v[204:207], v[76:79]
	v_mfma_f32_16x16x32_bf16 v[72:75], v[156:159], v[204:207], v[72:75]
	s_setprio 0
	s_setprio 1
	v_mfma_f32_16x16x32_bf16 v[116:119], v[160:163], v[176:179], v[116:119]
	v_mfma_f32_16x16x32_bf16 v[112:115], v[168:171], v[176:179], v[112:115]
	v_mfma_f32_16x16x32_bf16 v[100:103], v[160:163], v[184:187], v[100:103]
	v_mfma_f32_16x16x32_bf16 v[96:99], v[168:171], v[184:187], v[96:99]
	v_mfma_f32_16x16x32_bf16 v[84:87], v[160:163], v[192:195], v[84:87]
	v_mfma_f32_16x16x32_bf16 v[80:83], v[168:171], v[192:195], v[80:83]
	v_mfma_f32_16x16x32_bf16 v[68:71], v[160:163], v[200:203], v[68:71]
	v_mfma_f32_16x16x32_bf16 v[64:67], v[168:171], v[200:203], v[64:67]
	v_mfma_f32_16x16x32_bf16 v[116:119], v[164:167], v[180:183], v[116:119]
	v_mfma_f32_16x16x32_bf16 v[112:115], v[172:175], v[180:183], v[112:115]
	v_mfma_f32_16x16x32_bf16 v[100:103], v[164:167], v[188:191], v[100:103]
	v_mfma_f32_16x16x32_bf16 v[96:99], v[172:175], v[188:191], v[96:99]
	v_mfma_f32_16x16x32_bf16 v[84:87], v[164:167], v[196:199], v[84:87]
	v_mfma_f32_16x16x32_bf16 v[80:83], v[172:175], v[196:199], v[80:83]
	v_mfma_f32_16x16x32_bf16 v[68:71], v[164:167], v[204:207], v[68:71]
	v_mfma_f32_16x16x32_bf16 v[64:67], v[172:175], v[204:207], v[64:67]
	s_setprio 0
	s_barrier
	s_mov_b32 m0, s9
	s_mov_b32 s38, s62
	s_mov_b32 s39, s63
	ds_read_b128 v[176:179], v144 offset:16384
	ds_read_b128 v[180:183], v144 offset:17408
	ds_read_b128 v[184:187], v144 offset:18432
	ds_read_b128 v[188:191], v144 offset:19456
	ds_read_b128 v[192:195], v144 offset:20480
	ds_read_b128 v[196:199], v144 offset:21504
	ds_read_b128 v[200:203], v144 offset:22528
	ds_read_b128 v[204:207], v144 offset:23552
	buffer_load_dwordx4 v139, s[36:39], s23 offen lds
	s_mov_b32 m0, s18
	s_add_i32 s67, s23, 0x100000
	buffer_load_dwordx4 v141, s[36:39], s23 offen lds
	s_mov_b32 m0, s19
	s_nop 0
	buffer_load_dwordx4 v139, s[36:39], s67 offen lds
	s_mov_b32 m0, s20
	s_nop 0
	buffer_load_dwordx4 v141, s[36:39], s67 offen lds
	s_mov_b32 m0, s3
	s_nop 0
	buffer_load_dwordx4 v138, s[60:63], s66 offen lds
	s_mov_b32 m0, s21
	s_nop 0
	buffer_load_dwordx4 v140, s[60:63], s66 offen lds
	s_waitcnt vmcnt(8)
	s_waitcnt lgkmcnt(0)
	s_barrier
	s_setprio 1
	s_waitcnt lgkmcnt(7)
	v_mfma_f32_16x16x32_bf16 v[60:63], v[132:135], v[176:179], v[60:63]
	v_mfma_f32_16x16x32_bf16 v[56:59], v[152:155], v[176:179], v[56:59]
	s_waitcnt lgkmcnt(5)
	v_mfma_f32_16x16x32_bf16 v[44:47], v[132:135], v[184:187], v[44:47]
	v_mfma_f32_16x16x32_bf16 v[40:43], v[152:155], v[184:187], v[40:43]
	s_waitcnt lgkmcnt(3)
	v_mfma_f32_16x16x32_bf16 v[28:31], v[132:135], v[192:195], v[28:31]
	v_mfma_f32_16x16x32_bf16 v[24:27], v[152:155], v[192:195], v[24:27]
	s_waitcnt lgkmcnt(1)
	v_mfma_f32_16x16x32_bf16 v[12:15], v[132:135], v[200:203], v[12:15]
	v_mfma_f32_16x16x32_bf16 v[8:11], v[152:155], v[200:203], v[8:11]
	v_mfma_f32_16x16x32_bf16 v[60:63], v[148:151], v[180:183], v[60:63]
	v_mfma_f32_16x16x32_bf16 v[56:59], v[156:159], v[180:183], v[56:59]
	v_mfma_f32_16x16x32_bf16 v[44:47], v[148:151], v[188:191], v[44:47]
	v_mfma_f32_16x16x32_bf16 v[40:43], v[156:159], v[188:191], v[40:43]
	v_mfma_f32_16x16x32_bf16 v[28:31], v[148:151], v[196:199], v[28:31]
	v_mfma_f32_16x16x32_bf16 v[24:27], v[156:159], v[196:199], v[24:27]
	s_waitcnt lgkmcnt(0)
	v_mfma_f32_16x16x32_bf16 v[12:15], v[148:151], v[204:207], v[12:15]
	v_mfma_f32_16x16x32_bf16 v[8:11], v[156:159], v[204:207], v[8:11]
	s_setprio 0
	s_setprio 1
	v_mfma_f32_16x16x32_bf16 v[52:55], v[160:163], v[176:179], v[52:55]
	v_mfma_f32_16x16x32_bf16 v[48:51], v[168:171], v[176:179], v[48:51]
	v_mfma_f32_16x16x32_bf16 v[36:39], v[160:163], v[184:187], v[36:39]
	v_mfma_f32_16x16x32_bf16 v[32:35], v[168:171], v[184:187], v[32:35]
	v_mfma_f32_16x16x32_bf16 v[20:23], v[160:163], v[192:195], v[20:23]
	v_mfma_f32_16x16x32_bf16 v[16:19], v[168:171], v[192:195], v[16:19]
	v_mfma_f32_16x16x32_bf16 v[4:7], v[160:163], v[200:203], v[4:7]
	v_mfma_f32_16x16x32_bf16 v[0:3], v[168:171], v[200:203], v[0:3]
	v_mfma_f32_16x16x32_bf16 v[52:55], v[164:167], v[180:183], v[52:55]
	v_mfma_f32_16x16x32_bf16 v[48:51], v[172:175], v[180:183], v[48:51]
	v_mfma_f32_16x16x32_bf16 v[36:39], v[164:167], v[188:191], v[36:39]
	v_mfma_f32_16x16x32_bf16 v[32:35], v[172:175], v[188:191], v[32:35]
	v_mfma_f32_16x16x32_bf16 v[20:23], v[164:167], v[196:199], v[20:23]
	v_mfma_f32_16x16x32_bf16 v[16:19], v[172:175], v[196:199], v[16:19]
	v_mfma_f32_16x16x32_bf16 v[4:7], v[164:167], v[204:207], v[4:7]
	v_mfma_f32_16x16x32_bf16 v[0:3], v[172:175], v[204:207], v[0:3]
	s_setprio 0
	s_barrier
	ds_read_b128 v[132:135], v145
	ds_read_b128 v[148:151], v145 offset:1024
	ds_read_b128 v[152:155], v145 offset:2048
	ds_read_b128 v[156:159], v145 offset:3072
	ds_read_b128 v[160:163], v146
	ds_read_b128 v[164:167], v146 offset:1024
	ds_read_b128 v[168:171], v146 offset:2048
	ds_read_b128 v[172:175], v146 offset:3072
	s_add_i32 s66, s66, 0x100000
	s_mov_b32 m0, s24
	ds_read_b128 v[176:179], v144 offset:32768
	ds_read_b128 v[180:183], v144 offset:33792
	ds_read_b128 v[184:187], v144 offset:34816
	ds_read_b128 v[188:191], v144 offset:35840
	ds_read_b128 v[192:195], v144 offset:36864
	ds_read_b128 v[196:199], v144 offset:37888
	ds_read_b128 v[200:203], v144 offset:38912
	ds_read_b128 v[204:207], v144 offset:39936
	buffer_load_dwordx4 v138, s[60:63], s66 offen lds
	s_mov_b32 m0, s25
	s_nop 0
	buffer_load_dwordx4 v140, s[60:63], s66 offen lds
	s_waitcnt vmcnt(8)
	s_waitcnt lgkmcnt(0)
	s_barrier
	s_setprio 1
	s_waitcnt lgkmcnt(7)
	v_mfma_f32_16x16x32_bf16 v[124:127], v[132:135], v[176:179], v[124:127]
	v_mfma_f32_16x16x32_bf16 v[120:123], v[152:155], v[176:179], v[120:123]
	s_waitcnt lgkmcnt(5)
	v_mfma_f32_16x16x32_bf16 v[108:111], v[132:135], v[184:187], v[108:111]
	v_mfma_f32_16x16x32_bf16 v[104:107], v[152:155], v[184:187], v[104:107]
	s_waitcnt lgkmcnt(3)
	v_mfma_f32_16x16x32_bf16 v[92:95], v[132:135], v[192:195], v[92:95]
	v_mfma_f32_16x16x32_bf16 v[88:91], v[152:155], v[192:195], v[88:91]
	s_waitcnt lgkmcnt(1)
	v_mfma_f32_16x16x32_bf16 v[76:79], v[132:135], v[200:203], v[76:79]
	v_mfma_f32_16x16x32_bf16 v[72:75], v[152:155], v[200:203], v[72:75]
	v_mfma_f32_16x16x32_bf16 v[124:127], v[148:151], v[180:183], v[124:127]
	v_mfma_f32_16x16x32_bf16 v[120:123], v[156:159], v[180:183], v[120:123]
	v_mfma_f32_16x16x32_bf16 v[108:111], v[148:151], v[188:191], v[108:111]
	v_mfma_f32_16x16x32_bf16 v[104:107], v[156:159], v[188:191], v[104:107]
	v_mfma_f32_16x16x32_bf16 v[92:95], v[148:151], v[196:199], v[92:95]
	v_mfma_f32_16x16x32_bf16 v[88:91], v[156:159], v[196:199], v[88:91]
	s_waitcnt lgkmcnt(0)
	v_mfma_f32_16x16x32_bf16 v[76:79], v[148:151], v[204:207], v[76:79]
	v_mfma_f32_16x16x32_bf16 v[72:75], v[156:159], v[204:207], v[72:75]
	s_setprio 0
	s_setprio 1
	v_mfma_f32_16x16x32_bf16 v[116:119], v[160:163], v[176:179], v[116:119]
	v_mfma_f32_16x16x32_bf16 v[112:115], v[168:171], v[176:179], v[112:115]
	v_mfma_f32_16x16x32_bf16 v[100:103], v[160:163], v[184:187], v[100:103]
	v_mfma_f32_16x16x32_bf16 v[96:99], v[168:171], v[184:187], v[96:99]
	v_mfma_f32_16x16x32_bf16 v[84:87], v[160:163], v[192:195], v[84:87]
	v_mfma_f32_16x16x32_bf16 v[80:83], v[168:171], v[192:195], v[80:83]
	v_mfma_f32_16x16x32_bf16 v[68:71], v[160:163], v[200:203], v[68:71]
	v_mfma_f32_16x16x32_bf16 v[64:67], v[168:171], v[200:203], v[64:67]
	v_mfma_f32_16x16x32_bf16 v[116:119], v[164:167], v[180:183], v[116:119]
	v_mfma_f32_16x16x32_bf16 v[112:115], v[172:175], v[180:183], v[112:115]
	v_mfma_f32_16x16x32_bf16 v[100:103], v[164:167], v[188:191], v[100:103]
	v_mfma_f32_16x16x32_bf16 v[96:99], v[172:175], v[188:191], v[96:99]
	v_mfma_f32_16x16x32_bf16 v[84:87], v[164:167], v[196:199], v[84:87]
	v_mfma_f32_16x16x32_bf16 v[80:83], v[172:175], v[196:199], v[80:83]
	v_mfma_f32_16x16x32_bf16 v[68:71], v[164:167], v[204:207], v[68:71]
	v_mfma_f32_16x16x32_bf16 v[64:67], v[172:175], v[204:207], v[64:67]
	s_setprio 0
	s_barrier
	s_mov_b32 m0, s26
	s_add_i32 s66, s23, 0x80
	ds_read_b128 v[176:179], v144 offset:49152
	ds_read_b128 v[180:183], v144 offset:50176
	ds_read_b128 v[184:187], v144 offset:51200
	ds_read_b128 v[188:191], v144 offset:52224
	ds_read_b128 v[192:195], v144 offset:53248
	ds_read_b128 v[196:199], v144 offset:54272
	ds_read_b128 v[200:203], v144 offset:55296
	ds_read_b128 v[204:207], v144 offset:56320
	buffer_load_dwordx4 v139, s[36:39], s66 offen lds
	s_mov_b32 m0, s27
	s_add_i32 s23, s23, 0x100080
	buffer_load_dwordx4 v141, s[36:39], s66 offen lds
	s_mov_b32 m0, s31
	s_nop 0
	buffer_load_dwordx4 v139, s[36:39], s23 offen lds
	s_mov_b32 m0, s40
	s_nop 0
	buffer_load_dwordx4 v141, s[36:39], s23 offen lds
	s_mov_b32 m0, s29
	s_nop 0
	buffer_load_dwordx4 v138, s[60:63], s22 offen lds
	s_mov_b32 m0, s30
	s_nop 0
	buffer_load_dwordx4 v140, s[60:63], s22 offen lds
	s_waitcnt vmcnt(8)
	s_waitcnt lgkmcnt(0)
	s_barrier
	s_setprio 1
	s_waitcnt lgkmcnt(7)
	v_mfma_f32_16x16x32_bf16 v[60:63], v[132:135], v[176:179], v[60:63]
	v_mfma_f32_16x16x32_bf16 v[56:59], v[152:155], v[176:179], v[56:59]
	s_waitcnt lgkmcnt(5)
	v_mfma_f32_16x16x32_bf16 v[44:47], v[132:135], v[184:187], v[44:47]
	v_mfma_f32_16x16x32_bf16 v[40:43], v[152:155], v[184:187], v[40:43]
	s_waitcnt lgkmcnt(3)
	v_mfma_f32_16x16x32_bf16 v[28:31], v[132:135], v[192:195], v[28:31]
	v_mfma_f32_16x16x32_bf16 v[24:27], v[152:155], v[192:195], v[24:27]
	s_waitcnt lgkmcnt(1)
	v_mfma_f32_16x16x32_bf16 v[12:15], v[132:135], v[200:203], v[12:15]
	v_mfma_f32_16x16x32_bf16 v[8:11], v[152:155], v[200:203], v[8:11]
	v_mfma_f32_16x16x32_bf16 v[60:63], v[148:151], v[180:183], v[60:63]
	v_mfma_f32_16x16x32_bf16 v[56:59], v[156:159], v[180:183], v[56:59]
	v_mfma_f32_16x16x32_bf16 v[44:47], v[148:151], v[188:191], v[44:47]
	v_mfma_f32_16x16x32_bf16 v[40:43], v[156:159], v[188:191], v[40:43]
	v_mfma_f32_16x16x32_bf16 v[28:31], v[148:151], v[196:199], v[28:31]
	v_mfma_f32_16x16x32_bf16 v[24:27], v[156:159], v[196:199], v[24:27]
	s_waitcnt lgkmcnt(0)
	v_mfma_f32_16x16x32_bf16 v[12:15], v[148:151], v[204:207], v[12:15]
	v_mfma_f32_16x16x32_bf16 v[8:11], v[156:159], v[204:207], v[8:11]
	s_setprio 0
	s_setprio 1
	v_mfma_f32_16x16x32_bf16 v[52:55], v[160:163], v[176:179], v[52:55]
	v_mfma_f32_16x16x32_bf16 v[48:51], v[168:171], v[176:179], v[48:51]
	v_mfma_f32_16x16x32_bf16 v[36:39], v[160:163], v[184:187], v[36:39]
	v_mfma_f32_16x16x32_bf16 v[32:35], v[168:171], v[184:187], v[32:35]
	v_mfma_f32_16x16x32_bf16 v[20:23], v[160:163], v[192:195], v[20:23]
	v_mfma_f32_16x16x32_bf16 v[16:19], v[168:171], v[192:195], v[16:19]
	v_mfma_f32_16x16x32_bf16 v[4:7], v[160:163], v[200:203], v[4:7]
	v_mfma_f32_16x16x32_bf16 v[0:3], v[168:171], v[200:203], v[0:3]
	v_mfma_f32_16x16x32_bf16 v[52:55], v[164:167], v[180:183], v[52:55]
	v_mfma_f32_16x16x32_bf16 v[48:51], v[172:175], v[180:183], v[48:51]
	v_mfma_f32_16x16x32_bf16 v[36:39], v[164:167], v[188:191], v[36:39]
	v_mfma_f32_16x16x32_bf16 v[32:35], v[172:175], v[188:191], v[32:35]
	v_mfma_f32_16x16x32_bf16 v[20:23], v[164:167], v[196:199], v[20:23]
	v_mfma_f32_16x16x32_bf16 v[16:19], v[172:175], v[196:199], v[16:19]
	v_mfma_f32_16x16x32_bf16 v[4:7], v[164:167], v[204:207], v[4:7]
	v_mfma_f32_16x16x32_bf16 v[0:3], v[172:175], v[204:207], v[0:3]
	s_setprio 0
	s_add_i32 s65, s65, 2
	s_addk_i32 s59, 0x100
	s_addk_i32 s64, 0x100
	s_cmp_ge_i32 s65, s57
	s_barrier
	s_cbranch_scc0 .LBB0_1397
	s_and_b64 vcc, exec, s[6:7]
	s_cbranch_vccz .LBB0_1400

.LBB0_1565:
	v_add_u32_e32 v140, 0x10000, v150
	ds_read_b128 v[132:135], v140
	ds_read_b128 v[136:139], v140 offset:1024
	ds_read_b128 v[154:157], v140 offset:2048
	ds_read_b128 v[158:161], v140 offset:3072
	v_add_u32_e32 v140, 0x14000, v150
	ds_read_b128 v[162:165], v140
	ds_read_b128 v[166:169], v140 offset:1024
	ds_read_b128 v[170:173], v140 offset:2048
	ds_read_b128 v[174:177], v140 offset:3072
	s_add_i32 s22, s60, 0xfff80080
	s_cmp_eq_u32 s45, s62
	s_cselect_b32 s63, s58, s22
	s_cselect_b32 s23, s59, s61
	s_or_b32 s22, s63, 0x80
	s_mov_b32 m0, s46
	ds_read_b128 v[178:181], v151
	ds_read_b128 v[182:185], v151 offset:1024
	ds_read_b128 v[186:189], v151 offset:2048
	ds_read_b128 v[190:193], v151 offset:3072
	ds_read_b128 v[194:197], v151 offset:4096
	ds_read_b128 v[198:201], v151 offset:5120
	ds_read_b128 v[202:205], v151 offset:6144
	ds_read_b128 v[206:209], v151 offset:7168
	buffer_load_dwordx4 v143, s[88:91], s60 offen lds
	s_mov_b32 m0, s47
	s_nop 0
	buffer_load_dwordx4 v147, s[88:91], s60 offen lds
	s_waitcnt vmcnt(8)
	s_waitcnt lgkmcnt(0)
	s_barrier
	s_setprio 1
	s_waitcnt lgkmcnt(7)
	v_mfma_i32_16x16x64_i8 v[120:123], v[132:135], v[178:181], v[120:123]
	v_mfma_i32_16x16x64_i8 v[112:115], v[154:157], v[178:181], v[112:115]
	s_waitcnt lgkmcnt(5)
	v_mfma_i32_16x16x64_i8 v[104:107], v[132:135], v[186:189], v[104:107]
	v_mfma_i32_16x16x64_i8 v[96:99], v[154:157], v[186:189], v[96:99]
	s_waitcnt lgkmcnt(3)
	v_mfma_i32_16x16x64_i8 v[88:91], v[132:135], v[194:197], v[88:91]
	v_mfma_i32_16x16x64_i8 v[80:83], v[154:157], v[194:197], v[80:83]
	s_waitcnt lgkmcnt(1)
	v_mfma_i32_16x16x64_i8 v[72:75], v[132:135], v[202:205], v[72:75]
	v_mfma_i32_16x16x64_i8 v[64:67], v[154:157], v[202:205], v[64:67]
	v_mfma_i32_16x16x64_i8 v[120:123], v[136:139], v[182:185], v[120:123]
	v_mfma_i32_16x16x64_i8 v[112:115], v[158:161], v[182:185], v[112:115]
	v_mfma_i32_16x16x64_i8 v[104:107], v[136:139], v[190:193], v[104:107]
	v_mfma_i32_16x16x64_i8 v[96:99], v[158:161], v[190:193], v[96:99]
	v_mfma_i32_16x16x64_i8 v[88:91], v[136:139], v[198:201], v[88:91]
	v_mfma_i32_16x16x64_i8 v[80:83], v[158:161], v[198:201], v[80:83]
	s_waitcnt lgkmcnt(0)
	v_mfma_i32_16x16x64_i8 v[72:75], v[136:139], v[206:209], v[72:75]
	v_mfma_i32_16x16x64_i8 v[64:67], v[158:161], v[206:209], v[64:67]
	s_setprio 0
	s_setprio 1
	v_mfma_i32_16x16x64_i8 v[124:127], v[162:165], v[178:181], v[124:127]
	v_mfma_i32_16x16x64_i8 v[116:119], v[170:173], v[178:181], v[116:119]
	v_mfma_i32_16x16x64_i8 v[108:111], v[162:165], v[186:189], v[108:111]
	v_mfma_i32_16x16x64_i8 v[100:103], v[170:173], v[186:189], v[100:103]
	v_mfma_i32_16x16x64_i8 v[92:95], v[162:165], v[194:197], v[92:95]
	v_mfma_i32_16x16x64_i8 v[84:87], v[170:173], v[194:197], v[84:87]
	v_mfma_i32_16x16x64_i8 v[76:79], v[162:165], v[202:205], v[76:79]
	v_mfma_i32_16x16x64_i8 v[68:71], v[170:173], v[202:205], v[68:71]
	v_mfma_i32_16x16x64_i8 v[124:127], v[166:169], v[182:185], v[124:127]
	v_mfma_i32_16x16x64_i8 v[116:119], v[174:177], v[182:185], v[116:119]
	v_mfma_i32_16x16x64_i8 v[108:111], v[166:169], v[190:193], v[108:111]
	v_mfma_i32_16x16x64_i8 v[100:103], v[174:177], v[190:193], v[100:103]
	v_mfma_i32_16x16x64_i8 v[92:95], v[166:169], v[198:201], v[92:95]
	v_mfma_i32_16x16x64_i8 v[84:87], v[174:177], v[198:201], v[84:87]
	v_mfma_i32_16x16x64_i8 v[76:79], v[166:169], v[206:209], v[76:79]
	v_mfma_i32_16x16x64_i8 v[68:71], v[174:177], v[206:209], v[68:71]
	s_setprio 0
	s_barrier
	s_mov_b32 m0, s18
	s_mov_b32 s30, s90
	s_mov_b32 s31, s91
	ds_read_b128 v[178:181], v151 offset:16384
	ds_read_b128 v[182:185], v151 offset:17408
	ds_read_b128 v[186:189], v151 offset:18432
	ds_read_b128 v[190:193], v151 offset:19456
	ds_read_b128 v[194:197], v151 offset:20480
	ds_read_b128 v[198:201], v151 offset:21504
	ds_read_b128 v[202:205], v151 offset:22528
	ds_read_b128 v[206:209], v151 offset:23552
	buffer_load_dwordx4 v145, s[28:31], s23 offen lds
	s_mov_b32 m0, s19
	s_add_i32 s64, s23, 0x80000
	buffer_load_dwordx4 v149, s[28:31], s23 offen lds
	s_mov_b32 m0, s20
	s_nop 0
	buffer_load_dwordx4 v145, s[28:31], s64 offen lds
	s_mov_b32 m0, s21
	s_nop 0
	buffer_load_dwordx4 v149, s[28:31], s64 offen lds
	s_mov_b32 m0, s3
	s_nop 0
	buffer_load_dwordx4 v143, s[88:91], s63 offen lds
	s_mov_b32 m0, s24
	s_nop 0
	buffer_load_dwordx4 v147, s[88:91], s63 offen lds
	s_waitcnt vmcnt(8)
	s_waitcnt lgkmcnt(0)
	s_barrier
	s_setprio 1
	s_waitcnt lgkmcnt(7)
	v_mfma_i32_16x16x64_i8 v[56:59], v[132:135], v[178:181], v[56:59]
	v_mfma_i32_16x16x64_i8 v[48:51], v[154:157], v[178:181], v[48:51]
	s_waitcnt lgkmcnt(5)
	v_mfma_i32_16x16x64_i8 v[40:43], v[132:135], v[186:189], v[40:43]
	v_mfma_i32_16x16x64_i8 v[32:35], v[154:157], v[186:189], v[32:35]
	s_waitcnt lgkmcnt(3)
	v_mfma_i32_16x16x64_i8 v[24:27], v[132:135], v[194:197], v[24:27]
	v_mfma_i32_16x16x64_i8 v[16:19], v[154:157], v[194:197], v[16:19]
	s_waitcnt lgkmcnt(1)
	v_mfma_i32_16x16x64_i8 v[8:11], v[132:135], v[202:205], v[8:11]
	v_mfma_i32_16x16x64_i8 v[0:3], v[154:157], v[202:205], v[0:3]
	v_mfma_i32_16x16x64_i8 v[56:59], v[136:139], v[182:185], v[56:59]
	v_mfma_i32_16x16x64_i8 v[48:51], v[158:161], v[182:185], v[48:51]
	v_mfma_i32_16x16x64_i8 v[40:43], v[136:139], v[190:193], v[40:43]
	v_mfma_i32_16x16x64_i8 v[32:35], v[158:161], v[190:193], v[32:35]
	v_mfma_i32_16x16x64_i8 v[24:27], v[136:139], v[198:201], v[24:27]
	v_mfma_i32_16x16x64_i8 v[16:19], v[158:161], v[198:201], v[16:19]
	s_waitcnt lgkmcnt(0)
	v_mfma_i32_16x16x64_i8 v[8:11], v[136:139], v[206:209], v[8:11]
	v_mfma_i32_16x16x64_i8 v[0:3], v[158:161], v[206:209], v[0:3]
	s_setprio 0
	s_setprio 1
	v_mfma_i32_16x16x64_i8 v[60:63], v[162:165], v[178:181], v[60:63]
	v_mfma_i32_16x16x64_i8 v[52:55], v[170:173], v[178:181], v[52:55]
	v_mfma_i32_16x16x64_i8 v[44:47], v[162:165], v[186:189], v[44:47]
	v_mfma_i32_16x16x64_i8 v[36:39], v[170:173], v[186:189], v[36:39]
	v_mfma_i32_16x16x64_i8 v[28:31], v[162:165], v[194:197], v[28:31]
	v_mfma_i32_16x16x64_i8 v[20:23], v[170:173], v[194:197], v[20:23]
	v_mfma_i32_16x16x64_i8 v[12:15], v[162:165], v[202:205], v[12:15]
	v_mfma_i32_16x16x64_i8 v[4:7], v[170:173], v[202:205], v[4:7]
	v_mfma_i32_16x16x64_i8 v[60:63], v[166:169], v[182:185], v[60:63]
	v_mfma_i32_16x16x64_i8 v[52:55], v[174:177], v[182:185], v[52:55]
	v_mfma_i32_16x16x64_i8 v[44:47], v[166:169], v[190:193], v[44:47]
	v_mfma_i32_16x16x64_i8 v[36:39], v[174:177], v[190:193], v[36:39]
	v_mfma_i32_16x16x64_i8 v[28:31], v[166:169], v[198:201], v[28:31]
	v_mfma_i32_16x16x64_i8 v[20:23], v[174:177], v[198:201], v[20:23]
	v_mfma_i32_16x16x64_i8 v[12:15], v[166:169], v[206:209], v[12:15]
	v_mfma_i32_16x16x64_i8 v[4:7], v[174:177], v[206:209], v[4:7]
	s_setprio 0
	s_barrier
	v_add_u32_e32 v140, 0x18000, v150
	ds_read_b128 v[132:135], v140
	ds_read_b128 v[136:139], v140 offset:1024
	ds_read_b128 v[154:157], v140 offset:2048
	ds_read_b128 v[158:161], v140 offset:3072
	v_add_u32_e32 v140, 0x1c000, v150
	ds_read_b128 v[162:165], v140
	ds_read_b128 v[166:169], v140 offset:1024
	ds_read_b128 v[170:173], v140 offset:2048
	ds_read_b128 v[174:177], v140 offset:3072
	s_add_i32 s63, s63, 0x80000
	s_mov_b32 m0, s25
	ds_read_b128 v[178:181], v151 offset:32768
	ds_read_b128 v[182:185], v151 offset:33792
	ds_read_b128 v[186:189], v151 offset:34816
	ds_read_b128 v[190:193], v151 offset:35840
	ds_read_b128 v[194:197], v151 offset:36864
	ds_read_b128 v[198:201], v151 offset:37888
	ds_read_b128 v[202:205], v151 offset:38912
	ds_read_b128 v[206:209], v151 offset:39936
	buffer_load_dwordx4 v143, s[88:91], s63 offen lds
	s_mov_b32 m0, s26
	s_nop 0
	buffer_load_dwordx4 v147, s[88:91], s63 offen lds
	s_waitcnt vmcnt(8)
	s_waitcnt lgkmcnt(0)
	s_barrier
	s_setprio 1
	s_waitcnt lgkmcnt(7)
	v_mfma_i32_16x16x64_i8 v[120:123], v[132:135], v[178:181], v[120:123]
	v_mfma_i32_16x16x64_i8 v[112:115], v[154:157], v[178:181], v[112:115]
	s_waitcnt lgkmcnt(5)
	v_mfma_i32_16x16x64_i8 v[104:107], v[132:135], v[186:189], v[104:107]
	v_mfma_i32_16x16x64_i8 v[96:99], v[154:157], v[186:189], v[96:99]
	s_waitcnt lgkmcnt(3)
	v_mfma_i32_16x16x64_i8 v[88:91], v[132:135], v[194:197], v[88:91]
	v_mfma_i32_16x16x64_i8 v[80:83], v[154:157], v[194:197], v[80:83]
	s_waitcnt lgkmcnt(1)
	v_mfma_i32_16x16x64_i8 v[72:75], v[132:135], v[202:205], v[72:75]
	v_mfma_i32_16x16x64_i8 v[64:67], v[154:157], v[202:205], v[64:67]
	v_mfma_i32_16x16x64_i8 v[120:123], v[136:139], v[182:185], v[120:123]
	v_mfma_i32_16x16x64_i8 v[112:115], v[158:161], v[182:185], v[112:115]
	v_mfma_i32_16x16x64_i8 v[104:107], v[136:139], v[190:193], v[104:107]
	v_mfma_i32_16x16x64_i8 v[96:99], v[158:161], v[190:193], v[96:99]
	v_mfma_i32_16x16x64_i8 v[88:91], v[136:139], v[198:201], v[88:91]
	v_mfma_i32_16x16x64_i8 v[80:83], v[158:161], v[198:201], v[80:83]
	s_waitcnt lgkmcnt(0)
	v_mfma_i32_16x16x64_i8 v[72:75], v[136:139], v[206:209], v[72:75]
	v_mfma_i32_16x16x64_i8 v[64:67], v[158:161], v[206:209], v[64:67]
	s_setprio 0
	s_setprio 1
	v_mfma_i32_16x16x64_i8 v[124:127], v[162:165], v[178:181], v[124:127]
	v_mfma_i32_16x16x64_i8 v[116:119], v[170:173], v[178:181], v[116:119]
	v_mfma_i32_16x16x64_i8 v[108:111], v[162:165], v[186:189], v[108:111]
	v_mfma_i32_16x16x64_i8 v[100:103], v[170:173], v[186:189], v[100:103]
	v_mfma_i32_16x16x64_i8 v[92:95], v[162:165], v[194:197], v[92:95]
	v_mfma_i32_16x16x64_i8 v[84:87], v[170:173], v[194:197], v[84:87]
	v_mfma_i32_16x16x64_i8 v[76:79], v[162:165], v[202:205], v[76:79]
	v_mfma_i32_16x16x64_i8 v[68:71], v[170:173], v[202:205], v[68:71]
	v_mfma_i32_16x16x64_i8 v[124:127], v[166:169], v[182:185], v[124:127]
	v_mfma_i32_16x16x64_i8 v[116:119], v[174:177], v[182:185], v[116:119]
	v_mfma_i32_16x16x64_i8 v[108:111], v[166:169], v[190:193], v[108:111]
	v_mfma_i32_16x16x64_i8 v[100:103], v[174:177], v[190:193], v[100:103]
	v_mfma_i32_16x16x64_i8 v[92:95], v[166:169], v[198:201], v[92:95]
	v_mfma_i32_16x16x64_i8 v[84:87], v[174:177], v[198:201], v[84:87]
	v_mfma_i32_16x16x64_i8 v[76:79], v[166:169], v[206:209], v[76:79]
	v_mfma_i32_16x16x64_i8 v[68:71], v[174:177], v[206:209], v[68:71]
	s_setprio 0
	s_barrier
	s_mov_b32 m0, s36
	s_or_b32 s63, s23, 0x80
	ds_read_b128 v[178:181], v151 offset:49152
	ds_read_b128 v[182:185], v151 offset:50176
	ds_read_b128 v[186:189], v151 offset:51200
	ds_read_b128 v[190:193], v151 offset:52224
	ds_read_b128 v[194:197], v151 offset:53248
	ds_read_b128 v[198:201], v151 offset:54272
	ds_read_b128 v[202:205], v151 offset:55296
	ds_read_b128 v[206:209], v151 offset:56320
	buffer_load_dwordx4 v145, s[28:31], s63 offen lds
	s_mov_b32 m0, s37
	s_add_i32 s23, s23, 0x80080
	buffer_load_dwordx4 v149, s[28:31], s63 offen lds
	s_mov_b32 m0, s40
	s_nop 0
	buffer_load_dwordx4 v145, s[28:31], s23 offen lds
	s_mov_b32 m0, s41
	s_nop 0
	buffer_load_dwordx4 v149, s[28:31], s23 offen lds
	s_mov_b32 m0, s38
	s_nop 0
	buffer_load_dwordx4 v143, s[88:91], s22 offen lds
	s_mov_b32 m0, s39
	s_nop 0
	buffer_load_dwordx4 v147, s[88:91], s22 offen lds
	s_waitcnt vmcnt(8)
	s_waitcnt lgkmcnt(0)
	s_barrier
	s_setprio 1
	s_waitcnt lgkmcnt(7)
	v_mfma_i32_16x16x64_i8 v[56:59], v[132:135], v[178:181], v[56:59]
	v_mfma_i32_16x16x64_i8 v[48:51], v[154:157], v[178:181], v[48:51]
	s_waitcnt lgkmcnt(5)
	v_mfma_i32_16x16x64_i8 v[40:43], v[132:135], v[186:189], v[40:43]
	v_mfma_i32_16x16x64_i8 v[32:35], v[154:157], v[186:189], v[32:35]
	s_waitcnt lgkmcnt(3)
	v_mfma_i32_16x16x64_i8 v[24:27], v[132:135], v[194:197], v[24:27]
	v_mfma_i32_16x16x64_i8 v[16:19], v[154:157], v[194:197], v[16:19]
	s_waitcnt lgkmcnt(1)
	v_mfma_i32_16x16x64_i8 v[8:11], v[132:135], v[202:205], v[8:11]
	v_mfma_i32_16x16x64_i8 v[0:3], v[154:157], v[202:205], v[0:3]
	v_mfma_i32_16x16x64_i8 v[56:59], v[136:139], v[182:185], v[56:59]
	v_mfma_i32_16x16x64_i8 v[48:51], v[158:161], v[182:185], v[48:51]
	v_mfma_i32_16x16x64_i8 v[40:43], v[136:139], v[190:193], v[40:43]
	v_mfma_i32_16x16x64_i8 v[32:35], v[158:161], v[190:193], v[32:35]
	v_mfma_i32_16x16x64_i8 v[24:27], v[136:139], v[198:201], v[24:27]
	v_mfma_i32_16x16x64_i8 v[16:19], v[158:161], v[198:201], v[16:19]
	s_waitcnt lgkmcnt(0)
	v_mfma_i32_16x16x64_i8 v[8:11], v[136:139], v[206:209], v[8:11]
	v_mfma_i32_16x16x64_i8 v[0:3], v[158:161], v[206:209], v[0:3]
	s_setprio 0
	s_setprio 1
	v_mfma_i32_16x16x64_i8 v[60:63], v[162:165], v[178:181], v[60:63]
	v_mfma_i32_16x16x64_i8 v[52:55], v[170:173], v[178:181], v[52:55]
	v_mfma_i32_16x16x64_i8 v[44:47], v[162:165], v[186:189], v[44:47]
	v_mfma_i32_16x16x64_i8 v[36:39], v[170:173], v[186:189], v[36:39]
	v_mfma_i32_16x16x64_i8 v[28:31], v[162:165], v[194:197], v[28:31]
	v_mfma_i32_16x16x64_i8 v[20:23], v[170:173], v[194:197], v[20:23]
	v_mfma_i32_16x16x64_i8 v[12:15], v[162:165], v[202:205], v[12:15]
	v_mfma_i32_16x16x64_i8 v[4:7], v[170:173], v[202:205], v[4:7]
	v_mfma_i32_16x16x64_i8 v[60:63], v[166:169], v[182:185], v[60:63]
	v_mfma_i32_16x16x64_i8 v[52:55], v[174:177], v[182:185], v[52:55]
	v_mfma_i32_16x16x64_i8 v[44:47], v[166:169], v[190:193], v[44:47]
	v_mfma_i32_16x16x64_i8 v[36:39], v[174:177], v[190:193], v[36:39]
	v_mfma_i32_16x16x64_i8 v[28:31], v[166:169], v[198:201], v[28:31]
	v_mfma_i32_16x16x64_i8 v[20:23], v[174:177], v[198:201], v[20:23]
	v_mfma_i32_16x16x64_i8 v[12:15], v[166:169], v[206:209], v[12:15]
	v_mfma_i32_16x16x64_i8 v[4:7], v[174:177], v[206:209], v[4:7]
	s_setprio 0
	s_add_i32 s62, s62, 2
	s_addk_i32 s60, 0x100
	s_addk_i32 s61, 0x100
	s_cmp_ge_i32 s62, s42
	s_barrier
	s_cbranch_scc0 .LBB0_1565

.LBB0_1660:
	ds_read_b128 v[136:139], v148
	ds_read_b128 v[140:143], v148 offset:1024
	ds_read_b128 v[154:157], v148 offset:2048
	ds_read_b128 v[158:161], v148 offset:3072
	ds_read_b128 v[162:165], v149
	ds_read_b128 v[166:169], v149 offset:1024
	ds_read_b128 v[170:173], v149 offset:2048
	ds_read_b128 v[174:177], v149 offset:3072
	s_add_i32 s22, s70, 0xffea8080
	s_cmp_eq_u32 s69, s76
	s_cselect_b32 s77, s26, s22
	s_cselect_b32 s23, s27, s71
	s_add_i32 s22, s77, 0x80
	s_mov_b32 m0, s56
	ds_read_b128 v[178:181], v150
	ds_read_b128 v[182:185], v150 offset:1024
	ds_read_b128 v[186:189], v150 offset:2048
	ds_read_b128 v[190:193], v150 offset:3072
	ds_read_b128 v[194:197], v150 offset:4096
	ds_read_b128 v[198:201], v150 offset:5120
	ds_read_b128 v[202:205], v150 offset:6144
	ds_read_b128 v[206:209], v150 offset:7168
	buffer_load_dwordx4 v144, s[72:75], s70 offen lds
	s_mov_b32 m0, s57
	s_nop 0
	buffer_load_dwordx4 v146, s[72:75], s70 offen lds
	s_waitcnt vmcnt(8)
	s_waitcnt lgkmcnt(0)
	s_barrier
	s_setprio 1
	s_waitcnt lgkmcnt(6)
	v_mfma_scale_f32_16x16x128_f8f6f4 v[124:127], v[136:143], v[178:185], v[124:127], v151, v151 op_sel_hi:[0,0,0]
	v_mfma_scale_f32_16x16x128_f8f6f4 v[120:123], v[154:161], v[178:185], v[120:123], v151, v151 op_sel_hi:[0,0,0]
	s_waitcnt lgkmcnt(4)
	v_mfma_scale_f32_16x16x128_f8f6f4 v[108:111], v[136:143], v[186:193], v[108:111], v151, v151 op_sel_hi:[0,0,0]
	v_mfma_scale_f32_16x16x128_f8f6f4 v[104:107], v[154:161], v[186:193], v[104:107], v151, v151 op_sel_hi:[0,0,0]
	s_waitcnt lgkmcnt(2)
	v_mfma_scale_f32_16x16x128_f8f6f4 v[128:131], v[136:143], v[194:201], v[92:95], v151, v151 op_sel_hi:[0,0,0]
	v_mfma_scale_f32_16x16x128_f8f6f4 v[210:213], v[154:161], v[194:201], v[88:91], v151, v151 op_sel_hi:[0,0,0]
	s_waitcnt lgkmcnt(0)
	v_mfma_scale_f32_16x16x128_f8f6f4 v[214:217], v[136:143], v[202:209], v[76:79], v151, v151 op_sel_hi:[0,0,0]
	v_mfma_scale_f32_16x16x128_f8f6f4 v[218:221], v[154:161], v[202:209], v[72:75], v151, v151 op_sel_hi:[0,0,0]
	s_setprio 0
	s_setprio 1
	v_mfma_scale_f32_16x16x128_f8f6f4 v[116:119], v[162:169], v[178:185], v[116:119], v151, v151 op_sel_hi:[0,0,0]
	v_mfma_scale_f32_16x16x128_f8f6f4 v[112:115], v[170:177], v[178:185], v[112:115], v151, v151 op_sel_hi:[0,0,0]
	v_mfma_scale_f32_16x16x128_f8f6f4 v[100:103], v[162:169], v[186:193], v[100:103], v151, v151 op_sel_hi:[0,0,0]
	v_mfma_scale_f32_16x16x128_f8f6f4 v[96:99], v[170:177], v[186:193], v[96:99], v151, v151 op_sel_hi:[0,0,0]
	v_mfma_scale_f32_16x16x128_f8f6f4 v[178:181], v[162:169], v[194:201], v[84:87], v151, v151 op_sel_hi:[0,0,0]
	v_mfma_scale_f32_16x16x128_f8f6f4 v[182:185], v[170:177], v[194:201], v[80:83], v151, v151 op_sel_hi:[0,0,0]
	v_mfma_scale_f32_16x16x128_f8f6f4 v[186:189], v[162:169], v[202:209], v[68:71], v151, v151 op_sel_hi:[0,0,0]
	v_mfma_scale_f32_16x16x128_f8f6f4 v[190:193], v[170:177], v[202:209], v[64:67], v151, v151 op_sel_hi:[0,0,0]
	s_setprio 0
	s_barrier
	s_mov_b32 m0, s3
	s_mov_b32 s50, s74
	s_mov_b32 s51, s75
	s_nop 1
	ds_read_b128 v[64:67], v150 offset:16384
	ds_read_b128 v[68:71], v150 offset:17408
	ds_read_b128 v[72:75], v150 offset:18432
	ds_read_b128 v[76:79], v150 offset:19456
	ds_read_b128 v[80:83], v150 offset:20480
	ds_read_b128 v[84:87], v150 offset:21504
	ds_read_b128 v[88:91], v150 offset:22528
	ds_read_b128 v[92:95], v150 offset:23552
	buffer_load_dwordx4 v145, s[48:51], s23 offen lds
	s_mov_b32 m0, s9
	s_add_i32 s78, s23, 0x158000
	buffer_load_dwordx4 v147, s[48:51], s23 offen lds
	s_mov_b32 m0, s11
	s_nop 0
	buffer_load_dwordx4 v145, s[48:51], s78 offen lds
	s_mov_b32 m0, s30
	s_nop 0
	buffer_load_dwordx4 v147, s[48:51], s78 offen lds
	s_mov_b32 m0, s2
	s_nop 0
	buffer_load_dwordx4 v144, s[72:75], s77 offen lds
	s_mov_b32 m0, s31
	s_nop 0
	buffer_load_dwordx4 v146, s[72:75], s77 offen lds
	s_waitcnt vmcnt(8)
	s_waitcnt lgkmcnt(0)
	s_barrier
	s_setprio 1
	s_waitcnt lgkmcnt(6)
	v_mfma_scale_f32_16x16x128_f8f6f4 v[60:63], v[136:143], v[64:71], v[60:63], v151, v151 op_sel_hi:[0,0,0]
	v_mfma_scale_f32_16x16x128_f8f6f4 v[56:59], v[154:161], v[64:71], v[56:59], v151, v151 op_sel_hi:[0,0,0]
	s_waitcnt lgkmcnt(4)
	v_mfma_scale_f32_16x16x128_f8f6f4 v[194:197], v[136:143], v[72:79], v[44:47], v151, v151 op_sel_hi:[0,0,0]
	v_mfma_scale_f32_16x16x128_f8f6f4 v[198:201], v[154:161], v[72:79], v[40:43], v151, v151 op_sel_hi:[0,0,0]
	s_waitcnt lgkmcnt(2)
	v_mfma_scale_f32_16x16x128_f8f6f4 v[202:205], v[136:143], v[80:87], v[28:31], v151, v151 op_sel_hi:[0,0,0]
	v_mfma_scale_f32_16x16x128_f8f6f4 v[206:209], v[154:161], v[80:87], v[24:27], v151, v151 op_sel_hi:[0,0,0]
	s_waitcnt lgkmcnt(0)
	v_mfma_scale_f32_16x16x128_f8f6f4 v[222:225], v[136:143], v[88:95], v[12:15], v151, v151 op_sel_hi:[0,0,0]
	v_mfma_scale_f32_16x16x128_f8f6f4 v[226:229], v[154:161], v[88:95], v[8:11], v151, v151 op_sel_hi:[0,0,0]
	s_setprio 0
	s_setprio 1
	v_mfma_scale_f32_16x16x128_f8f6f4 v[52:55], v[162:169], v[64:71], v[52:55], v151, v151 op_sel_hi:[0,0,0]
	v_mfma_scale_f32_16x16x128_f8f6f4 v[48:51], v[170:177], v[64:71], v[48:51], v151, v151 op_sel_hi:[0,0,0]
	v_mfma_scale_f32_16x16x128_f8f6f4 v[230:233], v[162:169], v[72:79], v[36:39], v151, v151 op_sel_hi:[0,0,0]
	v_mfma_scale_f32_16x16x128_f8f6f4 v[234:237], v[170:177], v[72:79], v[32:35], v151, v151 op_sel_hi:[0,0,0]
	v_mfma_scale_f32_16x16x128_f8f6f4 v[238:241], v[162:169], v[80:87], v[20:23], v151, v151 op_sel_hi:[0,0,0]
	v_mfma_scale_f32_16x16x128_f8f6f4 v[242:245], v[170:177], v[80:87], v[16:19], v151, v151 op_sel_hi:[0,0,0]
	v_mfma_scale_f32_16x16x128_f8f6f4 v[246:249], v[162:169], v[88:95], v[4:7], v151, v151 op_sel_hi:[0,0,0]
	v_mfma_scale_f32_16x16x128_f8f6f4 v[250:253], v[170:177], v[88:95], v[0:3], v151, v151 op_sel_hi:[0,0,0]
	s_setprio 0
	s_barrier
	s_nop 4
	ds_read_b128 v[0:3], v152
	ds_read_b128 v[4:7], v152 offset:1024
	ds_read_b128 v[16:19], v152 offset:2048
	ds_read_b128 v[20:23], v152 offset:3072
	ds_read_b128 v[136:139], v153
	ds_read_b128 v[140:143], v153 offset:1024
	ds_read_b128 v[154:157], v153 offset:2048
	ds_read_b128 v[158:161], v153 offset:3072
	s_add_i32 s77, s77, 0x158000
	s_mov_b32 m0, s36
	ds_read_b128 v[8:11], v150 offset:32768
	ds_read_b128 v[12:15], v150 offset:33792
	ds_read_b128 v[24:27], v150 offset:34816
	ds_read_b128 v[28:31], v150 offset:35840
	ds_read_b128 v[32:35], v150 offset:36864
	ds_read_b128 v[36:39], v150 offset:37888
	ds_read_b128 v[40:43], v150 offset:38912
	ds_read_b128 v[44:47], v150 offset:39936
	buffer_load_dwordx4 v144, s[72:75], s77 offen lds
	s_mov_b32 m0, s37
	s_nop 0
	buffer_load_dwordx4 v146, s[72:75], s77 offen lds
	s_waitcnt vmcnt(8)
	s_waitcnt lgkmcnt(0)
	s_barrier
	s_setprio 1
	s_waitcnt lgkmcnt(6)
	v_mfma_scale_f32_16x16x128_f8f6f4 v[124:127], v[0:7], v[8:15], v[124:127], v151, v151 op_sel_hi:[0,0,0]
	v_mfma_scale_f32_16x16x128_f8f6f4 v[120:123], v[16:23], v[8:15], v[120:123], v151, v151 op_sel_hi:[0,0,0]
	s_waitcnt lgkmcnt(4)
	v_mfma_scale_f32_16x16x128_f8f6f4 v[108:111], v[0:7], v[24:31], v[108:111], v151, v151 op_sel_hi:[0,0,0]
	v_mfma_scale_f32_16x16x128_f8f6f4 v[104:107], v[16:23], v[24:31], v[104:107], v151, v151 op_sel_hi:[0,0,0]
	s_waitcnt lgkmcnt(2)
	v_mfma_scale_f32_16x16x128_f8f6f4 v[92:95], v[0:7], v[32:39], v[128:131], v151, v151 op_sel_hi:[0,0,0]
	v_mfma_scale_f32_16x16x128_f8f6f4 v[88:91], v[16:23], v[32:39], v[210:213], v151, v151 op_sel_hi:[0,0,0]
	s_waitcnt lgkmcnt(0)
	v_mfma_scale_f32_16x16x128_f8f6f4 v[76:79], v[0:7], v[40:47], v[214:217], v151, v151 op_sel_hi:[0,0,0]
	v_mfma_scale_f32_16x16x128_f8f6f4 v[72:75], v[16:23], v[40:47], v[218:221], v151, v151 op_sel_hi:[0,0,0]
	s_setprio 0
	s_setprio 1
	v_mfma_scale_f32_16x16x128_f8f6f4 v[116:119], v[136:143], v[8:15], v[116:119], v151, v151 op_sel_hi:[0,0,0]
	v_mfma_scale_f32_16x16x128_f8f6f4 v[112:115], v[154:161], v[8:15], v[112:115], v151, v151 op_sel_hi:[0,0,0]
	v_mfma_scale_f32_16x16x128_f8f6f4 v[100:103], v[136:143], v[24:31], v[100:103], v151, v151 op_sel_hi:[0,0,0]
	v_mfma_scale_f32_16x16x128_f8f6f4 v[96:99], v[154:161], v[24:31], v[96:99], v151, v151 op_sel_hi:[0,0,0]
	v_mfma_scale_f32_16x16x128_f8f6f4 v[84:87], v[136:143], v[32:39], v[178:181], v151, v151 op_sel_hi:[0,0,0]
	v_mfma_scale_f32_16x16x128_f8f6f4 v[80:83], v[154:161], v[32:39], v[182:185], v151, v151 op_sel_hi:[0,0,0]
	v_mfma_scale_f32_16x16x128_f8f6f4 v[68:71], v[136:143], v[40:47], v[186:189], v151, v151 op_sel_hi:[0,0,0]
	v_mfma_scale_f32_16x16x128_f8f6f4 v[64:67], v[154:161], v[40:47], v[190:193], v151, v151 op_sel_hi:[0,0,0]
	s_setprio 0
	s_barrier
	s_mov_b32 m0, s40
	s_add_i32 s77, s23, 0x80
	ds_read_b128 v[32:35], v150 offset:49152
	ds_read_b128 v[36:39], v150 offset:50176
	ds_read_b128 v[162:165], v150 offset:51200
	ds_read_b128 v[166:169], v150 offset:52224
	ds_read_b128 v[170:173], v150 offset:53248
	ds_read_b128 v[174:177], v150 offset:54272
	ds_read_b128 v[178:181], v150 offset:55296
	ds_read_b128 v[182:185], v150 offset:56320
	buffer_load_dwordx4 v145, s[48:51], s77 offen lds
	s_mov_b32 m0, s41
	s_add_i32 s23, s23, 0x158080
	buffer_load_dwordx4 v147, s[48:51], s77 offen lds
	s_mov_b32 m0, s44
	s_nop 0
	buffer_load_dwordx4 v145, s[48:51], s23 offen lds
	s_mov_b32 m0, s45
	s_nop 0
	buffer_load_dwordx4 v147, s[48:51], s23 offen lds
	s_mov_b32 m0, s42
	s_nop 0
	buffer_load_dwordx4 v144, s[72:75], s22 offen lds
	s_mov_b32 m0, s43
	s_nop 0
	buffer_load_dwordx4 v146, s[72:75], s22 offen lds
	s_waitcnt vmcnt(8)
	s_waitcnt lgkmcnt(0)
	s_barrier
	s_setprio 1
	s_waitcnt lgkmcnt(6)
	v_mfma_scale_f32_16x16x128_f8f6f4 v[60:63], v[0:7], v[32:39], v[60:63], v151, v151 op_sel_hi:[0,0,0]
	v_mfma_scale_f32_16x16x128_f8f6f4 v[56:59], v[16:23], v[32:39], v[56:59], v151, v151 op_sel_hi:[0,0,0]
	s_waitcnt lgkmcnt(4)
	v_mfma_scale_f32_16x16x128_f8f6f4 v[44:47], v[0:7], v[162:169], v[194:197], v151, v151 op_sel_hi:[0,0,0]
	v_mfma_scale_f32_16x16x128_f8f6f4 v[40:43], v[16:23], v[162:169], v[198:201], v151, v151 op_sel_hi:[0,0,0]
	s_waitcnt lgkmcnt(2)
	v_mfma_scale_f32_16x16x128_f8f6f4 v[28:31], v[0:7], v[170:177], v[202:205], v151, v151 op_sel_hi:[0,0,0]
	v_mfma_scale_f32_16x16x128_f8f6f4 v[24:27], v[16:23], v[170:177], v[206:209], v151, v151 op_sel_hi:[0,0,0]
	s_waitcnt lgkmcnt(0)
	v_mfma_scale_f32_16x16x128_f8f6f4 v[12:15], v[0:7], v[178:185], v[222:225], v151, v151 op_sel_hi:[0,0,0]
	v_mfma_scale_f32_16x16x128_f8f6f4 v[8:11], v[16:23], v[178:185], v[226:229], v151, v151 op_sel_hi:[0,0,0]
	s_setprio 0
	s_setprio 1
	v_mfma_scale_f32_16x16x128_f8f6f4 v[52:55], v[136:143], v[32:39], v[52:55], v151, v151 op_sel_hi:[0,0,0]
	v_mfma_scale_f32_16x16x128_f8f6f4 v[48:51], v[154:161], v[32:39], v[48:51], v151, v151 op_sel_hi:[0,0,0]
	v_mfma_scale_f32_16x16x128_f8f6f4 v[36:39], v[136:143], v[162:169], v[230:233], v151, v151 op_sel_hi:[0,0,0]
	v_mfma_scale_f32_16x16x128_f8f6f4 v[32:35], v[154:161], v[162:169], v[234:237], v151, v151 op_sel_hi:[0,0,0]
	v_mfma_scale_f32_16x16x128_f8f6f4 v[20:23], v[136:143], v[170:177], v[238:241], v151, v151 op_sel_hi:[0,0,0]
	v_mfma_scale_f32_16x16x128_f8f6f4 v[16:19], v[154:161], v[170:177], v[242:245], v151, v151 op_sel_hi:[0,0,0]
	v_mfma_scale_f32_16x16x128_f8f6f4 v[4:7], v[136:143], v[178:185], v[246:249], v151, v151 op_sel_hi:[0,0,0]
	v_mfma_scale_f32_16x16x128_f8f6f4 v[0:3], v[154:161], v[178:185], v[250:253], v151, v151 op_sel_hi:[0,0,0]
	s_setprio 0
	s_add_i32 s76, s76, 2
	s_addk_i32 s70, 0x100
	s_addk_i32 s71, 0x100
	s_cmp_ge_i32 s76, s68
	s_barrier
	s_cbranch_scc0 .LBB0_1660
	s_branch .LBB0_1662
